# loop-edge edit: back-edge SALU block (pointer bumps, counter, exit test) hoisted above the loop-back barrier in all 16 GEMM main loops
# speedup vs baseline: 1.0016x; 1.0016x over previous
; #define PG8_STAGE(bufoff, gbase, voff) do { _Pragma("unroll") for (int _i = 0; _i < 2; ++_i) \
;         __builtin_amdgcn_global_load_lds((const unsigned*)((const char*)(gbase) + (voff)[_i]), (LAS unsigned*)(lds + (bufoff) + ldsw + _i * 8192), 16, 0, 0); } while (0)
; #define PG8_LDA(dst, b, h) do { _Pragma("unroll") for (int m = 0; m < 4; ++m) _Pragma("unroll") for (int k = 0; k < 2; ++k) dst[m][k] = *(const LAS bf16x8*)(lds + PG8_SA(b, h) + aoff + m * 2048 + k * 1024); } while (0)
; #define PG8_LDB(dst, b, h) do { _Pragma("unroll") for (int n = 0; n < 2; ++n) _Pragma("unroll") for (int k = 0; k < 2; ++k) dst[n][k] = *(const LAS bf16x8*)(lds + PG8_SB(b, h) + boff + n * 2048 + k * 1024); } while (0)
; #define PG8_WAIT_V(n) asm volatile("s_waitcnt vmcnt(" #n ")" ::: "memory")
; #define PG8_WAIT_L(n) asm volatile("s_waitcnt lgkmcnt(" #n ")" ::: "memory")
; #define PG8_BAR __builtin_amdgcn_s_barrier()
; #define PG8_SCHED __builtin_amdgcn_sched_barrier(0)
; template <class Epi, class Sched, bool SWAPD = false>
; __device__ __forceinline__ void gemm_phase(LAS unsigned char* lds, const Gemm g, const Sched& S, const Epi& E) {
;     ...
;         for (int t = 0; t < nt; t += 2) {
;             const bool last = (t == nt - 2);
;             const char* a1 = cA + (size_t)(t + 1) * kstepA;
;             const char* a2 = last ? nA : cA + (size_t)(t + 2) * kstepA; const char* b2 = last ? nB : cB + (size_t)(t + 2) * kstep;
;             const char* a3 = a2 + kstepA; const char* b3 = b2 + kstep;
;             PG8_LDB(B0, 0, 0); PG8_LDB(B1, 0, 1); PG8_SCHED; PG8_LDA(At, 0, 0); PG8_STAGE(PG8_SA(1, 1), a1 + hstepA, voffA);
;             PG8_WAIT_V(8); PG8_WAIT_L(0); PG8_BAR; PG8_MMA(0, 0, At, B0); PG8_MMA(0, 1, At, B1); PG8_BAR; PG8_SCHED;
;             PG8_LDA(At, 0, 1); PG8_STAGE(PG8_SB(0, 0), b2, voffB); PG8_STAGE(PG8_SB(0, 1), b2 + hstepB, voffB); PG8_STAGE(PG8_SA(0, 0), a2, voffA);
;             PG8_WAIT_V(8); PG8_WAIT_L(0); PG8_BAR; PG8_MMA(1, 0, At, B0); PG8_MMA(1, 1, At, B1); PG8_BAR; PG8_SCHED;
.LBB0_256:
	ds_read_b128 v[148:151], v145
	ds_read_b128 v[152:155], v145 offset:1024
	ds_read_b128 v[156:159], v145 offset:2048
	ds_read_b128 v[160:163], v145 offset:3072
	ds_read_b128 v[164:167], v146
	ds_read_b128 v[168:171], v146 offset:1024
	ds_read_b128 v[172:175], v146 offset:2048
	ds_read_b128 v[176:179], v146 offset:3072
	s_add_u32 s46, s44, 0xfffc0080
	s_addc_u32 s47, s45, -1
	s_cmp_eq_u32 s68, 12
	s_cselect_b32 s51, s13, s47
	s_cselect_b32 s50, s23, s46
	s_cselect_b32 s47, s64, s67
	s_cselect_b32 s46, s65, s66
	v_lshl_add_u64 v[140:141], s[44:45], 0, v[132:133]
	s_add_i32 m0, s31, 0xc000
	ds_read_b128 v[180:183], v147
	ds_read_b128 v[184:187], v147 offset:1024
	ds_read_b128 v[188:191], v147 offset:2048
	ds_read_b128 v[192:195], v147 offset:3072
	ds_read_b128 v[196:199], v147 offset:4096
	ds_read_b128 v[200:203], v147 offset:5120
	ds_read_b128 v[208:211], v147 offset:6144
	ds_read_b128 v[212:215], v147 offset:7168
	global_load_lds_dwordx4 v[140:141], off
	v_lshl_add_u64 v[140:141], s[44:45], 0, v[134:135]
	s_add_i32 m0, s31, 0xe000
	s_nop 0
	global_load_lds_dwordx4 v[140:141], off
	s_waitcnt vmcnt(8)
	s_waitcnt lgkmcnt(0)
	s_barrier
	s_setprio 1
	v_mfma_f32_16x16x32_bf16 v[124:127], v[148:151], v[180:183], v[124:127]
	v_mfma_f32_16x16x32_bf16 v[116:119], v[156:159], v[180:183], v[116:119]
	v_mfma_f32_16x16x32_bf16 v[108:111], v[148:151], v[188:191], v[108:111]
	v_mfma_f32_16x16x32_bf16 v[100:103], v[156:159], v[188:191], v[100:103]
	v_mfma_f32_16x16x32_bf16 v[92:95], v[148:151], v[196:199], v[92:95]
	v_mfma_f32_16x16x32_bf16 v[84:87], v[156:159], v[196:199], v[84:87]
	v_mfma_f32_16x16x32_bf16 v[76:79], v[148:151], v[208:211], v[76:79]
	v_mfma_f32_16x16x32_bf16 v[68:71], v[156:159], v[208:211], v[68:71]
	v_mfma_f32_16x16x32_bf16 v[124:127], v[152:155], v[184:187], v[124:127]
	v_mfma_f32_16x16x32_bf16 v[116:119], v[160:163], v[184:187], v[116:119]
	v_mfma_f32_16x16x32_bf16 v[108:111], v[152:155], v[192:195], v[108:111]
	v_mfma_f32_16x16x32_bf16 v[100:103], v[160:163], v[192:195], v[100:103]
	v_mfma_f32_16x16x32_bf16 v[92:95], v[152:155], v[200:203], v[92:95]
	v_mfma_f32_16x16x32_bf16 v[84:87], v[160:163], v[200:203], v[84:87]
	v_mfma_f32_16x16x32_bf16 v[76:79], v[152:155], v[212:215], v[76:79]
	v_mfma_f32_16x16x32_bf16 v[68:71], v[160:163], v[212:215], v[68:71]
	s_setprio 0
	s_setprio 1
	v_mfma_f32_16x16x32_bf16 v[120:123], v[164:167], v[180:183], v[120:123]
	v_mfma_f32_16x16x32_bf16 v[112:115], v[172:175], v[180:183], v[112:115]
	v_mfma_f32_16x16x32_bf16 v[104:107], v[164:167], v[188:191], v[104:107]
	v_mfma_f32_16x16x32_bf16 v[96:99], v[172:175], v[188:191], v[96:99]
	v_mfma_f32_16x16x32_bf16 v[88:91], v[164:167], v[196:199], v[88:91]
	v_mfma_f32_16x16x32_bf16 v[80:83], v[172:175], v[196:199], v[80:83]
	v_mfma_f32_16x16x32_bf16 v[72:75], v[164:167], v[208:211], v[72:75]
	v_mfma_f32_16x16x32_bf16 v[64:67], v[172:175], v[208:211], v[64:67]
	v_mfma_f32_16x16x32_bf16 v[120:123], v[168:171], v[184:187], v[120:123]
	v_mfma_f32_16x16x32_bf16 v[112:115], v[176:179], v[184:187], v[112:115]
	v_mfma_f32_16x16x32_bf16 v[104:107], v[168:171], v[192:195], v[104:107]
	v_mfma_f32_16x16x32_bf16 v[96:99], v[176:179], v[192:195], v[96:99]
	v_mfma_f32_16x16x32_bf16 v[88:91], v[168:171], v[200:203], v[88:91]
	v_mfma_f32_16x16x32_bf16 v[80:83], v[176:179], v[200:203], v[80:83]
	v_mfma_f32_16x16x32_bf16 v[72:75], v[168:171], v[212:215], v[72:75]
	v_mfma_f32_16x16x32_bf16 v[64:67], v[176:179], v[212:215], v[64:67]
	s_setprio 0
	s_barrier
	s_add_i32 s69, s54, s11
	v_lshl_add_u64 v[140:141], s[46:47], 0, v[130:131]
	s_mov_b32 m0, s69
	ds_read_b128 v[180:183], v147 offset:16384
	ds_read_b128 v[184:187], v147 offset:17408
	ds_read_b128 v[188:191], v147 offset:18432
	ds_read_b128 v[192:195], v147 offset:19456
	ds_read_b128 v[196:199], v147 offset:20480
	ds_read_b128 v[200:203], v147 offset:21504
	ds_read_b128 v[208:211], v147 offset:22528
	ds_read_b128 v[212:215], v147 offset:23552
	global_load_lds_dwordx4 v[140:141], off
	s_add_i32 m0, s69, 0x2000
	s_add_u32 s72, s46, 0x40000
	v_lshl_add_u64 v[204:205], s[46:47], 0, v[128:129]
	s_addc_u32 s73, s47, 0
	s_add_i32 s69, s55, s11
	global_load_lds_dwordx4 v[204:205], off
	v_lshl_add_u64 v[216:217], s[72:73], 0, v[130:131]
	s_mov_b32 m0, s69
	v_lshl_add_u64 v[218:219], s[50:51], 0, v[128:129]
	global_load_lds_dwordx4 v[216:217], off
	v_lshl_add_u64 v[216:217], s[72:73], 0, v[128:129]
	s_add_i32 m0, s69, 0x2000
	s_nop 0
	global_load_lds_dwordx4 v[216:217], off
	v_lshl_add_u64 v[216:217], s[50:51], 0, v[130:131]
	s_mov_b32 m0, s31
	s_nop 0
	global_load_lds_dwordx4 v[216:217], off
	s_mov_b32 m0, s33
	s_nop 0
	global_load_lds_dwordx4 v[218:219], off
	s_waitcnt vmcnt(8)
	s_waitcnt lgkmcnt(0)
	s_barrier
; #define PG8_STAGE(bufoff, gbase, voff) do { _Pragma("unroll") for (int _i = 0; _i < 2; ++_i) \
;         __builtin_amdgcn_global_load_lds((const unsigned*)((const char*)(gbase) + (voff)[_i]), (LAS unsigned*)(lds + (bufoff) + ldsw + _i * 8192), 16, 0, 0); } while (0)
; #define PG8_LDA(dst, b, h) do { _Pragma("unroll") for (int m = 0; m < 4; ++m) _Pragma("unroll") for (int k = 0; k < 2; ++k) dst[m][k] = *(const LAS bf16x8*)(lds + PG8_SA(b, h) + aoff + m * 2048 + k * 1024); } while (0)
; #define PG8_LDB(dst, b, h) do { _Pragma("unroll") for (int n = 0; n < 2; ++n) _Pragma("unroll") for (int k = 0; k < 2; ++k) dst[n][k] = *(const LAS bf16x8*)(lds + PG8_SB(b, h) + boff + n * 2048 + k * 1024); } while (0)
; #define PG8_WAIT_V(n) asm volatile("s_waitcnt vmcnt(" #n ")" ::: "memory")
; #define PG8_WAIT_L(n) asm volatile("s_waitcnt lgkmcnt(" #n ")" ::: "memory")
; #define PG8_BAR __builtin_amdgcn_s_barrier()
; #define PG8_SCHED __builtin_amdgcn_sched_barrier(0)
; template <class Epi, class Sched, bool SWAPD = false>
; __device__ __forceinline__ void gemm_phase(LAS unsigned char* lds, const Gemm g, const Sched& S, const Epi& E) {
;     ...
;             PG8_WAIT_V(8); PG8_WAIT_L(0); PG8_BAR; PG8_MMA(1, 0, At, B0); PG8_MMA(1, 1, At, B1); PG8_BAR; PG8_SCHED;
;             PG8_LDB(B0, 1, 0); PG8_LDB(B1, 1, 1); PG8_SCHED; PG8_LDA(At, 1, 0); PG8_STAGE(PG8_SA(0, 1), a2 + hstepA, voffA);
;             PG8_WAIT_V(8); PG8_WAIT_L(0); PG8_BAR; PG8_MMA(0, 0, At, B0); PG8_MMA(0, 1, At, B1); PG8_BAR; PG8_SCHED;
;             PG8_LDA(At, 1, 1); PG8_STAGE(PG8_SB(1, 0), b3, voffB); PG8_STAGE(PG8_SB(1, 1), b3 + hstepB, voffB); PG8_STAGE(PG8_SA(1, 0), a3, voffA);
	s_setprio 1
	v_mfma_f32_16x16x32_bf16 v[60:63], v[148:151], v[180:183], v[60:63]
	v_mfma_f32_16x16x32_bf16 v[52:55], v[156:159], v[180:183], v[52:55]
	v_mfma_f32_16x16x32_bf16 v[44:47], v[148:151], v[188:191], v[44:47]
	v_mfma_f32_16x16x32_bf16 v[36:39], v[156:159], v[188:191], v[36:39]
	v_mfma_f32_16x16x32_bf16 v[28:31], v[148:151], v[196:199], v[28:31]
	v_mfma_f32_16x16x32_bf16 v[20:23], v[156:159], v[196:199], v[20:23]
	v_mfma_f32_16x16x32_bf16 v[12:15], v[148:151], v[208:211], v[12:15]
	v_mfma_f32_16x16x32_bf16 v[4:7], v[156:159], v[208:211], v[4:7]
	v_mfma_f32_16x16x32_bf16 v[60:63], v[152:155], v[184:187], v[60:63]
	v_mfma_f32_16x16x32_bf16 v[52:55], v[160:163], v[184:187], v[52:55]
	v_mfma_f32_16x16x32_bf16 v[44:47], v[152:155], v[192:195], v[44:47]
	v_mfma_f32_16x16x32_bf16 v[36:39], v[160:163], v[192:195], v[36:39]
	v_mfma_f32_16x16x32_bf16 v[28:31], v[152:155], v[200:203], v[28:31]
	v_mfma_f32_16x16x32_bf16 v[20:23], v[160:163], v[200:203], v[20:23]
	v_mfma_f32_16x16x32_bf16 v[12:15], v[152:155], v[212:215], v[12:15]
	v_mfma_f32_16x16x32_bf16 v[4:7], v[160:163], v[212:215], v[4:7]
	s_setprio 0
	s_setprio 1
	v_mfma_f32_16x16x32_bf16 v[56:59], v[164:167], v[180:183], v[56:59]
	v_mfma_f32_16x16x32_bf16 v[48:51], v[172:175], v[180:183], v[48:51]
	v_mfma_f32_16x16x32_bf16 v[40:43], v[164:167], v[188:191], v[40:43]
	v_mfma_f32_16x16x32_bf16 v[32:35], v[172:175], v[188:191], v[32:35]
	v_mfma_f32_16x16x32_bf16 v[24:27], v[164:167], v[196:199], v[24:27]
	v_mfma_f32_16x16x32_bf16 v[16:19], v[172:175], v[196:199], v[16:19]
	v_mfma_f32_16x16x32_bf16 v[8:11], v[164:167], v[208:211], v[8:11]
	v_mfma_f32_16x16x32_bf16 v[0:3], v[172:175], v[208:211], v[0:3]
	v_mfma_f32_16x16x32_bf16 v[56:59], v[168:171], v[184:187], v[56:59]
	v_mfma_f32_16x16x32_bf16 v[48:51], v[176:179], v[184:187], v[48:51]
	v_mfma_f32_16x16x32_bf16 v[40:43], v[168:171], v[192:195], v[40:43]
	v_mfma_f32_16x16x32_bf16 v[32:35], v[176:179], v[192:195], v[32:35]
	v_mfma_f32_16x16x32_bf16 v[24:27], v[168:171], v[200:203], v[24:27]
	v_mfma_f32_16x16x32_bf16 v[16:19], v[176:179], v[200:203], v[16:19]
	v_mfma_f32_16x16x32_bf16 v[8:11], v[168:171], v[212:215], v[8:11]
	v_mfma_f32_16x16x32_bf16 v[0:3], v[176:179], v[212:215], v[0:3]
	s_setprio 0
	s_barrier
	s_add_i32 s69, 0, 0x18000
	s_add_i32 s72, 0, 0x1c000
	v_add_u32_e32 v160, s69, v143
	v_add_u32_e32 v176, s72, v143
	ds_read_b128 v[148:151], v160
	ds_read_b128 v[152:155], v160 offset:1024
	ds_read_b128 v[156:159], v160 offset:2048
	ds_read_b128 v[160:163], v160 offset:3072
	ds_read_b128 v[164:167], v176
	ds_read_b128 v[168:171], v176 offset:1024
	ds_read_b128 v[172:175], v176 offset:2048
	ds_read_b128 v[176:179], v176 offset:3072
	s_add_u32 s50, s50, 0x40000
	s_addc_u32 s51, s51, 0
	s_mov_b32 m0, s34
	v_lshl_add_u64 v[220:221], s[50:51], 0, v[130:131]
	ds_read_b128 v[180:183], v147 offset:32768
	ds_read_b128 v[184:187], v147 offset:33792
	ds_read_b128 v[188:191], v147 offset:34816
	ds_read_b128 v[192:195], v147 offset:35840
	ds_read_b128 v[196:199], v147 offset:36864
	ds_read_b128 v[200:203], v147 offset:37888
	ds_read_b128 v[208:211], v147 offset:38912
	ds_read_b128 v[212:215], v147 offset:39936
	global_load_lds_dwordx4 v[220:221], off
	v_lshl_add_u64 v[220:221], s[50:51], 0, v[128:129]
	s_mov_b32 m0, s35
	s_nop 0
	global_load_lds_dwordx4 v[220:221], off
	s_waitcnt vmcnt(8)
	s_waitcnt lgkmcnt(0)
	s_barrier
	s_setprio 1
	v_mfma_f32_16x16x32_bf16 v[124:127], v[148:151], v[180:183], v[124:127]
	v_mfma_f32_16x16x32_bf16 v[116:119], v[156:159], v[180:183], v[116:119]
	v_mfma_f32_16x16x32_bf16 v[108:111], v[148:151], v[188:191], v[108:111]
	v_mfma_f32_16x16x32_bf16 v[100:103], v[156:159], v[188:191], v[100:103]
	v_mfma_f32_16x16x32_bf16 v[92:95], v[148:151], v[196:199], v[92:95]
	v_mfma_f32_16x16x32_bf16 v[84:87], v[156:159], v[196:199], v[84:87]
	v_mfma_f32_16x16x32_bf16 v[76:79], v[148:151], v[208:211], v[76:79]
	v_mfma_f32_16x16x32_bf16 v[68:71], v[156:159], v[208:211], v[68:71]
	v_mfma_f32_16x16x32_bf16 v[124:127], v[152:155], v[184:187], v[124:127]
	v_mfma_f32_16x16x32_bf16 v[116:119], v[160:163], v[184:187], v[116:119]
	v_mfma_f32_16x16x32_bf16 v[108:111], v[152:155], v[192:195], v[108:111]
	v_mfma_f32_16x16x32_bf16 v[100:103], v[160:163], v[192:195], v[100:103]
	v_mfma_f32_16x16x32_bf16 v[92:95], v[152:155], v[200:203], v[92:95]
	v_mfma_f32_16x16x32_bf16 v[84:87], v[160:163], v[200:203], v[84:87]
	v_mfma_f32_16x16x32_bf16 v[76:79], v[152:155], v[212:215], v[76:79]
	v_mfma_f32_16x16x32_bf16 v[68:71], v[160:163], v[212:215], v[68:71]
	s_setprio 0
	s_setprio 1
	v_mfma_f32_16x16x32_bf16 v[120:123], v[164:167], v[180:183], v[120:123]
	v_mfma_f32_16x16x32_bf16 v[112:115], v[172:175], v[180:183], v[112:115]
	v_mfma_f32_16x16x32_bf16 v[104:107], v[164:167], v[188:191], v[104:107]
	v_mfma_f32_16x16x32_bf16 v[96:99], v[172:175], v[188:191], v[96:99]
	v_mfma_f32_16x16x32_bf16 v[88:91], v[164:167], v[196:199], v[88:91]
	v_mfma_f32_16x16x32_bf16 v[80:83], v[172:175], v[196:199], v[80:83]
	v_mfma_f32_16x16x32_bf16 v[72:75], v[164:167], v[208:211], v[72:75]
	v_mfma_f32_16x16x32_bf16 v[64:67], v[172:175], v[208:211], v[64:67]
	v_mfma_f32_16x16x32_bf16 v[120:123], v[168:171], v[184:187], v[120:123]
	v_mfma_f32_16x16x32_bf16 v[112:115], v[176:179], v[184:187], v[112:115]
	v_mfma_f32_16x16x32_bf16 v[104:107], v[168:171], v[192:195], v[104:107]
	v_mfma_f32_16x16x32_bf16 v[96:99], v[176:179], v[192:195], v[96:99]
	v_mfma_f32_16x16x32_bf16 v[88:91], v[168:171], v[200:203], v[88:91]
	v_mfma_f32_16x16x32_bf16 v[80:83], v[176:179], v[200:203], v[80:83]
	v_mfma_f32_16x16x32_bf16 v[72:75], v[168:171], v[212:215], v[72:75]
	v_mfma_f32_16x16x32_bf16 v[64:67], v[176:179], v[212:215], v[64:67]
	s_setprio 0
	s_barrier
; #define PG8_STAGE(bufoff, gbase, voff) do { _Pragma("unroll") for (int _i = 0; _i < 2; ++_i) \
;         __builtin_amdgcn_global_load_lds((const unsigned*)((const char*)(gbase) + (voff)[_i]), (LAS unsigned*)(lds + (bufoff) + ldsw + _i * 8192), 16, 0, 0); } while (0)
; #define PG8_LDA(dst, b, h) do { _Pragma("unroll") for (int m = 0; m < 4; ++m) _Pragma("unroll") for (int k = 0; k < 2; ++k) dst[m][k] = *(const LAS bf16x8*)(lds + PG8_SA(b, h) + aoff + m * 2048 + k * 1024); } while (0)
; #define PG8_WAIT_V(n) asm volatile("s_waitcnt vmcnt(" #n ")" ::: "memory")
; #define PG8_WAIT_L(n) asm volatile("s_waitcnt lgkmcnt(" #n ")" ::: "memory")
; #define PG8_BAR __builtin_amdgcn_s_barrier()
; #define PG8_SCHED __builtin_amdgcn_sched_barrier(0)
; template <class Epi, class Sched, bool SWAPD = false>
; __device__ __forceinline__ void gemm_phase(LAS unsigned char* lds, const Gemm g, const Sched& S, const Epi& E) {
;     ...
;             PG8_WAIT_V(8); PG8_WAIT_L(0); PG8_BAR; PG8_MMA(0, 0, At, B0); PG8_MMA(0, 1, At, B1); PG8_BAR; PG8_SCHED;
;             PG8_LDA(At, 1, 1); PG8_STAGE(PG8_SB(1, 0), b3, voffB); PG8_STAGE(PG8_SB(1, 1), b3 + hstepB, voffB); PG8_STAGE(PG8_SA(1, 0), a3, voffA);
;             PG8_WAIT_V(8); PG8_WAIT_L(0); PG8_BAR; PG8_MMA(1, 0, At, B0); PG8_MMA(1, 1, At, B1); PG8_BAR; PG8_SCHED;
;         }
	s_add_i32 s50, s69, s11
	v_lshl_add_u64 v[140:141], v[140:141], 0, s[6:7]
	s_mov_b32 m0, s50
	ds_read_b128 v[180:183], v147 offset:49152
	ds_read_b128 v[184:187], v147 offset:50176
	ds_read_b128 v[188:191], v147 offset:51200
	ds_read_b128 v[192:195], v147 offset:52224
	ds_read_b128 v[196:199], v147 offset:53248
	ds_read_b128 v[200:203], v147 offset:54272
	ds_read_b128 v[208:211], v147 offset:55296
	ds_read_b128 v[212:215], v147 offset:56320
	global_load_lds_dwordx4 v[140:141], off
	s_add_i32 m0, s50, 0x2000
	s_add_u32 s46, s46, 0x40080
	v_lshl_add_u64 v[140:141], v[204:205], 0, s[6:7]
	s_addc_u32 s47, s47, 0
	s_add_i32 s50, s72, s11
	global_load_lds_dwordx4 v[140:141], off
	v_lshl_add_u64 v[140:141], s[46:47], 0, v[130:131]
	s_mov_b32 m0, s50
	s_nop 0
	global_load_lds_dwordx4 v[140:141], off
	v_lshl_add_u64 v[140:141], s[46:47], 0, v[128:129]
	s_add_i32 m0, s50, 0x2000
	s_nop 0
	global_load_lds_dwordx4 v[140:141], off
	v_lshl_add_u64 v[140:141], v[216:217], 0, s[6:7]
	s_mov_b32 m0, s52
	s_nop 0
	global_load_lds_dwordx4 v[140:141], off
	v_lshl_add_u64 v[140:141], v[218:219], 0, s[6:7]
	s_mov_b32 m0, s53
	s_nop 0
	global_load_lds_dwordx4 v[140:141], off
	s_waitcnt vmcnt(8)
	s_waitcnt lgkmcnt(0)
	s_barrier
	s_setprio 1
	v_mfma_f32_16x16x32_bf16 v[60:63], v[148:151], v[180:183], v[60:63]
	v_mfma_f32_16x16x32_bf16 v[52:55], v[156:159], v[180:183], v[52:55]
	v_mfma_f32_16x16x32_bf16 v[44:47], v[148:151], v[188:191], v[44:47]
	v_mfma_f32_16x16x32_bf16 v[36:39], v[156:159], v[188:191], v[36:39]
	v_mfma_f32_16x16x32_bf16 v[28:31], v[148:151], v[196:199], v[28:31]
	v_mfma_f32_16x16x32_bf16 v[20:23], v[156:159], v[196:199], v[20:23]
	v_mfma_f32_16x16x32_bf16 v[12:15], v[148:151], v[208:211], v[12:15]
	v_mfma_f32_16x16x32_bf16 v[4:7], v[156:159], v[208:211], v[4:7]
	v_mfma_f32_16x16x32_bf16 v[60:63], v[152:155], v[184:187], v[60:63]
	v_mfma_f32_16x16x32_bf16 v[52:55], v[160:163], v[184:187], v[52:55]
	v_mfma_f32_16x16x32_bf16 v[44:47], v[152:155], v[192:195], v[44:47]
	v_mfma_f32_16x16x32_bf16 v[36:39], v[160:163], v[192:195], v[36:39]
	v_mfma_f32_16x16x32_bf16 v[28:31], v[152:155], v[200:203], v[28:31]
	v_mfma_f32_16x16x32_bf16 v[20:23], v[160:163], v[200:203], v[20:23]
	v_mfma_f32_16x16x32_bf16 v[12:15], v[152:155], v[212:215], v[12:15]
	v_mfma_f32_16x16x32_bf16 v[4:7], v[160:163], v[212:215], v[4:7]
	s_setprio 0
	s_setprio 1
	v_mfma_f32_16x16x32_bf16 v[56:59], v[164:167], v[180:183], v[56:59]
	v_mfma_f32_16x16x32_bf16 v[48:51], v[172:175], v[180:183], v[48:51]
	v_mfma_f32_16x16x32_bf16 v[40:43], v[164:167], v[188:191], v[40:43]
	v_mfma_f32_16x16x32_bf16 v[32:35], v[172:175], v[188:191], v[32:35]
	v_mfma_f32_16x16x32_bf16 v[24:27], v[164:167], v[196:199], v[24:27]
	v_mfma_f32_16x16x32_bf16 v[16:19], v[172:175], v[196:199], v[16:19]
	v_mfma_f32_16x16x32_bf16 v[8:11], v[164:167], v[208:211], v[8:11]
	v_mfma_f32_16x16x32_bf16 v[0:3], v[172:175], v[208:211], v[0:3]
	v_mfma_f32_16x16x32_bf16 v[56:59], v[168:171], v[184:187], v[56:59]
	v_mfma_f32_16x16x32_bf16 v[48:51], v[176:179], v[184:187], v[48:51]
	v_mfma_f32_16x16x32_bf16 v[40:43], v[168:171], v[192:195], v[40:43]
	v_mfma_f32_16x16x32_bf16 v[32:35], v[176:179], v[192:195], v[32:35]
	v_mfma_f32_16x16x32_bf16 v[24:27], v[168:171], v[200:203], v[24:27]
	v_mfma_f32_16x16x32_bf16 v[16:19], v[176:179], v[200:203], v[16:19]
	v_mfma_f32_16x16x32_bf16 v[8:11], v[168:171], v[212:215], v[8:11]
	v_mfma_f32_16x16x32_bf16 v[0:3], v[176:179], v[212:215], v[0:3]
	s_setprio 0
	s_add_i32 s68, s68, 2
	s_add_u32 s44, s44, 0x100
	s_addc_u32 s45, s45, 0
	s_add_u32 s66, s66, 0x100
	s_addc_u32 s67, s67, 0
	s_cmp_gt_u32 s68, 13
	s_barrier
	s_cbranch_scc0 .LBB0_256
	s_and_b64 vcc, exec, s[8:9]
	s_cbranch_vccz .LBB0_259
	s_barrier

; #define PG8_STAGE(bufoff, gbase, voff) do { _Pragma("unroll") for (int _i = 0; _i < 2; ++_i) \
;         __builtin_amdgcn_global_load_lds((const unsigned*)((const char*)(gbase) + (voff)[_i]), (LAS unsigned*)(lds + (bufoff) + ldsw + _i * 8192), 16, 0, 0); } while (0)
; #define PG8_LDA(dst, b, h) do { _Pragma("unroll") for (int m = 0; m < 4; ++m) _Pragma("unroll") for (int k = 0; k < 2; ++k) dst[m][k] = *(const LAS bf16x8*)(lds + PG8_SA(b, h) + aoff + m * 2048 + k * 1024); } while (0)
; #define PG8_LDB(dst, b, h) do { _Pragma("unroll") for (int n = 0; n < 2; ++n) _Pragma("unroll") for (int k = 0; k < 2; ++k) dst[n][k] = *(const LAS bf16x8*)(lds + PG8_SB(b, h) + boff + n * 2048 + k * 1024); } while (0)
; #define PG8_WAIT_V(n) asm volatile("s_waitcnt vmcnt(" #n ")" ::: "memory")
; #define PG8_WAIT_L(n) asm volatile("s_waitcnt lgkmcnt(" #n ")" ::: "memory")
; #define PG8_BAR __builtin_amdgcn_s_barrier()
; #define PG8_SCHED __builtin_amdgcn_sched_barrier(0)
; template <class Epi, class Sched, bool SWAPD = false>
; __device__ __forceinline__ void gemm_phase(LAS unsigned char* lds, const Gemm g, const Sched& S, const Epi& E) {
;     ...
;         for (int t = 0; t < nt; t += 2) {
;             const bool last = (t == nt - 2);
;             const char* a1 = cA + (size_t)(t + 1) * kstepA;
;             const char* a2 = last ? nA : cA + (size_t)(t + 2) * kstepA; const char* b2 = last ? nB : cB + (size_t)(t + 2) * kstep;
;             const char* a3 = a2 + kstepA; const char* b3 = b2 + kstep;
;             PG8_LDB(B0, 0, 0); PG8_LDB(B1, 0, 1); PG8_SCHED; PG8_LDA(At, 0, 0); PG8_STAGE(PG8_SA(1, 1), a1 + hstepA, voffA);
;             PG8_WAIT_V(8); PG8_WAIT_L(0); PG8_BAR; PG8_MMA(0, 0, At, B0); PG8_MMA(0, 1, At, B1); PG8_BAR; PG8_SCHED;
;             PG8_LDA(At, 0, 1); PG8_STAGE(PG8_SB(0, 0), b2, voffB); PG8_STAGE(PG8_SB(0, 1), b2 + hstepB, voffB); PG8_STAGE(PG8_SA(0, 0), a2, voffA);
;             PG8_WAIT_V(8); PG8_WAIT_L(0); PG8_BAR; PG8_MMA(1, 0, At, B0); PG8_MMA(1, 1, At, B1); PG8_BAR; PG8_SCHED;
.LBB0_353:
	v_add_u32_e32 v132, s57, v184
	ds_read_b128 v[174:177], v132
	ds_read_b128 v[178:181], v132 offset:1024
	ds_read_b128 v[188:191], v132 offset:2048
	ds_read_b128 v[192:195], v132 offset:3072
	v_add_u32_e32 v132, s64, v184
	ds_read_b128 v[196:199], v132
	ds_read_b128 v[200:203], v132 offset:1024
	ds_read_b128 v[208:211], v132 offset:2048
	ds_read_b128 v[212:215], v132 offset:3072
	s_add_i32 s77, s44, 2
	s_add_u32 s42, s38, 0x100
	s_addc_u32 s43, s39, 0
	s_cmp_eq_u32 s74, s44
	s_cselect_b32 s44, s35, s75
	s_cselect_b32 s47, s29, s43
	s_cselect_b32 s46, s33, s42
	s_cselect_b32 s45, s34, s76
	v_lshl_add_u64 v[182:183], s[38:39], 0, v[166:167]
	s_add_i32 m0, s30, 0xc000
	ds_read_b128 v[216:219], v186
	ds_read_b128 v[220:223], v186 offset:1024
	ds_read_b128 v[224:227], v186 offset:2048
	ds_read_b128 v[228:231], v186 offset:3072
	ds_read_b128 v[232:235], v186 offset:4096
	ds_read_b128 v[236:239], v186 offset:5120
	ds_read_b128 v[240:243], v186 offset:6144
	ds_read_b128 v[244:247], v186 offset:7168
	global_load_lds_dwordx4 v[182:183], off
	v_lshl_add_u64 v[182:183], s[38:39], 0, v[168:169]
	s_add_i32 m0, s30, 0xe000
	s_nop 0
	global_load_lds_dwordx4 v[182:183], off
	s_waitcnt vmcnt(8)
	s_waitcnt lgkmcnt(0)
	s_barrier
	s_setprio 1
	v_mfma_f32_16x16x32_bf16 v[124:127], v[174:177], v[216:219], v[124:127]
	v_mfma_f32_16x16x32_bf16 v[120:123], v[188:191], v[216:219], v[120:123]
	v_mfma_f32_16x16x32_bf16 v[108:111], v[174:177], v[224:227], v[108:111]
	v_mfma_f32_16x16x32_bf16 v[104:107], v[188:191], v[224:227], v[104:107]
	v_mfma_f32_16x16x32_bf16 v[92:95], v[174:177], v[232:235], v[92:95]
	v_mfma_f32_16x16x32_bf16 v[88:91], v[188:191], v[232:235], v[88:91]
	v_mfma_f32_16x16x32_bf16 v[76:79], v[174:177], v[240:243], v[76:79]
	v_mfma_f32_16x16x32_bf16 v[72:75], v[188:191], v[240:243], v[72:75]
	v_mfma_f32_16x16x32_bf16 v[124:127], v[178:181], v[220:223], v[124:127]
	v_mfma_f32_16x16x32_bf16 v[120:123], v[192:195], v[220:223], v[120:123]
	v_mfma_f32_16x16x32_bf16 v[108:111], v[178:181], v[228:231], v[108:111]
	v_mfma_f32_16x16x32_bf16 v[104:107], v[192:195], v[228:231], v[104:107]
	v_mfma_f32_16x16x32_bf16 v[92:95], v[178:181], v[236:239], v[92:95]
	v_mfma_f32_16x16x32_bf16 v[88:91], v[192:195], v[236:239], v[88:91]
	v_mfma_f32_16x16x32_bf16 v[76:79], v[178:181], v[244:247], v[76:79]
	v_mfma_f32_16x16x32_bf16 v[72:75], v[192:195], v[244:247], v[72:75]
	s_setprio 0
	s_setprio 1
	v_mfma_f32_16x16x32_bf16 v[116:119], v[196:199], v[216:219], v[116:119]
	v_mfma_f32_16x16x32_bf16 v[112:115], v[208:211], v[216:219], v[112:115]
	v_mfma_f32_16x16x32_bf16 v[100:103], v[196:199], v[224:227], v[100:103]
	v_mfma_f32_16x16x32_bf16 v[96:99], v[208:211], v[224:227], v[96:99]
	v_mfma_f32_16x16x32_bf16 v[84:87], v[196:199], v[232:235], v[84:87]
	v_mfma_f32_16x16x32_bf16 v[80:83], v[208:211], v[232:235], v[80:83]
	v_mfma_f32_16x16x32_bf16 v[68:71], v[196:199], v[240:243], v[68:71]
	v_mfma_f32_16x16x32_bf16 v[64:67], v[208:211], v[240:243], v[64:67]
	v_mfma_f32_16x16x32_bf16 v[116:119], v[200:203], v[220:223], v[116:119]
	v_mfma_f32_16x16x32_bf16 v[112:115], v[212:215], v[220:223], v[112:115]
	v_mfma_f32_16x16x32_bf16 v[100:103], v[200:203], v[228:231], v[100:103]
	v_mfma_f32_16x16x32_bf16 v[96:99], v[212:215], v[228:231], v[96:99]
	v_mfma_f32_16x16x32_bf16 v[84:87], v[200:203], v[236:239], v[84:87]
	v_mfma_f32_16x16x32_bf16 v[80:83], v[212:215], v[236:239], v[80:83]
	v_mfma_f32_16x16x32_bf16 v[68:71], v[200:203], v[244:247], v[68:71]
	v_mfma_f32_16x16x32_bf16 v[64:67], v[212:215], v[244:247], v[64:67]
	s_setprio 0
	s_barrier
	s_add_i32 s38, s57, s21
	v_lshl_add_u64 v[182:183], s[44:45], 0, v[128:129]
	s_mov_b32 m0, s38
	ds_read_b128 v[216:219], v186 offset:16384
	ds_read_b128 v[220:223], v186 offset:17408
	ds_read_b128 v[224:227], v186 offset:18432
	ds_read_b128 v[228:231], v186 offset:19456
	ds_read_b128 v[232:235], v186 offset:20480
	ds_read_b128 v[236:239], v186 offset:21504
	ds_read_b128 v[240:243], v186 offset:22528
	ds_read_b128 v[244:247], v186 offset:23552
	global_load_lds_dwordx4 v[182:183], off
	s_add_i32 m0, s38, 0x2000
	s_add_u32 s38, s44, 0xb0000
	v_lshl_add_u64 v[204:205], s[44:45], 0, v[130:131]
	s_addc_u32 s39, s45, 0
	s_add_i32 s78, s64, s21
	global_load_lds_dwordx4 v[204:205], off
	v_lshl_add_u64 v[248:249], s[38:39], 0, v[128:129]
	s_mov_b32 m0, s78
	v_lshl_add_u64 v[250:251], s[46:47], 0, v[130:131]
	global_load_lds_dwordx4 v[248:249], off
	v_lshl_add_u64 v[248:249], s[38:39], 0, v[130:131]
	s_add_i32 m0, s78, 0x2000
	s_nop 0
	global_load_lds_dwordx4 v[248:249], off
	v_lshl_add_u64 v[248:249], s[46:47], 0, v[128:129]
	s_mov_b32 m0, s30
	s_nop 0
	global_load_lds_dwordx4 v[248:249], off
	s_mov_b32 m0, s31
	s_nop 0
	global_load_lds_dwordx4 v[250:251], off
	s_waitcnt vmcnt(8)
	s_waitcnt lgkmcnt(0)
	s_barrier
; #define PG8_STAGE(bufoff, gbase, voff) do { _Pragma("unroll") for (int _i = 0; _i < 2; ++_i) \
;         __builtin_amdgcn_global_load_lds((const unsigned*)((const char*)(gbase) + (voff)[_i]), (LAS unsigned*)(lds + (bufoff) + ldsw + _i * 8192), 16, 0, 0); } while (0)
; #define PG8_LDA(dst, b, h) do { _Pragma("unroll") for (int m = 0; m < 4; ++m) _Pragma("unroll") for (int k = 0; k < 2; ++k) dst[m][k] = *(const LAS bf16x8*)(lds + PG8_SA(b, h) + aoff + m * 2048 + k * 1024); } while (0)
; #define PG8_LDB(dst, b, h) do { _Pragma("unroll") for (int n = 0; n < 2; ++n) _Pragma("unroll") for (int k = 0; k < 2; ++k) dst[n][k] = *(const LAS bf16x8*)(lds + PG8_SB(b, h) + boff + n * 2048 + k * 1024); } while (0)
; #define PG8_WAIT_V(n) asm volatile("s_waitcnt vmcnt(" #n ")" ::: "memory")
; #define PG8_WAIT_L(n) asm volatile("s_waitcnt lgkmcnt(" #n ")" ::: "memory")
; #define PG8_BAR __builtin_amdgcn_s_barrier()
; #define PG8_SCHED __builtin_amdgcn_sched_barrier(0)
; template <class Epi, class Sched, bool SWAPD = false>
; __device__ __forceinline__ void gemm_phase(LAS unsigned char* lds, const Gemm g, const Sched& S, const Epi& E) {
;     ...
;             PG8_WAIT_V(8); PG8_WAIT_L(0); PG8_BAR; PG8_MMA(1, 0, At, B0); PG8_MMA(1, 1, At, B1); PG8_BAR; PG8_SCHED;
;             PG8_LDB(B0, 1, 0); PG8_LDB(B1, 1, 1); PG8_SCHED; PG8_LDA(At, 1, 0); PG8_STAGE(PG8_SA(0, 1), a2 + hstepA, voffA);
;             PG8_WAIT_V(8); PG8_WAIT_L(0); PG8_BAR; PG8_MMA(0, 0, At, B0); PG8_MMA(0, 1, At, B1); PG8_BAR; PG8_SCHED;
;             PG8_LDA(At, 1, 1); PG8_STAGE(PG8_SB(1, 0), b3, voffB); PG8_STAGE(PG8_SB(1, 1), b3 + hstepB, voffB); PG8_STAGE(PG8_SA(1, 0), a3, voffA);
	s_setprio 1
	v_mfma_f32_16x16x32_bf16 v[60:63], v[174:177], v[216:219], v[60:63]
	v_mfma_f32_16x16x32_bf16 v[56:59], v[188:191], v[216:219], v[56:59]
	v_mfma_f32_16x16x32_bf16 v[44:47], v[174:177], v[224:227], v[44:47]
	v_mfma_f32_16x16x32_bf16 v[40:43], v[188:191], v[224:227], v[40:43]
	v_mfma_f32_16x16x32_bf16 v[28:31], v[174:177], v[232:235], v[28:31]
	v_mfma_f32_16x16x32_bf16 v[24:27], v[188:191], v[232:235], v[24:27]
	v_mfma_f32_16x16x32_bf16 v[12:15], v[174:177], v[240:243], v[12:15]
	v_mfma_f32_16x16x32_bf16 v[8:11], v[188:191], v[240:243], v[8:11]
	v_mfma_f32_16x16x32_bf16 v[60:63], v[178:181], v[220:223], v[60:63]
	v_mfma_f32_16x16x32_bf16 v[56:59], v[192:195], v[220:223], v[56:59]
	v_mfma_f32_16x16x32_bf16 v[44:47], v[178:181], v[228:231], v[44:47]
	v_mfma_f32_16x16x32_bf16 v[40:43], v[192:195], v[228:231], v[40:43]
	v_mfma_f32_16x16x32_bf16 v[28:31], v[178:181], v[236:239], v[28:31]
	v_mfma_f32_16x16x32_bf16 v[24:27], v[192:195], v[236:239], v[24:27]
	v_mfma_f32_16x16x32_bf16 v[12:15], v[178:181], v[244:247], v[12:15]
	v_mfma_f32_16x16x32_bf16 v[8:11], v[192:195], v[244:247], v[8:11]
	s_setprio 0
	s_setprio 1
	v_mfma_f32_16x16x32_bf16 v[52:55], v[196:199], v[216:219], v[52:55]
	v_mfma_f32_16x16x32_bf16 v[48:51], v[208:211], v[216:219], v[48:51]
	v_mfma_f32_16x16x32_bf16 v[36:39], v[196:199], v[224:227], v[36:39]
	v_mfma_f32_16x16x32_bf16 v[32:35], v[208:211], v[224:227], v[32:35]
	v_mfma_f32_16x16x32_bf16 v[20:23], v[196:199], v[232:235], v[20:23]
	v_mfma_f32_16x16x32_bf16 v[16:19], v[208:211], v[232:235], v[16:19]
	v_mfma_f32_16x16x32_bf16 v[4:7], v[196:199], v[240:243], v[4:7]
	v_mfma_f32_16x16x32_bf16 v[0:3], v[208:211], v[240:243], v[0:3]
	v_mfma_f32_16x16x32_bf16 v[52:55], v[200:203], v[220:223], v[52:55]
	v_mfma_f32_16x16x32_bf16 v[48:51], v[212:215], v[220:223], v[48:51]
	v_mfma_f32_16x16x32_bf16 v[36:39], v[200:203], v[228:231], v[36:39]
	v_mfma_f32_16x16x32_bf16 v[32:35], v[212:215], v[228:231], v[32:35]
	v_mfma_f32_16x16x32_bf16 v[20:23], v[200:203], v[236:239], v[20:23]
	v_mfma_f32_16x16x32_bf16 v[16:19], v[212:215], v[236:239], v[16:19]
	v_mfma_f32_16x16x32_bf16 v[4:7], v[200:203], v[244:247], v[4:7]
	v_mfma_f32_16x16x32_bf16 v[0:3], v[212:215], v[244:247], v[0:3]
	s_setprio 0
	s_barrier
	s_add_i32 s78, 0, 0x18000
	v_add_u32_e32 v132, s78, v184
	s_add_i32 s79, 0, 0x1c000
	ds_read_b128 v[174:177], v132
	ds_read_b128 v[178:181], v132 offset:1024
	ds_read_b128 v[188:191], v132 offset:2048
	ds_read_b128 v[192:195], v132 offset:3072
	v_add_u32_e32 v132, s79, v184
	ds_read_b128 v[196:199], v132
	ds_read_b128 v[200:203], v132 offset:1024
	ds_read_b128 v[208:211], v132 offset:2048
	ds_read_b128 v[212:215], v132 offset:3072
	s_add_u32 s38, s46, 0xb0000
	s_addc_u32 s39, s47, 0
	s_mov_b32 m0, s50
	v_lshl_add_u64 v[252:253], s[38:39], 0, v[128:129]
	ds_read_b128 v[216:219], v186 offset:32768
	ds_read_b128 v[220:223], v186 offset:33792
	ds_read_b128 v[224:227], v186 offset:34816
	ds_read_b128 v[228:231], v186 offset:35840
	ds_read_b128 v[232:235], v186 offset:36864
	ds_read_b128 v[236:239], v186 offset:37888
	ds_read_b128 v[240:243], v186 offset:38912
	ds_read_b128 v[244:247], v186 offset:39936
	global_load_lds_dwordx4 v[252:253], off
	v_lshl_add_u64 v[252:253], s[38:39], 0, v[130:131]
	s_mov_b32 m0, s51
	s_nop 0
	global_load_lds_dwordx4 v[252:253], off
	s_waitcnt vmcnt(8)
	s_waitcnt lgkmcnt(0)
	s_barrier
	s_setprio 1
	v_mfma_f32_16x16x32_bf16 v[124:127], v[174:177], v[216:219], v[124:127]
	v_mfma_f32_16x16x32_bf16 v[120:123], v[188:191], v[216:219], v[120:123]
	v_mfma_f32_16x16x32_bf16 v[108:111], v[174:177], v[224:227], v[108:111]
	v_mfma_f32_16x16x32_bf16 v[104:107], v[188:191], v[224:227], v[104:107]
	v_mfma_f32_16x16x32_bf16 v[92:95], v[174:177], v[232:235], v[92:95]
	v_mfma_f32_16x16x32_bf16 v[88:91], v[188:191], v[232:235], v[88:91]
	v_mfma_f32_16x16x32_bf16 v[76:79], v[174:177], v[240:243], v[76:79]
	v_mfma_f32_16x16x32_bf16 v[72:75], v[188:191], v[240:243], v[72:75]
	v_mfma_f32_16x16x32_bf16 v[124:127], v[178:181], v[220:223], v[124:127]
	v_mfma_f32_16x16x32_bf16 v[120:123], v[192:195], v[220:223], v[120:123]
	v_mfma_f32_16x16x32_bf16 v[108:111], v[178:181], v[228:231], v[108:111]
	v_mfma_f32_16x16x32_bf16 v[104:107], v[192:195], v[228:231], v[104:107]
	v_mfma_f32_16x16x32_bf16 v[92:95], v[178:181], v[236:239], v[92:95]
	v_mfma_f32_16x16x32_bf16 v[88:91], v[192:195], v[236:239], v[88:91]
	v_mfma_f32_16x16x32_bf16 v[76:79], v[178:181], v[244:247], v[76:79]
	v_mfma_f32_16x16x32_bf16 v[72:75], v[192:195], v[244:247], v[72:75]
	s_setprio 0
	s_setprio 1
	v_mfma_f32_16x16x32_bf16 v[116:119], v[196:199], v[216:219], v[116:119]
	v_mfma_f32_16x16x32_bf16 v[112:115], v[208:211], v[216:219], v[112:115]
	v_mfma_f32_16x16x32_bf16 v[100:103], v[196:199], v[224:227], v[100:103]
	v_mfma_f32_16x16x32_bf16 v[96:99], v[208:211], v[224:227], v[96:99]
	v_mfma_f32_16x16x32_bf16 v[84:87], v[196:199], v[232:235], v[84:87]
	v_mfma_f32_16x16x32_bf16 v[80:83], v[208:211], v[232:235], v[80:83]
	v_mfma_f32_16x16x32_bf16 v[68:71], v[196:199], v[240:243], v[68:71]
	v_mfma_f32_16x16x32_bf16 v[64:67], v[208:211], v[240:243], v[64:67]
	v_mfma_f32_16x16x32_bf16 v[116:119], v[200:203], v[220:223], v[116:119]
	v_mfma_f32_16x16x32_bf16 v[112:115], v[212:215], v[220:223], v[112:115]
	v_mfma_f32_16x16x32_bf16 v[100:103], v[200:203], v[228:231], v[100:103]
	v_mfma_f32_16x16x32_bf16 v[96:99], v[212:215], v[228:231], v[96:99]
	v_mfma_f32_16x16x32_bf16 v[84:87], v[200:203], v[236:239], v[84:87]
	v_mfma_f32_16x16x32_bf16 v[80:83], v[212:215], v[236:239], v[80:83]
	v_mfma_f32_16x16x32_bf16 v[68:71], v[200:203], v[244:247], v[68:71]
	v_mfma_f32_16x16x32_bf16 v[64:67], v[212:215], v[244:247], v[64:67]
	s_setprio 0
	s_barrier
; #define PG8_STAGE(bufoff, gbase, voff) do { _Pragma("unroll") for (int _i = 0; _i < 2; ++_i) \
;         __builtin_amdgcn_global_load_lds((const unsigned*)((const char*)(gbase) + (voff)[_i]), (LAS unsigned*)(lds + (bufoff) + ldsw + _i * 8192), 16, 0, 0); } while (0)
; #define PG8_LDA(dst, b, h) do { _Pragma("unroll") for (int m = 0; m < 4; ++m) _Pragma("unroll") for (int k = 0; k < 2; ++k) dst[m][k] = *(const LAS bf16x8*)(lds + PG8_SA(b, h) + aoff + m * 2048 + k * 1024); } while (0)
; #define PG8_WAIT_V(n) asm volatile("s_waitcnt vmcnt(" #n ")" ::: "memory")
; #define PG8_WAIT_L(n) asm volatile("s_waitcnt lgkmcnt(" #n ")" ::: "memory")
; #define PG8_BAR __builtin_amdgcn_s_barrier()
; #define PG8_SCHED __builtin_amdgcn_sched_barrier(0)
; template <class Epi, class Sched, bool SWAPD = false>
; __device__ __forceinline__ void gemm_phase(LAS unsigned char* lds, const Gemm g, const Sched& S, const Epi& E) {
;     ...
;             PG8_WAIT_V(8); PG8_WAIT_L(0); PG8_BAR; PG8_MMA(0, 0, At, B0); PG8_MMA(0, 1, At, B1); PG8_BAR; PG8_SCHED;
;             PG8_LDA(At, 1, 1); PG8_STAGE(PG8_SB(1, 0), b3, voffB); PG8_STAGE(PG8_SB(1, 1), b3 + hstepB, voffB); PG8_STAGE(PG8_SA(1, 0), a3, voffA);
;             PG8_WAIT_V(8); PG8_WAIT_L(0); PG8_BAR; PG8_MMA(1, 0, At, B0); PG8_MMA(1, 1, At, B1); PG8_BAR; PG8_SCHED;
;         }
	s_add_i32 s38, s78, s21
	v_lshl_add_u64 v[182:183], v[182:183], 0, s[8:9]
	s_mov_b32 m0, s38
	ds_read_b128 v[216:219], v186 offset:49152
	ds_read_b128 v[220:223], v186 offset:50176
	ds_read_b128 v[224:227], v186 offset:51200
	ds_read_b128 v[228:231], v186 offset:52224
	ds_read_b128 v[232:235], v186 offset:53248
	ds_read_b128 v[236:239], v186 offset:54272
	ds_read_b128 v[240:243], v186 offset:55296
	ds_read_b128 v[244:247], v186 offset:56320
	global_load_lds_dwordx4 v[182:183], off
	s_add_i32 m0, s38, 0x2000
	s_add_u32 s38, s44, 0xb0080
	v_lshl_add_u64 v[182:183], v[204:205], 0, s[8:9]
	s_addc_u32 s39, s45, 0
	s_add_i32 s44, s79, s21
	global_load_lds_dwordx4 v[182:183], off
	v_lshl_add_u64 v[182:183], s[38:39], 0, v[128:129]
	s_mov_b32 m0, s44
	s_nop 0
	global_load_lds_dwordx4 v[182:183], off
	v_lshl_add_u64 v[182:183], s[38:39], 0, v[130:131]
	s_add_i32 m0, s44, 0x2000
	s_nop 0
	global_load_lds_dwordx4 v[182:183], off
	v_lshl_add_u64 v[182:183], v[248:249], 0, s[8:9]
	s_mov_b32 m0, s54
	s_nop 0
	global_load_lds_dwordx4 v[182:183], off
	v_lshl_add_u64 v[182:183], v[250:251], 0, s[8:9]
	s_mov_b32 m0, s55
	s_nop 0
	global_load_lds_dwordx4 v[182:183], off
	s_waitcnt vmcnt(8)
	s_waitcnt lgkmcnt(0)
	s_barrier
	s_setprio 1
	v_mfma_f32_16x16x32_bf16 v[60:63], v[174:177], v[216:219], v[60:63]
	v_mfma_f32_16x16x32_bf16 v[56:59], v[188:191], v[216:219], v[56:59]
	v_mfma_f32_16x16x32_bf16 v[44:47], v[174:177], v[224:227], v[44:47]
	v_mfma_f32_16x16x32_bf16 v[40:43], v[188:191], v[224:227], v[40:43]
	v_mfma_f32_16x16x32_bf16 v[28:31], v[174:177], v[232:235], v[28:31]
	v_mfma_f32_16x16x32_bf16 v[24:27], v[188:191], v[232:235], v[24:27]
	v_mfma_f32_16x16x32_bf16 v[12:15], v[174:177], v[240:243], v[12:15]
	v_mfma_f32_16x16x32_bf16 v[8:11], v[188:191], v[240:243], v[8:11]
	v_mfma_f32_16x16x32_bf16 v[60:63], v[178:181], v[220:223], v[60:63]
	v_mfma_f32_16x16x32_bf16 v[56:59], v[192:195], v[220:223], v[56:59]
	v_mfma_f32_16x16x32_bf16 v[44:47], v[178:181], v[228:231], v[44:47]
	v_mfma_f32_16x16x32_bf16 v[40:43], v[192:195], v[228:231], v[40:43]
	v_mfma_f32_16x16x32_bf16 v[28:31], v[178:181], v[236:239], v[28:31]
	v_mfma_f32_16x16x32_bf16 v[24:27], v[192:195], v[236:239], v[24:27]
	v_mfma_f32_16x16x32_bf16 v[12:15], v[178:181], v[244:247], v[12:15]
	v_mfma_f32_16x16x32_bf16 v[8:11], v[192:195], v[244:247], v[8:11]
	s_setprio 0
	s_setprio 1
	v_mfma_f32_16x16x32_bf16 v[52:55], v[196:199], v[216:219], v[52:55]
	v_mfma_f32_16x16x32_bf16 v[48:51], v[208:211], v[216:219], v[48:51]
	v_mfma_f32_16x16x32_bf16 v[36:39], v[196:199], v[224:227], v[36:39]
	v_mfma_f32_16x16x32_bf16 v[32:35], v[208:211], v[224:227], v[32:35]
	v_mfma_f32_16x16x32_bf16 v[20:23], v[196:199], v[232:235], v[20:23]
	v_mfma_f32_16x16x32_bf16 v[16:19], v[208:211], v[232:235], v[16:19]
	v_mfma_f32_16x16x32_bf16 v[4:7], v[196:199], v[240:243], v[4:7]
	v_mfma_f32_16x16x32_bf16 v[0:3], v[208:211], v[240:243], v[0:3]
	v_mfma_f32_16x16x32_bf16 v[52:55], v[200:203], v[220:223], v[52:55]
	v_mfma_f32_16x16x32_bf16 v[48:51], v[212:215], v[220:223], v[48:51]
	v_mfma_f32_16x16x32_bf16 v[36:39], v[200:203], v[228:231], v[36:39]
	v_mfma_f32_16x16x32_bf16 v[32:35], v[212:215], v[228:231], v[32:35]
	v_mfma_f32_16x16x32_bf16 v[20:23], v[200:203], v[236:239], v[20:23]
	v_mfma_f32_16x16x32_bf16 v[16:19], v[212:215], v[236:239], v[16:19]
	v_mfma_f32_16x16x32_bf16 v[4:7], v[200:203], v[244:247], v[4:7]
	v_mfma_f32_16x16x32_bf16 v[0:3], v[212:215], v[244:247], v[0:3]
	s_setprio 0
	s_add_u32 s75, s75, 0x100
	s_addc_u32 s76, s76, 0
	s_cmp_ge_i32 s77, s0
	s_mov_b64 s[38:39], s[42:43]
	s_mov_b32 s44, s77
	s_barrier
	s_cbranch_scc0 .LBB0_353
	s_and_b64 vcc, exec, s[10:11]
	s_cbranch_vccz .LBB0_359

; #define PG8_STAGE(bufoff, gbase, voff) do { _Pragma("unroll") for (int _i = 0; _i < 2; ++_i) \
;         __builtin_amdgcn_global_load_lds((const unsigned*)((const char*)(gbase) + (voff)[_i]), (LAS unsigned*)(lds + (bufoff) + ldsw + _i * 8192), 16, 0, 0); } while (0)
; #define PG8_LDA(dst, b, h) do { _Pragma("unroll") for (int m = 0; m < 4; ++m) _Pragma("unroll") for (int k = 0; k < 2; ++k) dst[m][k] = *(const LAS bf16x8*)(lds + PG8_SA(b, h) + aoff + m * 2048 + k * 1024); } while (0)
; #define PG8_LDB(dst, b, h) do { _Pragma("unroll") for (int n = 0; n < 2; ++n) _Pragma("unroll") for (int k = 0; k < 2; ++k) dst[n][k] = *(const LAS bf16x8*)(lds + PG8_SB(b, h) + boff + n * 2048 + k * 1024); } while (0)
; #define PG8_WAIT_V(n) asm volatile("s_waitcnt vmcnt(" #n ")" ::: "memory")
; #define PG8_WAIT_L(n) asm volatile("s_waitcnt lgkmcnt(" #n ")" ::: "memory")
; #define PG8_BAR __builtin_amdgcn_s_barrier()
; #define PG8_SCHED __builtin_amdgcn_sched_barrier(0)
; template <class Epi, class Sched, bool SWAPD = false>
; __device__ __forceinline__ void gemm_phase(LAS unsigned char* lds, const Gemm g, const Sched& S, const Epi& E) {
;     ...
;         for (int t = 0; t < nt; t += 2) {
;             const bool last = (t == nt - 2);
;             const char* a1 = cA + (size_t)(t + 1) * kstepA;
;             const char* a2 = last ? nA : cA + (size_t)(t + 2) * kstepA; const char* b2 = last ? nB : cB + (size_t)(t + 2) * kstep;
;             const char* a3 = a2 + kstepA; const char* b3 = b2 + kstep;
;             PG8_LDB(B0, 0, 0); PG8_LDB(B1, 0, 1); PG8_SCHED; PG8_LDA(At, 0, 0); PG8_STAGE(PG8_SA(1, 1), a1 + hstepA, voffA);
;             PG8_WAIT_V(8); PG8_WAIT_L(0); PG8_BAR; PG8_MMA(0, 0, At, B0); PG8_MMA(0, 1, At, B1); PG8_BAR; PG8_SCHED;
;             PG8_LDA(At, 0, 1); PG8_STAGE(PG8_SB(0, 0), b2, voffB); PG8_STAGE(PG8_SB(0, 1), b2 + hstepB, voffB); PG8_STAGE(PG8_SA(0, 0), a2, voffA);
;             PG8_WAIT_V(8); PG8_WAIT_L(0); PG8_BAR; PG8_MMA(1, 0, At, B0); PG8_MMA(1, 1, At, B1); PG8_BAR; PG8_SCHED;
.LBB0_486:
	ds_read_b128 v[152:155], v149
	ds_read_b128 v[156:159], v149 offset:1024
	ds_read_b128 v[160:163], v149 offset:2048
	ds_read_b128 v[164:167], v149 offset:3072
	ds_read_b128 v[168:171], v150
	ds_read_b128 v[172:175], v150 offset:1024
	ds_read_b128 v[176:179], v150 offset:2048
	ds_read_b128 v[180:183], v150 offset:3072
	s_add_u32 s42, s40, 0xfffc0080
	s_addc_u32 s43, s41, -1
	s_cmp_eq_u32 s66, 12
	s_cselect_b32 s45, s7, s43
	s_cselect_b32 s44, s13, s42
	s_cselect_b32 s43, s25, s65
	s_cselect_b32 s42, s57, s64
	v_lshl_add_u64 v[204:205], s[40:41], 0, v[138:139]
	s_add_i32 m0, s30, 0xc000
	ds_read_b128 v[184:187], v151
	ds_read_b128 v[188:191], v151 offset:1024
	ds_read_b128 v[192:195], v151 offset:2048
	ds_read_b128 v[196:199], v151 offset:3072
	ds_read_b128 v[200:203], v151 offset:4096
	ds_read_b128 v[208:211], v151 offset:5120
	ds_read_b128 v[212:215], v151 offset:6144
	ds_read_b128 v[216:219], v151 offset:7168
	global_load_lds_dwordx4 v[204:205], off
	v_lshl_add_u64 v[204:205], s[40:41], 0, v[140:141]
	s_add_i32 m0, s30, 0xe000
	s_nop 0
	global_load_lds_dwordx4 v[204:205], off
	s_waitcnt vmcnt(8)
	s_waitcnt lgkmcnt(0)
	s_barrier
	s_setprio 1
	v_mfma_f32_16x16x32_bf16 v[124:127], v[152:155], v[184:187], v[124:127]
	v_mfma_f32_16x16x32_bf16 v[120:123], v[160:163], v[184:187], v[120:123]
	v_mfma_f32_16x16x32_bf16 v[108:111], v[152:155], v[192:195], v[108:111]
	v_mfma_f32_16x16x32_bf16 v[104:107], v[160:163], v[192:195], v[104:107]
	v_mfma_f32_16x16x32_bf16 v[92:95], v[152:155], v[200:203], v[92:95]
	v_mfma_f32_16x16x32_bf16 v[88:91], v[160:163], v[200:203], v[88:91]
	v_mfma_f32_16x16x32_bf16 v[76:79], v[152:155], v[212:215], v[76:79]
	v_mfma_f32_16x16x32_bf16 v[72:75], v[160:163], v[212:215], v[72:75]
	v_mfma_f32_16x16x32_bf16 v[124:127], v[156:159], v[188:191], v[124:127]
	v_mfma_f32_16x16x32_bf16 v[120:123], v[164:167], v[188:191], v[120:123]
	v_mfma_f32_16x16x32_bf16 v[108:111], v[156:159], v[196:199], v[108:111]
	v_mfma_f32_16x16x32_bf16 v[104:107], v[164:167], v[196:199], v[104:107]
	v_mfma_f32_16x16x32_bf16 v[92:95], v[156:159], v[208:211], v[92:95]
	v_mfma_f32_16x16x32_bf16 v[88:91], v[164:167], v[208:211], v[88:91]
	v_mfma_f32_16x16x32_bf16 v[76:79], v[156:159], v[216:219], v[76:79]
	v_mfma_f32_16x16x32_bf16 v[72:75], v[164:167], v[216:219], v[72:75]
	s_setprio 0
	s_setprio 1
	v_mfma_f32_16x16x32_bf16 v[116:119], v[168:171], v[184:187], v[116:119]
	v_mfma_f32_16x16x32_bf16 v[112:115], v[176:179], v[184:187], v[112:115]
	v_mfma_f32_16x16x32_bf16 v[100:103], v[168:171], v[192:195], v[100:103]
	v_mfma_f32_16x16x32_bf16 v[96:99], v[176:179], v[192:195], v[96:99]
	v_mfma_f32_16x16x32_bf16 v[84:87], v[168:171], v[200:203], v[84:87]
	v_mfma_f32_16x16x32_bf16 v[80:83], v[176:179], v[200:203], v[80:83]
	v_mfma_f32_16x16x32_bf16 v[68:71], v[168:171], v[212:215], v[68:71]
	v_mfma_f32_16x16x32_bf16 v[64:67], v[176:179], v[212:215], v[64:67]
	v_mfma_f32_16x16x32_bf16 v[116:119], v[172:175], v[188:191], v[116:119]
	v_mfma_f32_16x16x32_bf16 v[112:115], v[180:183], v[188:191], v[112:115]
	v_mfma_f32_16x16x32_bf16 v[100:103], v[172:175], v[196:199], v[100:103]
	v_mfma_f32_16x16x32_bf16 v[96:99], v[180:183], v[196:199], v[96:99]
	v_mfma_f32_16x16x32_bf16 v[84:87], v[172:175], v[208:211], v[84:87]
	v_mfma_f32_16x16x32_bf16 v[80:83], v[180:183], v[208:211], v[80:83]
	v_mfma_f32_16x16x32_bf16 v[68:71], v[172:175], v[216:219], v[68:71]
	v_mfma_f32_16x16x32_bf16 v[64:67], v[180:183], v[216:219], v[64:67]
	s_setprio 0
	s_barrier
	s_add_i32 s67, s35, s21
	v_lshl_add_u64 v[204:205], s[42:43], 0, v[128:129]
	s_mov_b32 m0, s67
	ds_read_b128 v[184:187], v151 offset:16384
	ds_read_b128 v[188:191], v151 offset:17408
	ds_read_b128 v[192:195], v151 offset:18432
	ds_read_b128 v[196:199], v151 offset:19456
	ds_read_b128 v[200:203], v151 offset:20480
	ds_read_b128 v[208:211], v151 offset:21504
	ds_read_b128 v[212:215], v151 offset:22528
	ds_read_b128 v[216:219], v151 offset:23552
	global_load_lds_dwordx4 v[204:205], off
	s_add_i32 m0, s67, 0x2000
	s_add_u32 s68, s42, 0x40000
	v_lshl_add_u64 v[220:221], s[42:43], 0, v[130:131]
	s_addc_u32 s69, s43, 0
	s_add_i32 s67, s53, s21
	global_load_lds_dwordx4 v[220:221], off
	v_lshl_add_u64 v[222:223], s[68:69], 0, v[128:129]
	s_mov_b32 m0, s67
	v_lshl_add_u64 v[224:225], s[44:45], 0, v[130:131]
	global_load_lds_dwordx4 v[222:223], off
	v_lshl_add_u64 v[222:223], s[68:69], 0, v[130:131]
	s_add_i32 m0, s67, 0x2000
	s_nop 0
	global_load_lds_dwordx4 v[222:223], off
	v_lshl_add_u64 v[222:223], s[44:45], 0, v[128:129]
	s_mov_b32 m0, s30
	s_nop 0
	global_load_lds_dwordx4 v[222:223], off
	s_mov_b32 m0, s31
	s_nop 0
	global_load_lds_dwordx4 v[224:225], off
	s_waitcnt vmcnt(8)
	s_waitcnt lgkmcnt(0)
	s_barrier
; #define PG8_STAGE(bufoff, gbase, voff) do { _Pragma("unroll") for (int _i = 0; _i < 2; ++_i) \
;         __builtin_amdgcn_global_load_lds((const unsigned*)((const char*)(gbase) + (voff)[_i]), (LAS unsigned*)(lds + (bufoff) + ldsw + _i * 8192), 16, 0, 0); } while (0)
; #define PG8_LDA(dst, b, h) do { _Pragma("unroll") for (int m = 0; m < 4; ++m) _Pragma("unroll") for (int k = 0; k < 2; ++k) dst[m][k] = *(const LAS bf16x8*)(lds + PG8_SA(b, h) + aoff + m * 2048 + k * 1024); } while (0)
; #define PG8_LDB(dst, b, h) do { _Pragma("unroll") for (int n = 0; n < 2; ++n) _Pragma("unroll") for (int k = 0; k < 2; ++k) dst[n][k] = *(const LAS bf16x8*)(lds + PG8_SB(b, h) + boff + n * 2048 + k * 1024); } while (0)
; #define PG8_WAIT_V(n) asm volatile("s_waitcnt vmcnt(" #n ")" ::: "memory")
; #define PG8_WAIT_L(n) asm volatile("s_waitcnt lgkmcnt(" #n ")" ::: "memory")
; #define PG8_BAR __builtin_amdgcn_s_barrier()
; #define PG8_SCHED __builtin_amdgcn_sched_barrier(0)
; template <class Epi, class Sched, bool SWAPD = false>
; __device__ __forceinline__ void gemm_phase(LAS unsigned char* lds, const Gemm g, const Sched& S, const Epi& E) {
;     ...
;             PG8_WAIT_V(8); PG8_WAIT_L(0); PG8_BAR; PG8_MMA(1, 0, At, B0); PG8_MMA(1, 1, At, B1); PG8_BAR; PG8_SCHED;
;             PG8_LDB(B0, 1, 0); PG8_LDB(B1, 1, 1); PG8_SCHED; PG8_LDA(At, 1, 0); PG8_STAGE(PG8_SA(0, 1), a2 + hstepA, voffA);
;             PG8_WAIT_V(8); PG8_WAIT_L(0); PG8_BAR; PG8_MMA(0, 0, At, B0); PG8_MMA(0, 1, At, B1); PG8_BAR; PG8_SCHED;
;             PG8_LDA(At, 1, 1); PG8_STAGE(PG8_SB(1, 0), b3, voffB); PG8_STAGE(PG8_SB(1, 1), b3 + hstepB, voffB); PG8_STAGE(PG8_SA(1, 0), a3, voffA);
	s_setprio 1
	v_mfma_f32_16x16x32_bf16 v[60:63], v[152:155], v[184:187], v[60:63]
	v_mfma_f32_16x16x32_bf16 v[56:59], v[160:163], v[184:187], v[56:59]
	v_mfma_f32_16x16x32_bf16 v[44:47], v[152:155], v[192:195], v[44:47]
	v_mfma_f32_16x16x32_bf16 v[40:43], v[160:163], v[192:195], v[40:43]
	v_mfma_f32_16x16x32_bf16 v[28:31], v[152:155], v[200:203], v[28:31]
	v_mfma_f32_16x16x32_bf16 v[24:27], v[160:163], v[200:203], v[24:27]
	v_mfma_f32_16x16x32_bf16 v[12:15], v[152:155], v[212:215], v[12:15]
	v_mfma_f32_16x16x32_bf16 v[8:11], v[160:163], v[212:215], v[8:11]
	v_mfma_f32_16x16x32_bf16 v[60:63], v[156:159], v[188:191], v[60:63]
	v_mfma_f32_16x16x32_bf16 v[56:59], v[164:167], v[188:191], v[56:59]
	v_mfma_f32_16x16x32_bf16 v[44:47], v[156:159], v[196:199], v[44:47]
	v_mfma_f32_16x16x32_bf16 v[40:43], v[164:167], v[196:199], v[40:43]
	v_mfma_f32_16x16x32_bf16 v[28:31], v[156:159], v[208:211], v[28:31]
	v_mfma_f32_16x16x32_bf16 v[24:27], v[164:167], v[208:211], v[24:27]
	v_mfma_f32_16x16x32_bf16 v[12:15], v[156:159], v[216:219], v[12:15]
	v_mfma_f32_16x16x32_bf16 v[8:11], v[164:167], v[216:219], v[8:11]
	s_setprio 0
	s_setprio 1
	v_mfma_f32_16x16x32_bf16 v[52:55], v[168:171], v[184:187], v[52:55]
	v_mfma_f32_16x16x32_bf16 v[48:51], v[176:179], v[184:187], v[48:51]
	v_mfma_f32_16x16x32_bf16 v[36:39], v[168:171], v[192:195], v[36:39]
	v_mfma_f32_16x16x32_bf16 v[32:35], v[176:179], v[192:195], v[32:35]
	v_mfma_f32_16x16x32_bf16 v[20:23], v[168:171], v[200:203], v[20:23]
	v_mfma_f32_16x16x32_bf16 v[16:19], v[176:179], v[200:203], v[16:19]
	v_mfma_f32_16x16x32_bf16 v[4:7], v[168:171], v[212:215], v[4:7]
	v_mfma_f32_16x16x32_bf16 v[0:3], v[176:179], v[212:215], v[0:3]
	v_mfma_f32_16x16x32_bf16 v[52:55], v[172:175], v[188:191], v[52:55]
	v_mfma_f32_16x16x32_bf16 v[48:51], v[180:183], v[188:191], v[48:51]
	v_mfma_f32_16x16x32_bf16 v[36:39], v[172:175], v[196:199], v[36:39]
	v_mfma_f32_16x16x32_bf16 v[32:35], v[180:183], v[196:199], v[32:35]
	v_mfma_f32_16x16x32_bf16 v[20:23], v[172:175], v[208:211], v[20:23]
	v_mfma_f32_16x16x32_bf16 v[16:19], v[180:183], v[208:211], v[16:19]
	v_mfma_f32_16x16x32_bf16 v[4:7], v[172:175], v[216:219], v[4:7]
	v_mfma_f32_16x16x32_bf16 v[0:3], v[180:183], v[216:219], v[0:3]
	s_setprio 0
	s_barrier
	s_add_i32 s67, 0, 0x18000
	v_add_u32_e32 v132, s67, v146
	s_add_i32 s68, 0, 0x1c000
	ds_read_b128 v[152:155], v132
	ds_read_b128 v[156:159], v132 offset:1024
	ds_read_b128 v[160:163], v132 offset:2048
	ds_read_b128 v[164:167], v132 offset:3072
	v_add_u32_e32 v132, s68, v146
	ds_read_b128 v[168:171], v132
	ds_read_b128 v[172:175], v132 offset:1024
	ds_read_b128 v[176:179], v132 offset:2048
	ds_read_b128 v[180:183], v132 offset:3072
	s_add_u32 s44, s44, 0x40000
	s_addc_u32 s45, s45, 0
	s_mov_b32 m0, s33
	v_lshl_add_u64 v[226:227], s[44:45], 0, v[128:129]
	ds_read_b128 v[184:187], v151 offset:32768
	ds_read_b128 v[188:191], v151 offset:33792
	ds_read_b128 v[192:195], v151 offset:34816
	ds_read_b128 v[196:199], v151 offset:35840
	ds_read_b128 v[200:203], v151 offset:36864
	ds_read_b128 v[208:211], v151 offset:37888
	ds_read_b128 v[212:215], v151 offset:38912
	ds_read_b128 v[216:219], v151 offset:39936
	global_load_lds_dwordx4 v[226:227], off
	v_lshl_add_u64 v[226:227], s[44:45], 0, v[130:131]
	s_mov_b32 m0, s46
	s_nop 0
	global_load_lds_dwordx4 v[226:227], off
	s_waitcnt vmcnt(8)
	s_waitcnt lgkmcnt(0)
	s_barrier
	s_setprio 1
	v_mfma_f32_16x16x32_bf16 v[124:127], v[152:155], v[184:187], v[124:127]
	v_mfma_f32_16x16x32_bf16 v[120:123], v[160:163], v[184:187], v[120:123]
	v_mfma_f32_16x16x32_bf16 v[108:111], v[152:155], v[192:195], v[108:111]
	v_mfma_f32_16x16x32_bf16 v[104:107], v[160:163], v[192:195], v[104:107]
	v_mfma_f32_16x16x32_bf16 v[92:95], v[152:155], v[200:203], v[92:95]
	v_mfma_f32_16x16x32_bf16 v[88:91], v[160:163], v[200:203], v[88:91]
	v_mfma_f32_16x16x32_bf16 v[76:79], v[152:155], v[212:215], v[76:79]
	v_mfma_f32_16x16x32_bf16 v[72:75], v[160:163], v[212:215], v[72:75]
	v_mfma_f32_16x16x32_bf16 v[124:127], v[156:159], v[188:191], v[124:127]
	v_mfma_f32_16x16x32_bf16 v[120:123], v[164:167], v[188:191], v[120:123]
	v_mfma_f32_16x16x32_bf16 v[108:111], v[156:159], v[196:199], v[108:111]
	v_mfma_f32_16x16x32_bf16 v[104:107], v[164:167], v[196:199], v[104:107]
	v_mfma_f32_16x16x32_bf16 v[92:95], v[156:159], v[208:211], v[92:95]
	v_mfma_f32_16x16x32_bf16 v[88:91], v[164:167], v[208:211], v[88:91]
	v_mfma_f32_16x16x32_bf16 v[76:79], v[156:159], v[216:219], v[76:79]
	v_mfma_f32_16x16x32_bf16 v[72:75], v[164:167], v[216:219], v[72:75]
	s_setprio 0
	s_setprio 1
	v_mfma_f32_16x16x32_bf16 v[116:119], v[168:171], v[184:187], v[116:119]
	v_mfma_f32_16x16x32_bf16 v[112:115], v[176:179], v[184:187], v[112:115]
	v_mfma_f32_16x16x32_bf16 v[100:103], v[168:171], v[192:195], v[100:103]
	v_mfma_f32_16x16x32_bf16 v[96:99], v[176:179], v[192:195], v[96:99]
	v_mfma_f32_16x16x32_bf16 v[84:87], v[168:171], v[200:203], v[84:87]
	v_mfma_f32_16x16x32_bf16 v[80:83], v[176:179], v[200:203], v[80:83]
	v_mfma_f32_16x16x32_bf16 v[68:71], v[168:171], v[212:215], v[68:71]
	v_mfma_f32_16x16x32_bf16 v[64:67], v[176:179], v[212:215], v[64:67]
	v_mfma_f32_16x16x32_bf16 v[116:119], v[172:175], v[188:191], v[116:119]
	v_mfma_f32_16x16x32_bf16 v[112:115], v[180:183], v[188:191], v[112:115]
	v_mfma_f32_16x16x32_bf16 v[100:103], v[172:175], v[196:199], v[100:103]
	v_mfma_f32_16x16x32_bf16 v[96:99], v[180:183], v[196:199], v[96:99]
	v_mfma_f32_16x16x32_bf16 v[84:87], v[172:175], v[208:211], v[84:87]
	v_mfma_f32_16x16x32_bf16 v[80:83], v[180:183], v[208:211], v[80:83]
	v_mfma_f32_16x16x32_bf16 v[68:71], v[172:175], v[216:219], v[68:71]
	v_mfma_f32_16x16x32_bf16 v[64:67], v[180:183], v[216:219], v[64:67]
	s_setprio 0
	s_barrier
; #define PG8_STAGE(bufoff, gbase, voff) do { _Pragma("unroll") for (int _i = 0; _i < 2; ++_i) \
;         __builtin_amdgcn_global_load_lds((const unsigned*)((const char*)(gbase) + (voff)[_i]), (LAS unsigned*)(lds + (bufoff) + ldsw + _i * 8192), 16, 0, 0); } while (0)
; #define PG8_LDA(dst, b, h) do { _Pragma("unroll") for (int m = 0; m < 4; ++m) _Pragma("unroll") for (int k = 0; k < 2; ++k) dst[m][k] = *(const LAS bf16x8*)(lds + PG8_SA(b, h) + aoff + m * 2048 + k * 1024); } while (0)
; #define PG8_WAIT_V(n) asm volatile("s_waitcnt vmcnt(" #n ")" ::: "memory")
; #define PG8_WAIT_L(n) asm volatile("s_waitcnt lgkmcnt(" #n ")" ::: "memory")
; #define PG8_BAR __builtin_amdgcn_s_barrier()
; #define PG8_SCHED __builtin_amdgcn_sched_barrier(0)
; template <class Epi, class Sched, bool SWAPD = false>
; __device__ __forceinline__ void gemm_phase(LAS unsigned char* lds, const Gemm g, const Sched& S, const Epi& E) {
;     ...
;             PG8_WAIT_V(8); PG8_WAIT_L(0); PG8_BAR; PG8_MMA(0, 0, At, B0); PG8_MMA(0, 1, At, B1); PG8_BAR; PG8_SCHED;
;             PG8_LDA(At, 1, 1); PG8_STAGE(PG8_SB(1, 0), b3, voffB); PG8_STAGE(PG8_SB(1, 1), b3 + hstepB, voffB); PG8_STAGE(PG8_SA(1, 0), a3, voffA);
;             PG8_WAIT_V(8); PG8_WAIT_L(0); PG8_BAR; PG8_MMA(1, 0, At, B0); PG8_MMA(1, 1, At, B1); PG8_BAR; PG8_SCHED;
;         }
	s_add_i32 s44, s67, s21
	v_lshl_add_u64 v[204:205], v[204:205], 0, s[8:9]
	s_mov_b32 m0, s44
	ds_read_b128 v[184:187], v151 offset:49152
	ds_read_b128 v[188:191], v151 offset:50176
	ds_read_b128 v[192:195], v151 offset:51200
	ds_read_b128 v[196:199], v151 offset:52224
	ds_read_b128 v[200:203], v151 offset:53248
	ds_read_b128 v[208:211], v151 offset:54272
	ds_read_b128 v[212:215], v151 offset:55296
	ds_read_b128 v[216:219], v151 offset:56320
	global_load_lds_dwordx4 v[204:205], off
	s_add_i32 m0, s44, 0x2000
	s_add_u32 s42, s42, 0x40080
	v_lshl_add_u64 v[204:205], v[220:221], 0, s[8:9]
	s_addc_u32 s43, s43, 0
	s_add_i32 s44, s68, s21
	global_load_lds_dwordx4 v[204:205], off
	v_lshl_add_u64 v[204:205], s[42:43], 0, v[128:129]
	s_mov_b32 m0, s44
	s_nop 0
	global_load_lds_dwordx4 v[204:205], off
	v_lshl_add_u64 v[204:205], s[42:43], 0, v[130:131]
	s_add_i32 m0, s44, 0x2000
	s_nop 0
	global_load_lds_dwordx4 v[204:205], off
	v_lshl_add_u64 v[204:205], v[222:223], 0, s[8:9]
	s_mov_b32 m0, s51
	s_nop 0
	global_load_lds_dwordx4 v[204:205], off
	v_lshl_add_u64 v[204:205], v[224:225], 0, s[8:9]
	s_mov_b32 m0, s52
	s_nop 0
	global_load_lds_dwordx4 v[204:205], off
	s_waitcnt vmcnt(8)
	s_waitcnt lgkmcnt(0)
	s_barrier
	s_setprio 1
	v_mfma_f32_16x16x32_bf16 v[60:63], v[152:155], v[184:187], v[60:63]
	v_mfma_f32_16x16x32_bf16 v[56:59], v[160:163], v[184:187], v[56:59]
	v_mfma_f32_16x16x32_bf16 v[44:47], v[152:155], v[192:195], v[44:47]
	v_mfma_f32_16x16x32_bf16 v[40:43], v[160:163], v[192:195], v[40:43]
	v_mfma_f32_16x16x32_bf16 v[28:31], v[152:155], v[200:203], v[28:31]
	v_mfma_f32_16x16x32_bf16 v[24:27], v[160:163], v[200:203], v[24:27]
	v_mfma_f32_16x16x32_bf16 v[12:15], v[152:155], v[212:215], v[12:15]
	v_mfma_f32_16x16x32_bf16 v[8:11], v[160:163], v[212:215], v[8:11]
	v_mfma_f32_16x16x32_bf16 v[60:63], v[156:159], v[188:191], v[60:63]
	v_mfma_f32_16x16x32_bf16 v[56:59], v[164:167], v[188:191], v[56:59]
	v_mfma_f32_16x16x32_bf16 v[44:47], v[156:159], v[196:199], v[44:47]
	v_mfma_f32_16x16x32_bf16 v[40:43], v[164:167], v[196:199], v[40:43]
	v_mfma_f32_16x16x32_bf16 v[28:31], v[156:159], v[208:211], v[28:31]
	v_mfma_f32_16x16x32_bf16 v[24:27], v[164:167], v[208:211], v[24:27]
	v_mfma_f32_16x16x32_bf16 v[12:15], v[156:159], v[216:219], v[12:15]
	v_mfma_f32_16x16x32_bf16 v[8:11], v[164:167], v[216:219], v[8:11]
	s_setprio 0
	s_setprio 1
	v_mfma_f32_16x16x32_bf16 v[52:55], v[168:171], v[184:187], v[52:55]
	v_mfma_f32_16x16x32_bf16 v[48:51], v[176:179], v[184:187], v[48:51]
	v_mfma_f32_16x16x32_bf16 v[36:39], v[168:171], v[192:195], v[36:39]
	v_mfma_f32_16x16x32_bf16 v[32:35], v[176:179], v[192:195], v[32:35]
	v_mfma_f32_16x16x32_bf16 v[20:23], v[168:171], v[200:203], v[20:23]
	v_mfma_f32_16x16x32_bf16 v[16:19], v[176:179], v[200:203], v[16:19]
	v_mfma_f32_16x16x32_bf16 v[4:7], v[168:171], v[212:215], v[4:7]
	v_mfma_f32_16x16x32_bf16 v[0:3], v[176:179], v[212:215], v[0:3]
	v_mfma_f32_16x16x32_bf16 v[52:55], v[172:175], v[188:191], v[52:55]
	v_mfma_f32_16x16x32_bf16 v[48:51], v[180:183], v[188:191], v[48:51]
	v_mfma_f32_16x16x32_bf16 v[36:39], v[172:175], v[196:199], v[36:39]
	v_mfma_f32_16x16x32_bf16 v[32:35], v[180:183], v[196:199], v[32:35]
	v_mfma_f32_16x16x32_bf16 v[20:23], v[172:175], v[208:211], v[20:23]
	v_mfma_f32_16x16x32_bf16 v[16:19], v[180:183], v[208:211], v[16:19]
	v_mfma_f32_16x16x32_bf16 v[4:7], v[172:175], v[216:219], v[4:7]
	v_mfma_f32_16x16x32_bf16 v[0:3], v[180:183], v[216:219], v[0:3]
	s_setprio 0
	s_add_i32 s66, s66, 2
	s_add_u32 s40, s40, 0x100
	s_addc_u32 s41, s41, 0
	s_add_u32 s64, s64, 0x100
	s_addc_u32 s65, s65, 0
	s_cmp_gt_u32 s66, 13
	s_barrier
	s_cbranch_scc0 .LBB0_486
	s_and_b64 vcc, exec, s[10:11]
	s_cbranch_vccz .LBB0_489
	s_barrier

; #define PG8_STAGE(bufoff, gbase, voff) do { _Pragma("unroll") for (int _i = 0; _i < 2; ++_i) \
;         __builtin_amdgcn_global_load_lds((const unsigned*)((const char*)(gbase) + (voff)[_i]), (LAS unsigned*)(lds + (bufoff) + ldsw + _i * 8192), 16, 0, 0); } while (0)
; #define PG8_LDA(dst, b, h) do { _Pragma("unroll") for (int m = 0; m < 4; ++m) _Pragma("unroll") for (int k = 0; k < 2; ++k) dst[m][k] = *(const LAS bf16x8*)(lds + PG8_SA(b, h) + aoff + m * 2048 + k * 1024); } while (0)
; #define PG8_LDB(dst, b, h) do { _Pragma("unroll") for (int n = 0; n < 2; ++n) _Pragma("unroll") for (int k = 0; k < 2; ++k) dst[n][k] = *(const LAS bf16x8*)(lds + PG8_SB(b, h) + boff + n * 2048 + k * 1024); } while (0)
; #define PG8_WAIT_V(n) asm volatile("s_waitcnt vmcnt(" #n ")" ::: "memory")
; #define PG8_WAIT_L(n) asm volatile("s_waitcnt lgkmcnt(" #n ")" ::: "memory")
; #define PG8_BAR __builtin_amdgcn_s_barrier()
; #define PG8_SCHED __builtin_amdgcn_sched_barrier(0)
; template <class Epi, class Sched, bool SWAPD = false>
; __device__ __forceinline__ void gemm_phase(LAS unsigned char* lds, const Gemm g, const Sched& S, const Epi& E) {
;     ...
;         for (int t = 0; t < nt; t += 2) {
;             const bool last = (t == nt - 2);
;             const char* a1 = cA + (size_t)(t + 1) * kstepA;
;             const char* a2 = last ? nA : cA + (size_t)(t + 2) * kstepA; const char* b2 = last ? nB : cB + (size_t)(t + 2) * kstep;
;             const char* a3 = a2 + kstepA; const char* b3 = b2 + kstep;
;             PG8_LDB(B0, 0, 0); PG8_LDB(B1, 0, 1); PG8_SCHED; PG8_LDA(At, 0, 0); PG8_STAGE(PG8_SA(1, 1), a1 + hstepA, voffA);
;             PG8_WAIT_V(8); PG8_WAIT_L(0); PG8_BAR; PG8_MMA(0, 0, At, B0); PG8_MMA(0, 1, At, B1); PG8_BAR; PG8_SCHED;
;             PG8_LDA(At, 0, 1); PG8_STAGE(PG8_SB(0, 0), b2, voffB); PG8_STAGE(PG8_SB(0, 1), b2 + hstepB, voffB); PG8_STAGE(PG8_SA(0, 0), a2, voffA);
;             PG8_WAIT_V(8); PG8_WAIT_L(0); PG8_BAR; PG8_MMA(1, 0, At, B0); PG8_MMA(1, 1, At, B1); PG8_BAR; PG8_SCHED;
.LBB0_633:
	ds_read_b128 v[152:155], v148
	ds_read_b128 v[156:159], v148 offset:1024
	ds_read_b128 v[160:163], v148 offset:2048
	ds_read_b128 v[164:167], v148 offset:3072
	ds_read_b128 v[168:171], v149
	ds_read_b128 v[172:175], v149 offset:1024
	ds_read_b128 v[176:179], v149 offset:2048
	ds_read_b128 v[180:183], v149 offset:3072
	s_add_u32 s52, s50, 0x100
	s_addc_u32 s53, s51, 0
	s_cmp_eq_u32 s81, 4
	s_cselect_b32 s57, s75, s53
	s_cselect_b32 s56, s76, s52
	s_cselect_b32 s55, s77, s80
	s_cselect_b32 s54, s78, s79
	v_lshl_add_u64 v[204:205], s[50:51], 0, v[138:139]
	s_add_i32 m0, s33, 0xc000
	ds_read_b128 v[184:187], v150
	ds_read_b128 v[188:191], v150 offset:1024
	ds_read_b128 v[192:195], v150 offset:2048
	ds_read_b128 v[196:199], v150 offset:3072
	ds_read_b128 v[200:203], v150 offset:4096
	ds_read_b128 v[208:211], v150 offset:5120
	ds_read_b128 v[212:215], v150 offset:6144
	ds_read_b128 v[216:219], v150 offset:7168
	global_load_lds_dwordx4 v[204:205], off
	v_lshl_add_u64 v[204:205], s[50:51], 0, v[140:141]
	s_add_i32 m0, s33, 0xe000
	s_nop 0
	global_load_lds_dwordx4 v[204:205], off
	s_waitcnt vmcnt(8)
	s_waitcnt lgkmcnt(0)
	s_barrier
	s_setprio 1
	v_mfma_f32_16x16x32_bf16 v[124:127], v[152:155], v[184:187], v[124:127]
	v_mfma_f32_16x16x32_bf16 v[120:123], v[160:163], v[184:187], v[120:123]
	v_mfma_f32_16x16x32_bf16 v[116:119], v[152:155], v[192:195], v[116:119]
	v_mfma_f32_16x16x32_bf16 v[112:115], v[160:163], v[192:195], v[112:115]
	v_mfma_f32_16x16x32_bf16 v[104:107], v[152:155], v[200:203], v[104:107]
	v_mfma_f32_16x16x32_bf16 v[96:99], v[160:163], v[200:203], v[96:99]
	v_mfma_f32_16x16x32_bf16 v[88:91], v[152:155], v[212:215], v[88:91]
	v_mfma_f32_16x16x32_bf16 v[80:83], v[160:163], v[212:215], v[80:83]
	v_mfma_f32_16x16x32_bf16 v[124:127], v[156:159], v[188:191], v[124:127]
	v_mfma_f32_16x16x32_bf16 v[120:123], v[164:167], v[188:191], v[120:123]
	v_mfma_f32_16x16x32_bf16 v[116:119], v[156:159], v[196:199], v[116:119]
	v_mfma_f32_16x16x32_bf16 v[112:115], v[164:167], v[196:199], v[112:115]
	v_mfma_f32_16x16x32_bf16 v[104:107], v[156:159], v[208:211], v[104:107]
	v_mfma_f32_16x16x32_bf16 v[96:99], v[164:167], v[208:211], v[96:99]
	v_mfma_f32_16x16x32_bf16 v[88:91], v[156:159], v[216:219], v[88:91]
	v_mfma_f32_16x16x32_bf16 v[80:83], v[164:167], v[216:219], v[80:83]
	s_setprio 0
	s_setprio 1
	v_mfma_f32_16x16x32_bf16 v[108:111], v[168:171], v[184:187], v[108:111]
	v_mfma_f32_16x16x32_bf16 v[100:103], v[176:179], v[184:187], v[100:103]
	v_mfma_f32_16x16x32_bf16 v[92:95], v[168:171], v[192:195], v[92:95]
	v_mfma_f32_16x16x32_bf16 v[84:87], v[176:179], v[192:195], v[84:87]
	v_mfma_f32_16x16x32_bf16 v[76:79], v[168:171], v[200:203], v[76:79]
	v_mfma_f32_16x16x32_bf16 v[72:75], v[176:179], v[200:203], v[72:75]
	v_mfma_f32_16x16x32_bf16 v[68:71], v[168:171], v[212:215], v[68:71]
	v_mfma_f32_16x16x32_bf16 v[64:67], v[176:179], v[212:215], v[64:67]
	v_mfma_f32_16x16x32_bf16 v[108:111], v[172:175], v[188:191], v[108:111]
	v_mfma_f32_16x16x32_bf16 v[100:103], v[180:183], v[188:191], v[100:103]
	v_mfma_f32_16x16x32_bf16 v[92:95], v[172:175], v[196:199], v[92:95]
	v_mfma_f32_16x16x32_bf16 v[84:87], v[180:183], v[196:199], v[84:87]
	v_mfma_f32_16x16x32_bf16 v[76:79], v[172:175], v[208:211], v[76:79]
	v_mfma_f32_16x16x32_bf16 v[72:75], v[180:183], v[208:211], v[72:75]
	v_mfma_f32_16x16x32_bf16 v[68:71], v[172:175], v[216:219], v[68:71]
	v_mfma_f32_16x16x32_bf16 v[64:67], v[180:183], v[216:219], v[64:67]
	s_setprio 0
	s_barrier
	s_add_i32 s50, s64, s21
	v_lshl_add_u64 v[204:205], s[54:55], 0, v[132:133]
	s_mov_b32 m0, s50
	ds_read_b128 v[184:187], v150 offset:16384
	ds_read_b128 v[188:191], v150 offset:17408
	ds_read_b128 v[192:195], v150 offset:18432
	ds_read_b128 v[196:199], v150 offset:19456
	ds_read_b128 v[200:203], v150 offset:20480
	ds_read_b128 v[208:211], v150 offset:21504
	ds_read_b128 v[212:215], v150 offset:22528
	ds_read_b128 v[216:219], v150 offset:23552
	global_load_lds_dwordx4 v[204:205], off
	s_add_i32 m0, s50, 0x2000
	s_add_u32 s50, s54, 0x20000
	v_lshl_add_u64 v[220:221], s[54:55], 0, v[128:129]
	s_addc_u32 s51, s55, 0
	s_add_i32 s82, s65, s21
	global_load_lds_dwordx4 v[220:221], off
	v_lshl_add_u64 v[222:223], s[50:51], 0, v[132:133]
	s_mov_b32 m0, s82
	v_lshl_add_u64 v[224:225], s[56:57], 0, v[130:131]
	global_load_lds_dwordx4 v[222:223], off
	v_lshl_add_u64 v[222:223], s[50:51], 0, v[128:129]
	s_add_i32 m0, s82, 0x2000
	s_nop 0
	global_load_lds_dwordx4 v[222:223], off
	v_lshl_add_u64 v[222:223], s[56:57], 0, v[134:135]
	s_mov_b32 m0, s33
	s_nop 0
	global_load_lds_dwordx4 v[222:223], off
	s_mov_b32 m0, s34
	s_nop 0
	global_load_lds_dwordx4 v[224:225], off
	s_waitcnt vmcnt(8)
	s_waitcnt lgkmcnt(0)
	s_barrier
; #define PG8_STAGE(bufoff, gbase, voff) do { _Pragma("unroll") for (int _i = 0; _i < 2; ++_i) \
;         __builtin_amdgcn_global_load_lds((const unsigned*)((const char*)(gbase) + (voff)[_i]), (LAS unsigned*)(lds + (bufoff) + ldsw + _i * 8192), 16, 0, 0); } while (0)
; #define PG8_LDA(dst, b, h) do { _Pragma("unroll") for (int m = 0; m < 4; ++m) _Pragma("unroll") for (int k = 0; k < 2; ++k) dst[m][k] = *(const LAS bf16x8*)(lds + PG8_SA(b, h) + aoff + m * 2048 + k * 1024); } while (0)
; #define PG8_LDB(dst, b, h) do { _Pragma("unroll") for (int n = 0; n < 2; ++n) _Pragma("unroll") for (int k = 0; k < 2; ++k) dst[n][k] = *(const LAS bf16x8*)(lds + PG8_SB(b, h) + boff + n * 2048 + k * 1024); } while (0)
; #define PG8_WAIT_V(n) asm volatile("s_waitcnt vmcnt(" #n ")" ::: "memory")
; #define PG8_WAIT_L(n) asm volatile("s_waitcnt lgkmcnt(" #n ")" ::: "memory")
; #define PG8_BAR __builtin_amdgcn_s_barrier()
; #define PG8_SCHED __builtin_amdgcn_sched_barrier(0)
; template <class Epi, class Sched, bool SWAPD = false>
; __device__ __forceinline__ void gemm_phase(LAS unsigned char* lds, const Gemm g, const Sched& S, const Epi& E) {
;     ...
;             PG8_WAIT_V(8); PG8_WAIT_L(0); PG8_BAR; PG8_MMA(1, 0, At, B0); PG8_MMA(1, 1, At, B1); PG8_BAR; PG8_SCHED;
;             PG8_LDB(B0, 1, 0); PG8_LDB(B1, 1, 1); PG8_SCHED; PG8_LDA(At, 1, 0); PG8_STAGE(PG8_SA(0, 1), a2 + hstepA, voffA);
;             PG8_WAIT_V(8); PG8_WAIT_L(0); PG8_BAR; PG8_MMA(0, 0, At, B0); PG8_MMA(0, 1, At, B1); PG8_BAR; PG8_SCHED;
;             PG8_LDA(At, 1, 1); PG8_STAGE(PG8_SB(1, 0), b3, voffB); PG8_STAGE(PG8_SB(1, 1), b3 + hstepB, voffB); PG8_STAGE(PG8_SA(1, 0), a3, voffA);
	s_setprio 1
	v_mfma_f32_16x16x32_bf16 v[60:63], v[152:155], v[184:187], v[60:63]
	v_mfma_f32_16x16x32_bf16 v[56:59], v[160:163], v[184:187], v[56:59]
	v_mfma_f32_16x16x32_bf16 v[52:55], v[152:155], v[192:195], v[52:55]
	v_mfma_f32_16x16x32_bf16 v[48:51], v[160:163], v[192:195], v[48:51]
	v_mfma_f32_16x16x32_bf16 v[40:43], v[152:155], v[200:203], v[40:43]
	v_mfma_f32_16x16x32_bf16 v[32:35], v[160:163], v[200:203], v[32:35]
	v_mfma_f32_16x16x32_bf16 v[24:27], v[152:155], v[212:215], v[24:27]
	v_mfma_f32_16x16x32_bf16 v[16:19], v[160:163], v[212:215], v[16:19]
	v_mfma_f32_16x16x32_bf16 v[60:63], v[156:159], v[188:191], v[60:63]
	v_mfma_f32_16x16x32_bf16 v[56:59], v[164:167], v[188:191], v[56:59]
	v_mfma_f32_16x16x32_bf16 v[52:55], v[156:159], v[196:199], v[52:55]
	v_mfma_f32_16x16x32_bf16 v[48:51], v[164:167], v[196:199], v[48:51]
	v_mfma_f32_16x16x32_bf16 v[40:43], v[156:159], v[208:211], v[40:43]
	v_mfma_f32_16x16x32_bf16 v[32:35], v[164:167], v[208:211], v[32:35]
	v_mfma_f32_16x16x32_bf16 v[24:27], v[156:159], v[216:219], v[24:27]
	v_mfma_f32_16x16x32_bf16 v[16:19], v[164:167], v[216:219], v[16:19]
	s_setprio 0
	s_setprio 1
	v_mfma_f32_16x16x32_bf16 v[44:47], v[168:171], v[184:187], v[44:47]
	v_mfma_f32_16x16x32_bf16 v[36:39], v[176:179], v[184:187], v[36:39]
	v_mfma_f32_16x16x32_bf16 v[28:31], v[168:171], v[192:195], v[28:31]
	v_mfma_f32_16x16x32_bf16 v[20:23], v[176:179], v[192:195], v[20:23]
	v_mfma_f32_16x16x32_bf16 v[12:15], v[168:171], v[200:203], v[12:15]
	v_mfma_f32_16x16x32_bf16 v[8:11], v[176:179], v[200:203], v[8:11]
	v_mfma_f32_16x16x32_bf16 v[4:7], v[168:171], v[212:215], v[4:7]
	v_mfma_f32_16x16x32_bf16 v[0:3], v[176:179], v[212:215], v[0:3]
	v_mfma_f32_16x16x32_bf16 v[44:47], v[172:175], v[188:191], v[44:47]
	v_mfma_f32_16x16x32_bf16 v[36:39], v[180:183], v[188:191], v[36:39]
	v_mfma_f32_16x16x32_bf16 v[28:31], v[172:175], v[196:199], v[28:31]
	v_mfma_f32_16x16x32_bf16 v[20:23], v[180:183], v[196:199], v[20:23]
	v_mfma_f32_16x16x32_bf16 v[12:15], v[172:175], v[208:211], v[12:15]
	v_mfma_f32_16x16x32_bf16 v[8:11], v[180:183], v[208:211], v[8:11]
	v_mfma_f32_16x16x32_bf16 v[4:7], v[172:175], v[216:219], v[4:7]
	v_mfma_f32_16x16x32_bf16 v[0:3], v[180:183], v[216:219], v[0:3]
	s_setprio 0
	s_barrier
	s_add_i32 s82, 0, 0x18000
	v_add_u32_e32 v151, s82, v147
	s_add_i32 s83, 0, 0x1c000
	ds_read_b128 v[152:155], v151
	ds_read_b128 v[156:159], v151 offset:1024
	ds_read_b128 v[160:163], v151 offset:2048
	ds_read_b128 v[164:167], v151 offset:3072
	v_add_u32_e32 v151, s83, v147
	ds_read_b128 v[168:171], v151
	ds_read_b128 v[172:175], v151 offset:1024
	ds_read_b128 v[176:179], v151 offset:2048
	ds_read_b128 v[180:183], v151 offset:3072
	s_add_u32 s50, s56, 0x30000
	s_addc_u32 s51, s57, 0
	s_mov_b32 m0, s35
	v_lshl_add_u64 v[226:227], s[50:51], 0, v[134:135]
	ds_read_b128 v[184:187], v150 offset:32768
	ds_read_b128 v[188:191], v150 offset:33792
	ds_read_b128 v[192:195], v150 offset:34816
	ds_read_b128 v[196:199], v150 offset:35840
	ds_read_b128 v[200:203], v150 offset:36864
	ds_read_b128 v[208:211], v150 offset:37888
	ds_read_b128 v[212:215], v150 offset:38912
	ds_read_b128 v[216:219], v150 offset:39936
	global_load_lds_dwordx4 v[226:227], off
	v_lshl_add_u64 v[226:227], s[50:51], 0, v[130:131]
	s_mov_b32 m0, s58
	s_nop 0
	global_load_lds_dwordx4 v[226:227], off
	s_waitcnt vmcnt(8)
	s_waitcnt lgkmcnt(0)
	s_barrier
	s_setprio 1
	v_mfma_f32_16x16x32_bf16 v[124:127], v[152:155], v[184:187], v[124:127]
	v_mfma_f32_16x16x32_bf16 v[120:123], v[160:163], v[184:187], v[120:123]
	v_mfma_f32_16x16x32_bf16 v[116:119], v[152:155], v[192:195], v[116:119]
	v_mfma_f32_16x16x32_bf16 v[112:115], v[160:163], v[192:195], v[112:115]
	v_mfma_f32_16x16x32_bf16 v[104:107], v[152:155], v[200:203], v[104:107]
	v_mfma_f32_16x16x32_bf16 v[96:99], v[160:163], v[200:203], v[96:99]
	v_mfma_f32_16x16x32_bf16 v[88:91], v[152:155], v[212:215], v[88:91]
	v_mfma_f32_16x16x32_bf16 v[80:83], v[160:163], v[212:215], v[80:83]
	v_mfma_f32_16x16x32_bf16 v[124:127], v[156:159], v[188:191], v[124:127]
	v_mfma_f32_16x16x32_bf16 v[120:123], v[164:167], v[188:191], v[120:123]
	v_mfma_f32_16x16x32_bf16 v[116:119], v[156:159], v[196:199], v[116:119]
	v_mfma_f32_16x16x32_bf16 v[112:115], v[164:167], v[196:199], v[112:115]
	v_mfma_f32_16x16x32_bf16 v[104:107], v[156:159], v[208:211], v[104:107]
	v_mfma_f32_16x16x32_bf16 v[96:99], v[164:167], v[208:211], v[96:99]
	v_mfma_f32_16x16x32_bf16 v[88:91], v[156:159], v[216:219], v[88:91]
	v_mfma_f32_16x16x32_bf16 v[80:83], v[164:167], v[216:219], v[80:83]
	s_setprio 0
	s_setprio 1
	v_mfma_f32_16x16x32_bf16 v[108:111], v[168:171], v[184:187], v[108:111]
	v_mfma_f32_16x16x32_bf16 v[100:103], v[176:179], v[184:187], v[100:103]
	v_mfma_f32_16x16x32_bf16 v[92:95], v[168:171], v[192:195], v[92:95]
	v_mfma_f32_16x16x32_bf16 v[84:87], v[176:179], v[192:195], v[84:87]
	v_mfma_f32_16x16x32_bf16 v[76:79], v[168:171], v[200:203], v[76:79]
	v_mfma_f32_16x16x32_bf16 v[72:75], v[176:179], v[200:203], v[72:75]
	v_mfma_f32_16x16x32_bf16 v[68:71], v[168:171], v[212:215], v[68:71]
	v_mfma_f32_16x16x32_bf16 v[64:67], v[176:179], v[212:215], v[64:67]
	v_mfma_f32_16x16x32_bf16 v[108:111], v[172:175], v[188:191], v[108:111]
	v_mfma_f32_16x16x32_bf16 v[100:103], v[180:183], v[188:191], v[100:103]
	v_mfma_f32_16x16x32_bf16 v[92:95], v[172:175], v[196:199], v[92:95]
	v_mfma_f32_16x16x32_bf16 v[84:87], v[180:183], v[196:199], v[84:87]
	v_mfma_f32_16x16x32_bf16 v[76:79], v[172:175], v[208:211], v[76:79]
	v_mfma_f32_16x16x32_bf16 v[72:75], v[180:183], v[208:211], v[72:75]
	v_mfma_f32_16x16x32_bf16 v[68:71], v[172:175], v[216:219], v[68:71]
	v_mfma_f32_16x16x32_bf16 v[64:67], v[180:183], v[216:219], v[64:67]
	s_setprio 0
	s_barrier
; #define PG8_STAGE(bufoff, gbase, voff) do { _Pragma("unroll") for (int _i = 0; _i < 2; ++_i) \
;         __builtin_amdgcn_global_load_lds((const unsigned*)((const char*)(gbase) + (voff)[_i]), (LAS unsigned*)(lds + (bufoff) + ldsw + _i * 8192), 16, 0, 0); } while (0)
; #define PG8_LDA(dst, b, h) do { _Pragma("unroll") for (int m = 0; m < 4; ++m) _Pragma("unroll") for (int k = 0; k < 2; ++k) dst[m][k] = *(const LAS bf16x8*)(lds + PG8_SA(b, h) + aoff + m * 2048 + k * 1024); } while (0)
; #define PG8_WAIT_V(n) asm volatile("s_waitcnt vmcnt(" #n ")" ::: "memory")
; #define PG8_WAIT_L(n) asm volatile("s_waitcnt lgkmcnt(" #n ")" ::: "memory")
; #define PG8_BAR __builtin_amdgcn_s_barrier()
; #define PG8_SCHED __builtin_amdgcn_sched_barrier(0)
; template <class Epi, class Sched, bool SWAPD = false>
; __device__ __forceinline__ void gemm_phase(LAS unsigned char* lds, const Gemm g, const Sched& S, const Epi& E) {
;     ...
;             PG8_WAIT_V(8); PG8_WAIT_L(0); PG8_BAR; PG8_MMA(0, 0, At, B0); PG8_MMA(0, 1, At, B1); PG8_BAR; PG8_SCHED;
;             PG8_LDA(At, 1, 1); PG8_STAGE(PG8_SB(1, 0), b3, voffB); PG8_STAGE(PG8_SB(1, 1), b3 + hstepB, voffB); PG8_STAGE(PG8_SA(1, 0), a3, voffA);
;             PG8_WAIT_V(8); PG8_WAIT_L(0); PG8_BAR; PG8_MMA(1, 0, At, B0); PG8_MMA(1, 1, At, B1); PG8_BAR; PG8_SCHED;
;         }
	s_add_i32 s50, s82, s21
	v_lshl_add_u64 v[204:205], v[204:205], 0, s[10:11]
	s_mov_b32 m0, s50
	ds_read_b128 v[184:187], v150 offset:49152
	ds_read_b128 v[188:191], v150 offset:50176
	ds_read_b128 v[192:195], v150 offset:51200
	ds_read_b128 v[196:199], v150 offset:52224
	ds_read_b128 v[200:203], v150 offset:53248
	ds_read_b128 v[208:211], v150 offset:54272
	ds_read_b128 v[212:215], v150 offset:55296
	ds_read_b128 v[216:219], v150 offset:56320
	global_load_lds_dwordx4 v[204:205], off
	s_add_i32 m0, s50, 0x2000
	s_add_u32 s50, s54, 0x20080
	v_lshl_add_u64 v[204:205], v[220:221], 0, s[10:11]
	s_addc_u32 s51, s55, 0
	s_add_i32 s54, s83, s21
	global_load_lds_dwordx4 v[204:205], off
	v_lshl_add_u64 v[204:205], s[50:51], 0, v[132:133]
	s_mov_b32 m0, s54
	s_nop 0
	global_load_lds_dwordx4 v[204:205], off
	v_lshl_add_u64 v[204:205], s[50:51], 0, v[128:129]
	s_add_i32 m0, s54, 0x2000
	s_nop 0
	global_load_lds_dwordx4 v[204:205], off
	v_lshl_add_u64 v[204:205], v[222:223], 0, s[10:11]
	s_mov_b32 m0, s60
	s_nop 0
	global_load_lds_dwordx4 v[204:205], off
	v_lshl_add_u64 v[204:205], v[224:225], 0, s[10:11]
	s_mov_b32 m0, s61
	s_nop 0
	global_load_lds_dwordx4 v[204:205], off
	s_waitcnt vmcnt(8)
	s_waitcnt lgkmcnt(0)
	s_barrier
	s_setprio 1
	v_mfma_f32_16x16x32_bf16 v[60:63], v[152:155], v[184:187], v[60:63]
	v_mfma_f32_16x16x32_bf16 v[56:59], v[160:163], v[184:187], v[56:59]
	v_mfma_f32_16x16x32_bf16 v[52:55], v[152:155], v[192:195], v[52:55]
	v_mfma_f32_16x16x32_bf16 v[48:51], v[160:163], v[192:195], v[48:51]
	v_mfma_f32_16x16x32_bf16 v[40:43], v[152:155], v[200:203], v[40:43]
	v_mfma_f32_16x16x32_bf16 v[32:35], v[160:163], v[200:203], v[32:35]
	v_mfma_f32_16x16x32_bf16 v[24:27], v[152:155], v[212:215], v[24:27]
	v_mfma_f32_16x16x32_bf16 v[16:19], v[160:163], v[212:215], v[16:19]
	v_mfma_f32_16x16x32_bf16 v[60:63], v[156:159], v[188:191], v[60:63]
	v_mfma_f32_16x16x32_bf16 v[56:59], v[164:167], v[188:191], v[56:59]
	v_mfma_f32_16x16x32_bf16 v[52:55], v[156:159], v[196:199], v[52:55]
	v_mfma_f32_16x16x32_bf16 v[48:51], v[164:167], v[196:199], v[48:51]
	v_mfma_f32_16x16x32_bf16 v[40:43], v[156:159], v[208:211], v[40:43]
	v_mfma_f32_16x16x32_bf16 v[32:35], v[164:167], v[208:211], v[32:35]
	v_mfma_f32_16x16x32_bf16 v[24:27], v[156:159], v[216:219], v[24:27]
	v_mfma_f32_16x16x32_bf16 v[16:19], v[164:167], v[216:219], v[16:19]
	s_setprio 0
	s_setprio 1
	v_mfma_f32_16x16x32_bf16 v[44:47], v[168:171], v[184:187], v[44:47]
	v_mfma_f32_16x16x32_bf16 v[36:39], v[176:179], v[184:187], v[36:39]
	v_mfma_f32_16x16x32_bf16 v[28:31], v[168:171], v[192:195], v[28:31]
	v_mfma_f32_16x16x32_bf16 v[20:23], v[176:179], v[192:195], v[20:23]
	v_mfma_f32_16x16x32_bf16 v[12:15], v[168:171], v[200:203], v[12:15]
	v_mfma_f32_16x16x32_bf16 v[8:11], v[176:179], v[200:203], v[8:11]
	v_mfma_f32_16x16x32_bf16 v[4:7], v[168:171], v[212:215], v[4:7]
	v_mfma_f32_16x16x32_bf16 v[0:3], v[176:179], v[212:215], v[0:3]
	v_mfma_f32_16x16x32_bf16 v[44:47], v[172:175], v[188:191], v[44:47]
	v_mfma_f32_16x16x32_bf16 v[36:39], v[180:183], v[188:191], v[36:39]
	v_mfma_f32_16x16x32_bf16 v[28:31], v[172:175], v[196:199], v[28:31]
	v_mfma_f32_16x16x32_bf16 v[20:23], v[180:183], v[196:199], v[20:23]
	v_mfma_f32_16x16x32_bf16 v[12:15], v[172:175], v[208:211], v[12:15]
	v_mfma_f32_16x16x32_bf16 v[8:11], v[180:183], v[208:211], v[8:11]
	v_mfma_f32_16x16x32_bf16 v[4:7], v[172:175], v[216:219], v[4:7]
	v_mfma_f32_16x16x32_bf16 v[0:3], v[180:183], v[216:219], v[0:3]
	s_setprio 0
	s_add_i32 s81, s81, 2
	s_add_u32 s79, s79, 0x100
	s_addc_u32 s80, s80, 0
	s_cmp_gt_u32 s81, 5
	s_mov_b64 s[50:51], s[52:53]
	s_barrier
	s_cbranch_scc0 .LBB0_633
	s_and_b64 vcc, exec, s[12:13]
	s_cbranch_vccz .LBB0_636
	s_barrier

; #define PG8_STAGE(bufoff, gbase, voff) do { _Pragma("unroll") for (int _i = 0; _i < 2; ++_i) \
;         __builtin_amdgcn_global_load_lds((const unsigned*)((const char*)(gbase) + (voff)[_i]), (LAS unsigned*)(lds + (bufoff) + ldsw + _i * 8192), 16, 0, 0); } while (0)
; #define PG8_LDA(dst, b, h) do { _Pragma("unroll") for (int m = 0; m < 4; ++m) _Pragma("unroll") for (int k = 0; k < 2; ++k) dst[m][k] = *(const LAS bf16x8*)(lds + PG8_SA(b, h) + aoff + m * 2048 + k * 1024); } while (0)
; #define PG8_LDB(dst, b, h) do { _Pragma("unroll") for (int n = 0; n < 2; ++n) _Pragma("unroll") for (int k = 0; k < 2; ++k) dst[n][k] = *(const LAS bf16x8*)(lds + PG8_SB(b, h) + boff + n * 2048 + k * 1024); } while (0)
; #define PG8_WAIT_V(n) asm volatile("s_waitcnt vmcnt(" #n ")" ::: "memory")
; #define PG8_WAIT_L(n) asm volatile("s_waitcnt lgkmcnt(" #n ")" ::: "memory")
; #define PG8_BAR __builtin_amdgcn_s_barrier()
; #define PG8_SCHED __builtin_amdgcn_sched_barrier(0)
; template <class Epi, class Sched, bool SWAPD = false>
; __device__ __forceinline__ void gemm_phase(LAS unsigned char* lds, const Gemm g, const Sched& S, const Epi& E) {
;     ...
;         for (int t = 0; t < nt; t += 2) {
;             const bool last = (t == nt - 2);
;             const char* a1 = cA + (size_t)(t + 1) * kstepA;
;             const char* a2 = last ? nA : cA + (size_t)(t + 2) * kstepA; const char* b2 = last ? nB : cB + (size_t)(t + 2) * kstep;
;             const char* a3 = a2 + kstepA; const char* b3 = b2 + kstep;
;             PG8_LDB(B0, 0, 0); PG8_LDB(B1, 0, 1); PG8_SCHED; PG8_LDA(At, 0, 0); PG8_STAGE(PG8_SA(1, 1), a1 + hstepA, voffA);
;             PG8_WAIT_V(8); PG8_WAIT_L(0); PG8_BAR; PG8_MMA(0, 0, At, B0); PG8_MMA(0, 1, At, B1); PG8_BAR; PG8_SCHED;
;             PG8_LDA(At, 0, 1); PG8_STAGE(PG8_SB(0, 0), b2, voffB); PG8_STAGE(PG8_SB(0, 1), b2 + hstepB, voffB); PG8_STAGE(PG8_SA(0, 0), a2, voffA);
;             PG8_WAIT_V(8); PG8_WAIT_L(0); PG8_BAR; PG8_MMA(1, 0, At, B0); PG8_MMA(1, 1, At, B1); PG8_BAR; PG8_SCHED;
.LBB0_766:
	ds_read_b128 v[150:153], v146
	ds_read_b128 v[154:157], v146 offset:1024
	ds_read_b128 v[158:161], v146 offset:2048
	ds_read_b128 v[162:165], v146 offset:3072
	ds_read_b128 v[166:169], v147
	ds_read_b128 v[170:173], v147 offset:1024
	ds_read_b128 v[174:177], v147 offset:2048
	ds_read_b128 v[178:181], v147 offset:3072
	s_add_u32 s42, s40, 0x100
	s_addc_u32 s43, s41, 0
	s_cmp_eq_u32 s67, 8
	s_cselect_b32 s47, s61, s43
	s_cselect_b32 s46, s62, s42
	s_cselect_b32 s45, s63, s66
	s_cselect_b32 s44, s64, s65
	v_lshl_add_u64 v[142:143], s[40:41], 0, v[134:135]
	s_add_i32 m0, s33, 0xc000
	ds_read_b128 v[182:185], v148
	ds_read_b128 v[186:189], v148 offset:1024
	ds_read_b128 v[190:193], v148 offset:2048
	ds_read_b128 v[194:197], v148 offset:3072
	ds_read_b128 v[198:201], v148 offset:4096
	ds_read_b128 v[202:205], v148 offset:5120
	ds_read_b128 v[208:211], v148 offset:6144
	ds_read_b128 v[212:215], v148 offset:7168
	global_load_lds_dwordx4 v[142:143], off
	v_lshl_add_u64 v[142:143], s[40:41], 0, v[136:137]
	s_add_i32 m0, s33, 0xe000
	s_nop 0
	global_load_lds_dwordx4 v[142:143], off
	s_waitcnt vmcnt(8)
	s_waitcnt lgkmcnt(0)
	s_barrier
	s_setprio 1
	v_mfma_f32_16x16x32_bf16 v[124:127], v[150:153], v[182:185], v[124:127]
	v_mfma_f32_16x16x32_bf16 v[120:123], v[158:161], v[182:185], v[120:123]
	v_mfma_f32_16x16x32_bf16 v[108:111], v[150:153], v[190:193], v[108:111]
	v_mfma_f32_16x16x32_bf16 v[104:107], v[158:161], v[190:193], v[104:107]
	v_mfma_f32_16x16x32_bf16 v[92:95], v[150:153], v[198:201], v[92:95]
	v_mfma_f32_16x16x32_bf16 v[88:91], v[158:161], v[198:201], v[88:91]
	v_mfma_f32_16x16x32_bf16 v[76:79], v[150:153], v[208:211], v[76:79]
	v_mfma_f32_16x16x32_bf16 v[72:75], v[158:161], v[208:211], v[72:75]
	v_mfma_f32_16x16x32_bf16 v[124:127], v[154:157], v[186:189], v[124:127]
	v_mfma_f32_16x16x32_bf16 v[120:123], v[162:165], v[186:189], v[120:123]
	v_mfma_f32_16x16x32_bf16 v[108:111], v[154:157], v[194:197], v[108:111]
	v_mfma_f32_16x16x32_bf16 v[104:107], v[162:165], v[194:197], v[104:107]
	v_mfma_f32_16x16x32_bf16 v[92:95], v[154:157], v[202:205], v[92:95]
	v_mfma_f32_16x16x32_bf16 v[88:91], v[162:165], v[202:205], v[88:91]
	v_mfma_f32_16x16x32_bf16 v[76:79], v[154:157], v[212:215], v[76:79]
	v_mfma_f32_16x16x32_bf16 v[72:75], v[162:165], v[212:215], v[72:75]
	s_setprio 0
	s_setprio 1
	v_mfma_f32_16x16x32_bf16 v[116:119], v[166:169], v[182:185], v[116:119]
	v_mfma_f32_16x16x32_bf16 v[112:115], v[174:177], v[182:185], v[112:115]
	v_mfma_f32_16x16x32_bf16 v[100:103], v[166:169], v[190:193], v[100:103]
	v_mfma_f32_16x16x32_bf16 v[96:99], v[174:177], v[190:193], v[96:99]
	v_mfma_f32_16x16x32_bf16 v[84:87], v[166:169], v[198:201], v[84:87]
	v_mfma_f32_16x16x32_bf16 v[80:83], v[174:177], v[198:201], v[80:83]
	v_mfma_f32_16x16x32_bf16 v[68:71], v[166:169], v[208:211], v[68:71]
	v_mfma_f32_16x16x32_bf16 v[64:67], v[174:177], v[208:211], v[64:67]
	v_mfma_f32_16x16x32_bf16 v[116:119], v[170:173], v[186:189], v[116:119]
	v_mfma_f32_16x16x32_bf16 v[112:115], v[178:181], v[186:189], v[112:115]
	v_mfma_f32_16x16x32_bf16 v[100:103], v[170:173], v[194:197], v[100:103]
	v_mfma_f32_16x16x32_bf16 v[96:99], v[178:181], v[194:197], v[96:99]
	v_mfma_f32_16x16x32_bf16 v[84:87], v[170:173], v[202:205], v[84:87]
	v_mfma_f32_16x16x32_bf16 v[80:83], v[178:181], v[202:205], v[80:83]
	v_mfma_f32_16x16x32_bf16 v[68:71], v[170:173], v[212:215], v[68:71]
	v_mfma_f32_16x16x32_bf16 v[64:67], v[178:181], v[212:215], v[64:67]
	s_setprio 0
	s_barrier
	s_add_i32 s40, s57, s21
	v_lshl_add_u64 v[142:143], s[44:45], 0, v[130:131]
	s_mov_b32 m0, s40
	ds_read_b128 v[182:185], v148 offset:16384
	ds_read_b128 v[186:189], v148 offset:17408
	ds_read_b128 v[190:193], v148 offset:18432
	ds_read_b128 v[194:197], v148 offset:19456
	ds_read_b128 v[198:201], v148 offset:20480
	ds_read_b128 v[202:205], v148 offset:21504
	ds_read_b128 v[208:211], v148 offset:22528
	ds_read_b128 v[212:215], v148 offset:23552
	global_load_lds_dwordx4 v[142:143], off
	s_add_i32 m0, s40, 0x2000
	s_add_u32 s40, s44, 0x30000
	v_lshl_add_u64 v[216:217], s[44:45], 0, v[128:129]
	s_addc_u32 s41, s45, 0
	s_add_i32 s68, s58, s21
	global_load_lds_dwordx4 v[216:217], off
	v_lshl_add_u64 v[218:219], s[40:41], 0, v[130:131]
	s_mov_b32 m0, s68
	v_lshl_add_u64 v[220:221], s[46:47], 0, v[128:129]
	global_load_lds_dwordx4 v[218:219], off
	v_lshl_add_u64 v[218:219], s[40:41], 0, v[128:129]
	s_add_i32 m0, s68, 0x2000
	s_nop 0
	global_load_lds_dwordx4 v[218:219], off
	v_lshl_add_u64 v[218:219], s[46:47], 0, v[130:131]
	s_mov_b32 m0, s33
	s_nop 0
	global_load_lds_dwordx4 v[218:219], off
	s_mov_b32 m0, s50
	s_nop 0
	global_load_lds_dwordx4 v[220:221], off
	s_waitcnt vmcnt(8)
	s_waitcnt lgkmcnt(0)
	s_barrier
; #define PG8_STAGE(bufoff, gbase, voff) do { _Pragma("unroll") for (int _i = 0; _i < 2; ++_i) \
;         __builtin_amdgcn_global_load_lds((const unsigned*)((const char*)(gbase) + (voff)[_i]), (LAS unsigned*)(lds + (bufoff) + ldsw + _i * 8192), 16, 0, 0); } while (0)
; #define PG8_LDA(dst, b, h) do { _Pragma("unroll") for (int m = 0; m < 4; ++m) _Pragma("unroll") for (int k = 0; k < 2; ++k) dst[m][k] = *(const LAS bf16x8*)(lds + PG8_SA(b, h) + aoff + m * 2048 + k * 1024); } while (0)
; #define PG8_LDB(dst, b, h) do { _Pragma("unroll") for (int n = 0; n < 2; ++n) _Pragma("unroll") for (int k = 0; k < 2; ++k) dst[n][k] = *(const LAS bf16x8*)(lds + PG8_SB(b, h) + boff + n * 2048 + k * 1024); } while (0)
; #define PG8_WAIT_V(n) asm volatile("s_waitcnt vmcnt(" #n ")" ::: "memory")
; #define PG8_WAIT_L(n) asm volatile("s_waitcnt lgkmcnt(" #n ")" ::: "memory")
; #define PG8_BAR __builtin_amdgcn_s_barrier()
; #define PG8_SCHED __builtin_amdgcn_sched_barrier(0)
; template <class Epi, class Sched, bool SWAPD = false>
; __device__ __forceinline__ void gemm_phase(LAS unsigned char* lds, const Gemm g, const Sched& S, const Epi& E) {
;     ...
;             PG8_WAIT_V(8); PG8_WAIT_L(0); PG8_BAR; PG8_MMA(1, 0, At, B0); PG8_MMA(1, 1, At, B1); PG8_BAR; PG8_SCHED;
;             PG8_LDB(B0, 1, 0); PG8_LDB(B1, 1, 1); PG8_SCHED; PG8_LDA(At, 1, 0); PG8_STAGE(PG8_SA(0, 1), a2 + hstepA, voffA);
;             PG8_WAIT_V(8); PG8_WAIT_L(0); PG8_BAR; PG8_MMA(0, 0, At, B0); PG8_MMA(0, 1, At, B1); PG8_BAR; PG8_SCHED;
;             PG8_LDA(At, 1, 1); PG8_STAGE(PG8_SB(1, 0), b3, voffB); PG8_STAGE(PG8_SB(1, 1), b3 + hstepB, voffB); PG8_STAGE(PG8_SA(1, 0), a3, voffA);
	s_setprio 1
	v_mfma_f32_16x16x32_bf16 v[60:63], v[150:153], v[182:185], v[60:63]
	v_mfma_f32_16x16x32_bf16 v[56:59], v[158:161], v[182:185], v[56:59]
	v_mfma_f32_16x16x32_bf16 v[44:47], v[150:153], v[190:193], v[44:47]
	v_mfma_f32_16x16x32_bf16 v[40:43], v[158:161], v[190:193], v[40:43]
	v_mfma_f32_16x16x32_bf16 v[28:31], v[150:153], v[198:201], v[28:31]
	v_mfma_f32_16x16x32_bf16 v[24:27], v[158:161], v[198:201], v[24:27]
	v_mfma_f32_16x16x32_bf16 v[12:15], v[150:153], v[208:211], v[12:15]
	v_mfma_f32_16x16x32_bf16 v[8:11], v[158:161], v[208:211], v[8:11]
	v_mfma_f32_16x16x32_bf16 v[60:63], v[154:157], v[186:189], v[60:63]
	v_mfma_f32_16x16x32_bf16 v[56:59], v[162:165], v[186:189], v[56:59]
	v_mfma_f32_16x16x32_bf16 v[44:47], v[154:157], v[194:197], v[44:47]
	v_mfma_f32_16x16x32_bf16 v[40:43], v[162:165], v[194:197], v[40:43]
	v_mfma_f32_16x16x32_bf16 v[28:31], v[154:157], v[202:205], v[28:31]
	v_mfma_f32_16x16x32_bf16 v[24:27], v[162:165], v[202:205], v[24:27]
	v_mfma_f32_16x16x32_bf16 v[12:15], v[154:157], v[212:215], v[12:15]
	v_mfma_f32_16x16x32_bf16 v[8:11], v[162:165], v[212:215], v[8:11]
	s_setprio 0
	s_setprio 1
	v_mfma_f32_16x16x32_bf16 v[52:55], v[166:169], v[182:185], v[52:55]
	v_mfma_f32_16x16x32_bf16 v[48:51], v[174:177], v[182:185], v[48:51]
	v_mfma_f32_16x16x32_bf16 v[36:39], v[166:169], v[190:193], v[36:39]
	v_mfma_f32_16x16x32_bf16 v[32:35], v[174:177], v[190:193], v[32:35]
	v_mfma_f32_16x16x32_bf16 v[20:23], v[166:169], v[198:201], v[20:23]
	v_mfma_f32_16x16x32_bf16 v[16:19], v[174:177], v[198:201], v[16:19]
	v_mfma_f32_16x16x32_bf16 v[4:7], v[166:169], v[208:211], v[4:7]
	v_mfma_f32_16x16x32_bf16 v[0:3], v[174:177], v[208:211], v[0:3]
	v_mfma_f32_16x16x32_bf16 v[52:55], v[170:173], v[186:189], v[52:55]
	v_mfma_f32_16x16x32_bf16 v[48:51], v[178:181], v[186:189], v[48:51]
	v_mfma_f32_16x16x32_bf16 v[36:39], v[170:173], v[194:197], v[36:39]
	v_mfma_f32_16x16x32_bf16 v[32:35], v[178:181], v[194:197], v[32:35]
	v_mfma_f32_16x16x32_bf16 v[20:23], v[170:173], v[202:205], v[20:23]
	v_mfma_f32_16x16x32_bf16 v[16:19], v[178:181], v[202:205], v[16:19]
	v_mfma_f32_16x16x32_bf16 v[4:7], v[170:173], v[212:215], v[4:7]
	v_mfma_f32_16x16x32_bf16 v[0:3], v[178:181], v[212:215], v[0:3]
	s_setprio 0
	s_barrier
	s_add_i32 s68, 0, 0x18000
	v_add_u32_e32 v149, s68, v144
	s_add_i32 s69, 0, 0x1c000
	ds_read_b128 v[150:153], v149
	ds_read_b128 v[154:157], v149 offset:1024
	ds_read_b128 v[158:161], v149 offset:2048
	ds_read_b128 v[162:165], v149 offset:3072
	v_add_u32_e32 v149, s69, v144
	ds_read_b128 v[166:169], v149
	ds_read_b128 v[170:173], v149 offset:1024
	ds_read_b128 v[174:177], v149 offset:2048
	ds_read_b128 v[178:181], v149 offset:3072
	s_add_u32 s40, s46, 0x30000
	s_addc_u32 s41, s47, 0
	s_mov_b32 m0, s51
	v_lshl_add_u64 v[222:223], s[40:41], 0, v[130:131]
	ds_read_b128 v[182:185], v148 offset:32768
	ds_read_b128 v[186:189], v148 offset:33792
	ds_read_b128 v[190:193], v148 offset:34816
	ds_read_b128 v[194:197], v148 offset:35840
	ds_read_b128 v[198:201], v148 offset:36864
	ds_read_b128 v[202:205], v148 offset:37888
	ds_read_b128 v[208:211], v148 offset:38912
	ds_read_b128 v[212:215], v148 offset:39936
	global_load_lds_dwordx4 v[222:223], off
	v_lshl_add_u64 v[222:223], s[40:41], 0, v[128:129]
	s_mov_b32 m0, s52
	s_nop 0
	global_load_lds_dwordx4 v[222:223], off
	s_waitcnt vmcnt(8)
	s_waitcnt lgkmcnt(0)
	s_barrier
	s_setprio 1
	v_mfma_f32_16x16x32_bf16 v[124:127], v[150:153], v[182:185], v[124:127]
	v_mfma_f32_16x16x32_bf16 v[120:123], v[158:161], v[182:185], v[120:123]
	v_mfma_f32_16x16x32_bf16 v[108:111], v[150:153], v[190:193], v[108:111]
	v_mfma_f32_16x16x32_bf16 v[104:107], v[158:161], v[190:193], v[104:107]
	v_mfma_f32_16x16x32_bf16 v[92:95], v[150:153], v[198:201], v[92:95]
	v_mfma_f32_16x16x32_bf16 v[88:91], v[158:161], v[198:201], v[88:91]
	v_mfma_f32_16x16x32_bf16 v[76:79], v[150:153], v[208:211], v[76:79]
	v_mfma_f32_16x16x32_bf16 v[72:75], v[158:161], v[208:211], v[72:75]
	v_mfma_f32_16x16x32_bf16 v[124:127], v[154:157], v[186:189], v[124:127]
	v_mfma_f32_16x16x32_bf16 v[120:123], v[162:165], v[186:189], v[120:123]
	v_mfma_f32_16x16x32_bf16 v[108:111], v[154:157], v[194:197], v[108:111]
	v_mfma_f32_16x16x32_bf16 v[104:107], v[162:165], v[194:197], v[104:107]
	v_mfma_f32_16x16x32_bf16 v[92:95], v[154:157], v[202:205], v[92:95]
	v_mfma_f32_16x16x32_bf16 v[88:91], v[162:165], v[202:205], v[88:91]
	v_mfma_f32_16x16x32_bf16 v[76:79], v[154:157], v[212:215], v[76:79]
	v_mfma_f32_16x16x32_bf16 v[72:75], v[162:165], v[212:215], v[72:75]
	s_setprio 0
	s_setprio 1
	v_mfma_f32_16x16x32_bf16 v[116:119], v[166:169], v[182:185], v[116:119]
	v_mfma_f32_16x16x32_bf16 v[112:115], v[174:177], v[182:185], v[112:115]
	v_mfma_f32_16x16x32_bf16 v[100:103], v[166:169], v[190:193], v[100:103]
	v_mfma_f32_16x16x32_bf16 v[96:99], v[174:177], v[190:193], v[96:99]
	v_mfma_f32_16x16x32_bf16 v[84:87], v[166:169], v[198:201], v[84:87]
	v_mfma_f32_16x16x32_bf16 v[80:83], v[174:177], v[198:201], v[80:83]
	v_mfma_f32_16x16x32_bf16 v[68:71], v[166:169], v[208:211], v[68:71]
	v_mfma_f32_16x16x32_bf16 v[64:67], v[174:177], v[208:211], v[64:67]
	v_mfma_f32_16x16x32_bf16 v[116:119], v[170:173], v[186:189], v[116:119]
	v_mfma_f32_16x16x32_bf16 v[112:115], v[178:181], v[186:189], v[112:115]
	v_mfma_f32_16x16x32_bf16 v[100:103], v[170:173], v[194:197], v[100:103]
	v_mfma_f32_16x16x32_bf16 v[96:99], v[178:181], v[194:197], v[96:99]
	v_mfma_f32_16x16x32_bf16 v[84:87], v[170:173], v[202:205], v[84:87]
	v_mfma_f32_16x16x32_bf16 v[80:83], v[178:181], v[202:205], v[80:83]
	v_mfma_f32_16x16x32_bf16 v[68:71], v[170:173], v[212:215], v[68:71]
	v_mfma_f32_16x16x32_bf16 v[64:67], v[178:181], v[212:215], v[64:67]
	s_setprio 0
	s_barrier
; #define PG8_STAGE(bufoff, gbase, voff) do { _Pragma("unroll") for (int _i = 0; _i < 2; ++_i) \
;         __builtin_amdgcn_global_load_lds((const unsigned*)((const char*)(gbase) + (voff)[_i]), (LAS unsigned*)(lds + (bufoff) + ldsw + _i * 8192), 16, 0, 0); } while (0)
; #define PG8_LDA(dst, b, h) do { _Pragma("unroll") for (int m = 0; m < 4; ++m) _Pragma("unroll") for (int k = 0; k < 2; ++k) dst[m][k] = *(const LAS bf16x8*)(lds + PG8_SA(b, h) + aoff + m * 2048 + k * 1024); } while (0)
; #define PG8_WAIT_V(n) asm volatile("s_waitcnt vmcnt(" #n ")" ::: "memory")
; #define PG8_WAIT_L(n) asm volatile("s_waitcnt lgkmcnt(" #n ")" ::: "memory")
; #define PG8_BAR __builtin_amdgcn_s_barrier()
; #define PG8_SCHED __builtin_amdgcn_sched_barrier(0)
; template <class Epi, class Sched, bool SWAPD = false>
; __device__ __forceinline__ void gemm_phase(LAS unsigned char* lds, const Gemm g, const Sched& S, const Epi& E) {
;     ...
;             PG8_WAIT_V(8); PG8_WAIT_L(0); PG8_BAR; PG8_MMA(0, 0, At, B0); PG8_MMA(0, 1, At, B1); PG8_BAR; PG8_SCHED;
;             PG8_LDA(At, 1, 1); PG8_STAGE(PG8_SB(1, 0), b3, voffB); PG8_STAGE(PG8_SB(1, 1), b3 + hstepB, voffB); PG8_STAGE(PG8_SA(1, 0), a3, voffA);
;             PG8_WAIT_V(8); PG8_WAIT_L(0); PG8_BAR; PG8_MMA(1, 0, At, B0); PG8_MMA(1, 1, At, B1); PG8_BAR; PG8_SCHED;
;         }
	s_add_i32 s40, s68, s21
	v_lshl_add_u64 v[142:143], v[142:143], 0, s[12:13]
	s_mov_b32 m0, s40
	ds_read_b128 v[182:185], v148 offset:49152
	ds_read_b128 v[186:189], v148 offset:50176
	ds_read_b128 v[190:193], v148 offset:51200
	ds_read_b128 v[194:197], v148 offset:52224
	ds_read_b128 v[198:201], v148 offset:53248
	ds_read_b128 v[202:205], v148 offset:54272
	ds_read_b128 v[208:211], v148 offset:55296
	ds_read_b128 v[212:215], v148 offset:56320
	global_load_lds_dwordx4 v[142:143], off
	s_add_i32 m0, s40, 0x2000
	s_add_u32 s40, s44, 0x30080
	v_lshl_add_u64 v[142:143], v[216:217], 0, s[12:13]
	s_addc_u32 s41, s45, 0
	s_add_i32 s44, s69, s21
	global_load_lds_dwordx4 v[142:143], off
	v_lshl_add_u64 v[142:143], s[40:41], 0, v[130:131]
	s_mov_b32 m0, s44
	s_nop 0
	global_load_lds_dwordx4 v[142:143], off
	v_lshl_add_u64 v[142:143], s[40:41], 0, v[128:129]
	s_add_i32 m0, s44, 0x2000
	s_nop 0
	global_load_lds_dwordx4 v[142:143], off
	v_lshl_add_u64 v[142:143], v[218:219], 0, s[12:13]
	s_mov_b32 m0, s54
	s_nop 0
	global_load_lds_dwordx4 v[142:143], off
	v_lshl_add_u64 v[142:143], v[220:221], 0, s[12:13]
	s_mov_b32 m0, s55
	s_nop 0
	global_load_lds_dwordx4 v[142:143], off
	s_waitcnt vmcnt(8)
	s_waitcnt lgkmcnt(0)
	s_barrier
	s_setprio 1
	v_mfma_f32_16x16x32_bf16 v[60:63], v[150:153], v[182:185], v[60:63]
	v_mfma_f32_16x16x32_bf16 v[56:59], v[158:161], v[182:185], v[56:59]
	v_mfma_f32_16x16x32_bf16 v[44:47], v[150:153], v[190:193], v[44:47]
	v_mfma_f32_16x16x32_bf16 v[40:43], v[158:161], v[190:193], v[40:43]
	v_mfma_f32_16x16x32_bf16 v[28:31], v[150:153], v[198:201], v[28:31]
	v_mfma_f32_16x16x32_bf16 v[24:27], v[158:161], v[198:201], v[24:27]
	v_mfma_f32_16x16x32_bf16 v[12:15], v[150:153], v[208:211], v[12:15]
	v_mfma_f32_16x16x32_bf16 v[8:11], v[158:161], v[208:211], v[8:11]
	v_mfma_f32_16x16x32_bf16 v[60:63], v[154:157], v[186:189], v[60:63]
	v_mfma_f32_16x16x32_bf16 v[56:59], v[162:165], v[186:189], v[56:59]
	v_mfma_f32_16x16x32_bf16 v[44:47], v[154:157], v[194:197], v[44:47]
	v_mfma_f32_16x16x32_bf16 v[40:43], v[162:165], v[194:197], v[40:43]
	v_mfma_f32_16x16x32_bf16 v[28:31], v[154:157], v[202:205], v[28:31]
	v_mfma_f32_16x16x32_bf16 v[24:27], v[162:165], v[202:205], v[24:27]
	v_mfma_f32_16x16x32_bf16 v[12:15], v[154:157], v[212:215], v[12:15]
	v_mfma_f32_16x16x32_bf16 v[8:11], v[162:165], v[212:215], v[8:11]
	s_setprio 0
	s_setprio 1
	v_mfma_f32_16x16x32_bf16 v[52:55], v[166:169], v[182:185], v[52:55]
	v_mfma_f32_16x16x32_bf16 v[48:51], v[174:177], v[182:185], v[48:51]
	v_mfma_f32_16x16x32_bf16 v[36:39], v[166:169], v[190:193], v[36:39]
	v_mfma_f32_16x16x32_bf16 v[32:35], v[174:177], v[190:193], v[32:35]
	v_mfma_f32_16x16x32_bf16 v[20:23], v[166:169], v[198:201], v[20:23]
	v_mfma_f32_16x16x32_bf16 v[16:19], v[174:177], v[198:201], v[16:19]
	v_mfma_f32_16x16x32_bf16 v[4:7], v[166:169], v[208:211], v[4:7]
	v_mfma_f32_16x16x32_bf16 v[0:3], v[174:177], v[208:211], v[0:3]
	v_mfma_f32_16x16x32_bf16 v[52:55], v[170:173], v[186:189], v[52:55]
	v_mfma_f32_16x16x32_bf16 v[48:51], v[178:181], v[186:189], v[48:51]
	v_mfma_f32_16x16x32_bf16 v[36:39], v[170:173], v[194:197], v[36:39]
	v_mfma_f32_16x16x32_bf16 v[32:35], v[178:181], v[194:197], v[32:35]
	v_mfma_f32_16x16x32_bf16 v[20:23], v[170:173], v[202:205], v[20:23]
	v_mfma_f32_16x16x32_bf16 v[16:19], v[178:181], v[202:205], v[16:19]
	v_mfma_f32_16x16x32_bf16 v[4:7], v[170:173], v[212:215], v[4:7]
	v_mfma_f32_16x16x32_bf16 v[0:3], v[178:181], v[212:215], v[0:3]
	s_setprio 0
	s_add_i32 s67, s67, 2
	s_add_u32 s65, s65, 0x100
	s_addc_u32 s66, s66, 0
	s_cmp_gt_u32 s67, 9
	s_mov_b64 s[40:41], s[42:43]
	s_barrier
	s_cbranch_scc0 .LBB0_766
	s_and_b64 vcc, exec, s[24:25]
	s_cbranch_vccz .LBB0_769
	s_barrier

; #define PG8_STAGE(bufoff, gbase, voff) do { _Pragma("unroll") for (int _i = 0; _i < 2; ++_i) \
;         __builtin_amdgcn_global_load_lds((const unsigned*)((const char*)(gbase) + (voff)[_i]), (LAS unsigned*)(lds + (bufoff) + ldsw + _i * 8192), 16, 0, 0); } while (0)
; #define PG8_LDA(dst, b, h) do { _Pragma("unroll") for (int m = 0; m < 4; ++m) _Pragma("unroll") for (int k = 0; k < 2; ++k) dst[m][k] = *(const LAS bf16x8*)(lds + PG8_SA(b, h) + aoff + m * 2048 + k * 1024); } while (0)
; #define PG8_LDB(dst, b, h) do { _Pragma("unroll") for (int n = 0; n < 2; ++n) _Pragma("unroll") for (int k = 0; k < 2; ++k) dst[n][k] = *(const LAS bf16x8*)(lds + PG8_SB(b, h) + boff + n * 2048 + k * 1024); } while (0)
; #define PG8_WAIT_V(n) asm volatile("s_waitcnt vmcnt(" #n ")" ::: "memory")
; #define PG8_WAIT_L(n) asm volatile("s_waitcnt lgkmcnt(" #n ")" ::: "memory")
; #define PG8_BAR __builtin_amdgcn_s_barrier()
; #define PG8_SCHED __builtin_amdgcn_sched_barrier(0)
; template <class Epi, class Sched, bool SWAPD = false>
; __device__ __forceinline__ void gemm_phase(LAS unsigned char* lds, const Gemm g, const Sched& S, const Epi& E) {
;     ...
;         for (int t = 0; t < nt; t += 2) {
;             const bool last = (t == nt - 2);
;             const char* a1 = cA + (size_t)(t + 1) * kstepA;
;             const char* a2 = last ? nA : cA + (size_t)(t + 2) * kstepA; const char* b2 = last ? nB : cB + (size_t)(t + 2) * kstep;
;             const char* a3 = a2 + kstepA; const char* b3 = b2 + kstep;
;             PG8_LDB(B0, 0, 0); PG8_LDB(B1, 0, 1); PG8_SCHED; PG8_LDA(At, 0, 0); PG8_STAGE(PG8_SA(1, 1), a1 + hstepA, voffA);
;             PG8_WAIT_V(8); PG8_WAIT_L(0); PG8_BAR; PG8_MMA(0, 0, At, B0); PG8_MMA(0, 1, At, B1); PG8_BAR; PG8_SCHED;
;             PG8_LDA(At, 0, 1); PG8_STAGE(PG8_SB(0, 0), b2, voffB); PG8_STAGE(PG8_SB(0, 1), b2 + hstepB, voffB); PG8_STAGE(PG8_SA(0, 0), a2, voffA);
;             PG8_WAIT_V(8); PG8_WAIT_L(0); PG8_BAR; PG8_MMA(1, 0, At, B0); PG8_MMA(1, 1, At, B1); PG8_BAR; PG8_SCHED;
.LBB0_842:
	ds_read_b128 v[146:149], v153
	ds_read_b128 v[156:159], v153 offset:1024
	ds_read_b128 v[160:163], v153 offset:2048
	ds_read_b128 v[164:167], v153 offset:3072
	ds_read_b128 v[168:171], v154
	ds_read_b128 v[172:175], v154 offset:1024
	ds_read_b128 v[176:179], v154 offset:2048
	ds_read_b128 v[180:183], v154 offset:3072
	s_add_u32 s44, s42, 0x800000
	s_addc_u32 s45, s43, 0
	s_cmp_eq_u32 s62, 4
	s_cselect_b32 s52, s25, s44
	s_cselect_b32 s53, s23, s45
	s_cselect_b32 s50, s59, s60
	s_cselect_b32 s51, s35, s61
	s_add_u32 s46, s52, 0x400000
	s_addc_u32 s47, s53, 0
	v_lshl_add_u64 v[204:205], s[42:43], 0, v[138:139]
	s_add_i32 m0, s30, 0xc000
	ds_read_b128 v[184:187], v155
	ds_read_b128 v[188:191], v155 offset:1024
	ds_read_b128 v[192:195], v155 offset:2048
	ds_read_b128 v[196:199], v155 offset:3072
	ds_read_b128 v[200:203], v155 offset:4096
	ds_read_b128 v[208:211], v155 offset:5120
	ds_read_b128 v[212:215], v155 offset:6144
	ds_read_b128 v[216:219], v155 offset:7168
	global_load_lds_dwordx4 v[204:205], off
	v_lshl_add_u64 v[204:205], s[42:43], 0, v[140:141]
	s_add_i32 m0, s30, 0xe000
	s_nop 0
	global_load_lds_dwordx4 v[204:205], off
	s_waitcnt vmcnt(8)
	s_waitcnt lgkmcnt(0)
	s_barrier
	s_setprio 1
	v_mfma_f32_16x16x32_bf16 v[124:127], v[146:149], v[184:187], v[124:127]
	v_mfma_f32_16x16x32_bf16 v[120:123], v[160:163], v[184:187], v[120:123]
	v_mfma_f32_16x16x32_bf16 v[108:111], v[146:149], v[192:195], v[108:111]
	v_mfma_f32_16x16x32_bf16 v[104:107], v[160:163], v[192:195], v[104:107]
	v_mfma_f32_16x16x32_bf16 v[92:95], v[146:149], v[200:203], v[92:95]
	v_mfma_f32_16x16x32_bf16 v[88:91], v[160:163], v[200:203], v[88:91]
	v_mfma_f32_16x16x32_bf16 v[76:79], v[146:149], v[212:215], v[76:79]
	v_mfma_f32_16x16x32_bf16 v[72:75], v[160:163], v[212:215], v[72:75]
	v_mfma_f32_16x16x32_bf16 v[124:127], v[156:159], v[188:191], v[124:127]
	v_mfma_f32_16x16x32_bf16 v[120:123], v[164:167], v[188:191], v[120:123]
	v_mfma_f32_16x16x32_bf16 v[108:111], v[156:159], v[196:199], v[108:111]
	v_mfma_f32_16x16x32_bf16 v[104:107], v[164:167], v[196:199], v[104:107]
	v_mfma_f32_16x16x32_bf16 v[92:95], v[156:159], v[208:211], v[92:95]
	v_mfma_f32_16x16x32_bf16 v[88:91], v[164:167], v[208:211], v[88:91]
	v_mfma_f32_16x16x32_bf16 v[76:79], v[156:159], v[216:219], v[76:79]
	v_mfma_f32_16x16x32_bf16 v[72:75], v[164:167], v[216:219], v[72:75]
	s_setprio 0
	s_setprio 1
	v_mfma_f32_16x16x32_bf16 v[116:119], v[168:171], v[184:187], v[116:119]
	v_mfma_f32_16x16x32_bf16 v[112:115], v[176:179], v[184:187], v[112:115]
	v_mfma_f32_16x16x32_bf16 v[100:103], v[168:171], v[192:195], v[100:103]
	v_mfma_f32_16x16x32_bf16 v[96:99], v[176:179], v[192:195], v[96:99]
	v_mfma_f32_16x16x32_bf16 v[84:87], v[168:171], v[200:203], v[84:87]
	v_mfma_f32_16x16x32_bf16 v[80:83], v[176:179], v[200:203], v[80:83]
	v_mfma_f32_16x16x32_bf16 v[68:71], v[168:171], v[212:215], v[68:71]
	v_mfma_f32_16x16x32_bf16 v[64:67], v[176:179], v[212:215], v[64:67]
	v_mfma_f32_16x16x32_bf16 v[116:119], v[172:175], v[188:191], v[116:119]
	v_mfma_f32_16x16x32_bf16 v[112:115], v[180:183], v[188:191], v[112:115]
	v_mfma_f32_16x16x32_bf16 v[100:103], v[172:175], v[196:199], v[100:103]
	v_mfma_f32_16x16x32_bf16 v[96:99], v[180:183], v[196:199], v[96:99]
	v_mfma_f32_16x16x32_bf16 v[84:87], v[172:175], v[208:211], v[84:87]
	v_mfma_f32_16x16x32_bf16 v[80:83], v[180:183], v[208:211], v[80:83]
	v_mfma_f32_16x16x32_bf16 v[68:71], v[172:175], v[216:219], v[68:71]
	v_mfma_f32_16x16x32_bf16 v[64:67], v[180:183], v[216:219], v[64:67]
	s_setprio 0
	s_barrier
	s_add_i32 s42, s57, s21
	v_lshl_add_u64 v[204:205], s[50:51], 0, v[130:131]
	s_mov_b32 m0, s42
	ds_read_b128 v[184:187], v155 offset:16384
	ds_read_b128 v[188:191], v155 offset:17408
	ds_read_b128 v[192:195], v155 offset:18432
	ds_read_b128 v[196:199], v155 offset:19456
	ds_read_b128 v[200:203], v155 offset:20480
	ds_read_b128 v[208:211], v155 offset:21504
	ds_read_b128 v[212:215], v155 offset:22528
	ds_read_b128 v[216:219], v155 offset:23552
	global_load_lds_dwordx4 v[204:205], off
	s_add_i32 m0, s42, 0x2000
	s_add_u32 s42, s50, 0x20000
	v_lshl_add_u64 v[220:221], s[50:51], 0, v[134:135]
	s_addc_u32 s43, s51, 0
	s_add_i32 s63, s58, s21
	global_load_lds_dwordx4 v[220:221], off
	v_lshl_add_u64 v[222:223], s[42:43], 0, v[130:131]
	s_mov_b32 m0, s63
	s_nop 0
	global_load_lds_dwordx4 v[222:223], off
	v_lshl_add_u64 v[222:223], s[42:43], 0, v[134:135]
	s_add_i32 m0, s63, 0x2000
	s_nop 0
	global_load_lds_dwordx4 v[222:223], off
	v_lshl_add_u64 v[222:223], s[52:53], 0, v[128:129]
	s_mov_b32 m0, s30
	s_nop 0
	global_load_lds_dwordx4 v[222:223], off
	v_lshl_add_u64 v[222:223], s[52:53], 0, v[132:133]
	s_mov_b32 m0, s31
	s_nop 0
	global_load_lds_dwordx4 v[222:223], off
	s_waitcnt vmcnt(8)
	s_waitcnt lgkmcnt(0)
	s_barrier
; #define PG8_STAGE(bufoff, gbase, voff) do { _Pragma("unroll") for (int _i = 0; _i < 2; ++_i) \
;         __builtin_amdgcn_global_load_lds((const unsigned*)((const char*)(gbase) + (voff)[_i]), (LAS unsigned*)(lds + (bufoff) + ldsw + _i * 8192), 16, 0, 0); } while (0)
; #define PG8_LDA(dst, b, h) do { _Pragma("unroll") for (int m = 0; m < 4; ++m) _Pragma("unroll") for (int k = 0; k < 2; ++k) dst[m][k] = *(const LAS bf16x8*)(lds + PG8_SA(b, h) + aoff + m * 2048 + k * 1024); } while (0)
; #define PG8_LDB(dst, b, h) do { _Pragma("unroll") for (int n = 0; n < 2; ++n) _Pragma("unroll") for (int k = 0; k < 2; ++k) dst[n][k] = *(const LAS bf16x8*)(lds + PG8_SB(b, h) + boff + n * 2048 + k * 1024); } while (0)
; #define PG8_WAIT_V(n) asm volatile("s_waitcnt vmcnt(" #n ")" ::: "memory")
; #define PG8_WAIT_L(n) asm volatile("s_waitcnt lgkmcnt(" #n ")" ::: "memory")
; #define PG8_BAR __builtin_amdgcn_s_barrier()
; #define PG8_SCHED __builtin_amdgcn_sched_barrier(0)
; template <class Epi, class Sched, bool SWAPD = false>
; __device__ __forceinline__ void gemm_phase(LAS unsigned char* lds, const Gemm g, const Sched& S, const Epi& E) {
;     ...
;             PG8_WAIT_V(8); PG8_WAIT_L(0); PG8_BAR; PG8_MMA(1, 0, At, B0); PG8_MMA(1, 1, At, B1); PG8_BAR; PG8_SCHED;
;             PG8_LDB(B0, 1, 0); PG8_LDB(B1, 1, 1); PG8_SCHED; PG8_LDA(At, 1, 0); PG8_STAGE(PG8_SA(0, 1), a2 + hstepA, voffA);
;             PG8_WAIT_V(8); PG8_WAIT_L(0); PG8_BAR; PG8_MMA(0, 0, At, B0); PG8_MMA(0, 1, At, B1); PG8_BAR; PG8_SCHED;
;             PG8_LDA(At, 1, 1); PG8_STAGE(PG8_SB(1, 0), b3, voffB); PG8_STAGE(PG8_SB(1, 1), b3 + hstepB, voffB); PG8_STAGE(PG8_SA(1, 0), a3, voffA);
	s_setprio 1
	v_mfma_f32_16x16x32_bf16 v[60:63], v[146:149], v[184:187], v[60:63]
	v_mfma_f32_16x16x32_bf16 v[56:59], v[160:163], v[184:187], v[56:59]
	v_mfma_f32_16x16x32_bf16 v[44:47], v[146:149], v[192:195], v[44:47]
	v_mfma_f32_16x16x32_bf16 v[40:43], v[160:163], v[192:195], v[40:43]
	v_mfma_f32_16x16x32_bf16 v[28:31], v[146:149], v[200:203], v[28:31]
	v_mfma_f32_16x16x32_bf16 v[24:27], v[160:163], v[200:203], v[24:27]
	v_mfma_f32_16x16x32_bf16 v[12:15], v[146:149], v[212:215], v[12:15]
	v_mfma_f32_16x16x32_bf16 v[8:11], v[160:163], v[212:215], v[8:11]
	v_mfma_f32_16x16x32_bf16 v[60:63], v[156:159], v[188:191], v[60:63]
	v_mfma_f32_16x16x32_bf16 v[56:59], v[164:167], v[188:191], v[56:59]
	v_mfma_f32_16x16x32_bf16 v[44:47], v[156:159], v[196:199], v[44:47]
	v_mfma_f32_16x16x32_bf16 v[40:43], v[164:167], v[196:199], v[40:43]
	v_mfma_f32_16x16x32_bf16 v[28:31], v[156:159], v[208:211], v[28:31]
	v_mfma_f32_16x16x32_bf16 v[24:27], v[164:167], v[208:211], v[24:27]
	v_mfma_f32_16x16x32_bf16 v[12:15], v[156:159], v[216:219], v[12:15]
	v_mfma_f32_16x16x32_bf16 v[8:11], v[164:167], v[216:219], v[8:11]
	s_setprio 0
	s_setprio 1
	v_mfma_f32_16x16x32_bf16 v[52:55], v[168:171], v[184:187], v[52:55]
	v_mfma_f32_16x16x32_bf16 v[48:51], v[176:179], v[184:187], v[48:51]
	v_mfma_f32_16x16x32_bf16 v[36:39], v[168:171], v[192:195], v[36:39]
	v_mfma_f32_16x16x32_bf16 v[32:35], v[176:179], v[192:195], v[32:35]
	v_mfma_f32_16x16x32_bf16 v[20:23], v[168:171], v[200:203], v[20:23]
	v_mfma_f32_16x16x32_bf16 v[16:19], v[176:179], v[200:203], v[16:19]
	v_mfma_f32_16x16x32_bf16 v[4:7], v[168:171], v[212:215], v[4:7]
	v_mfma_f32_16x16x32_bf16 v[0:3], v[176:179], v[212:215], v[0:3]
	v_mfma_f32_16x16x32_bf16 v[52:55], v[172:175], v[188:191], v[52:55]
	v_mfma_f32_16x16x32_bf16 v[48:51], v[180:183], v[188:191], v[48:51]
	v_mfma_f32_16x16x32_bf16 v[36:39], v[172:175], v[196:199], v[36:39]
	v_mfma_f32_16x16x32_bf16 v[32:35], v[180:183], v[196:199], v[32:35]
	v_mfma_f32_16x16x32_bf16 v[20:23], v[172:175], v[208:211], v[20:23]
	v_mfma_f32_16x16x32_bf16 v[16:19], v[180:183], v[208:211], v[16:19]
	v_mfma_f32_16x16x32_bf16 v[4:7], v[172:175], v[216:219], v[4:7]
	v_mfma_f32_16x16x32_bf16 v[0:3], v[180:183], v[216:219], v[0:3]
	s_setprio 0
	s_barrier
	s_add_i32 s63, 0, 0x18000
	s_add_i32 s64, 0, 0x1c000
	v_add_u32_e32 v164, s63, v151
	v_add_u32_e32 v180, s64, v151
	ds_read_b128 v[146:149], v164
	ds_read_b128 v[156:159], v164 offset:1024
	ds_read_b128 v[160:163], v164 offset:2048
	ds_read_b128 v[164:167], v164 offset:3072
	ds_read_b128 v[168:171], v180
	ds_read_b128 v[172:175], v180 offset:1024
	ds_read_b128 v[176:179], v180 offset:2048
	ds_read_b128 v[180:183], v180 offset:3072
	s_add_u32 s42, s52, 0x1000
	s_addc_u32 s43, s53, 0
	s_mov_b32 m0, s33
	v_lshl_add_u64 v[222:223], s[42:43], 0, v[128:129]
	ds_read_b128 v[184:187], v155 offset:32768
	ds_read_b128 v[188:191], v155 offset:33792
	ds_read_b128 v[192:195], v155 offset:34816
	ds_read_b128 v[196:199], v155 offset:35840
	ds_read_b128 v[200:203], v155 offset:36864
	ds_read_b128 v[208:211], v155 offset:37888
	ds_read_b128 v[212:215], v155 offset:38912
	ds_read_b128 v[216:219], v155 offset:39936
	global_load_lds_dwordx4 v[222:223], off
	v_lshl_add_u64 v[222:223], s[42:43], 0, v[132:133]
	s_mov_b32 m0, s41
	s_nop 0
	global_load_lds_dwordx4 v[222:223], off
	s_waitcnt vmcnt(8)
	s_waitcnt lgkmcnt(0)
	s_barrier
	s_setprio 1
	v_mfma_f32_16x16x32_bf16 v[124:127], v[146:149], v[184:187], v[124:127]
	v_mfma_f32_16x16x32_bf16 v[120:123], v[160:163], v[184:187], v[120:123]
	v_mfma_f32_16x16x32_bf16 v[108:111], v[146:149], v[192:195], v[108:111]
	v_mfma_f32_16x16x32_bf16 v[104:107], v[160:163], v[192:195], v[104:107]
	v_mfma_f32_16x16x32_bf16 v[92:95], v[146:149], v[200:203], v[92:95]
	v_mfma_f32_16x16x32_bf16 v[88:91], v[160:163], v[200:203], v[88:91]
	v_mfma_f32_16x16x32_bf16 v[76:79], v[146:149], v[212:215], v[76:79]
	v_mfma_f32_16x16x32_bf16 v[72:75], v[160:163], v[212:215], v[72:75]
	v_mfma_f32_16x16x32_bf16 v[124:127], v[156:159], v[188:191], v[124:127]
	v_mfma_f32_16x16x32_bf16 v[120:123], v[164:167], v[188:191], v[120:123]
	v_mfma_f32_16x16x32_bf16 v[108:111], v[156:159], v[196:199], v[108:111]
	v_mfma_f32_16x16x32_bf16 v[104:107], v[164:167], v[196:199], v[104:107]
	v_mfma_f32_16x16x32_bf16 v[92:95], v[156:159], v[208:211], v[92:95]
	v_mfma_f32_16x16x32_bf16 v[88:91], v[164:167], v[208:211], v[88:91]
	v_mfma_f32_16x16x32_bf16 v[76:79], v[156:159], v[216:219], v[76:79]
	v_mfma_f32_16x16x32_bf16 v[72:75], v[164:167], v[216:219], v[72:75]
	s_setprio 0
	s_setprio 1
	v_mfma_f32_16x16x32_bf16 v[116:119], v[168:171], v[184:187], v[116:119]
	v_mfma_f32_16x16x32_bf16 v[112:115], v[176:179], v[184:187], v[112:115]
	v_mfma_f32_16x16x32_bf16 v[100:103], v[168:171], v[192:195], v[100:103]
	v_mfma_f32_16x16x32_bf16 v[96:99], v[176:179], v[192:195], v[96:99]
	v_mfma_f32_16x16x32_bf16 v[84:87], v[168:171], v[200:203], v[84:87]
	v_mfma_f32_16x16x32_bf16 v[80:83], v[176:179], v[200:203], v[80:83]
	v_mfma_f32_16x16x32_bf16 v[68:71], v[168:171], v[212:215], v[68:71]
	v_mfma_f32_16x16x32_bf16 v[64:67], v[176:179], v[212:215], v[64:67]
	v_mfma_f32_16x16x32_bf16 v[116:119], v[172:175], v[188:191], v[116:119]
	v_mfma_f32_16x16x32_bf16 v[112:115], v[180:183], v[188:191], v[112:115]
	v_mfma_f32_16x16x32_bf16 v[100:103], v[172:175], v[196:199], v[100:103]
	v_mfma_f32_16x16x32_bf16 v[96:99], v[180:183], v[196:199], v[96:99]
	v_mfma_f32_16x16x32_bf16 v[84:87], v[172:175], v[208:211], v[84:87]
	v_mfma_f32_16x16x32_bf16 v[80:83], v[180:183], v[208:211], v[80:83]
	v_mfma_f32_16x16x32_bf16 v[68:71], v[172:175], v[216:219], v[68:71]
	v_mfma_f32_16x16x32_bf16 v[64:67], v[180:183], v[216:219], v[64:67]
	s_setprio 0
	s_barrier
; #define PG8_STAGE(bufoff, gbase, voff) do { _Pragma("unroll") for (int _i = 0; _i < 2; ++_i) \
;         __builtin_amdgcn_global_load_lds((const unsigned*)((const char*)(gbase) + (voff)[_i]), (LAS unsigned*)(lds + (bufoff) + ldsw + _i * 8192), 16, 0, 0); } while (0)
; #define PG8_LDA(dst, b, h) do { _Pragma("unroll") for (int m = 0; m < 4; ++m) _Pragma("unroll") for (int k = 0; k < 2; ++k) dst[m][k] = *(const LAS bf16x8*)(lds + PG8_SA(b, h) + aoff + m * 2048 + k * 1024); } while (0)
; #define PG8_WAIT_V(n) asm volatile("s_waitcnt vmcnt(" #n ")" ::: "memory")
; #define PG8_WAIT_L(n) asm volatile("s_waitcnt lgkmcnt(" #n ")" ::: "memory")
; #define PG8_BAR __builtin_amdgcn_s_barrier()
; #define PG8_SCHED __builtin_amdgcn_sched_barrier(0)
; template <class Epi, class Sched, bool SWAPD = false>
; __device__ __forceinline__ void gemm_phase(LAS unsigned char* lds, const Gemm g, const Sched& S, const Epi& E) {
;     ...
;             PG8_WAIT_V(8); PG8_WAIT_L(0); PG8_BAR; PG8_MMA(0, 0, At, B0); PG8_MMA(0, 1, At, B1); PG8_BAR; PG8_SCHED;
;             PG8_LDA(At, 1, 1); PG8_STAGE(PG8_SB(1, 0), b3, voffB); PG8_STAGE(PG8_SB(1, 1), b3 + hstepB, voffB); PG8_STAGE(PG8_SA(1, 0), a3, voffA);
;             PG8_WAIT_V(8); PG8_WAIT_L(0); PG8_BAR; PG8_MMA(1, 0, At, B0); PG8_MMA(1, 1, At, B1); PG8_BAR; PG8_SCHED;
;         }
	s_add_i32 s42, s63, s21
	v_lshl_add_u64 v[204:205], v[204:205], 0, s[10:11]
	s_mov_b32 m0, s42
	ds_read_b128 v[184:187], v155 offset:49152
	ds_read_b128 v[188:191], v155 offset:50176
	ds_read_b128 v[192:195], v155 offset:51200
	ds_read_b128 v[196:199], v155 offset:52224
	ds_read_b128 v[200:203], v155 offset:53248
	ds_read_b128 v[208:211], v155 offset:54272
	ds_read_b128 v[212:215], v155 offset:55296
	ds_read_b128 v[216:219], v155 offset:56320
	global_load_lds_dwordx4 v[204:205], off
	s_add_i32 m0, s42, 0x2000
	s_add_u32 s42, s50, 0x20080
	v_lshl_add_u64 v[204:205], v[220:221], 0, s[10:11]
	s_addc_u32 s43, s51, 0
	s_add_i32 s50, s64, s21
	global_load_lds_dwordx4 v[204:205], off
	v_lshl_add_u64 v[204:205], s[42:43], 0, v[130:131]
	s_mov_b32 m0, s50
	s_nop 0
	global_load_lds_dwordx4 v[204:205], off
	v_lshl_add_u64 v[204:205], s[42:43], 0, v[134:135]
	s_add_i32 m0, s50, 0x2000
	s_nop 0
	global_load_lds_dwordx4 v[204:205], off
	v_lshl_add_u64 v[204:205], s[46:47], 0, v[128:129]
	s_mov_b32 m0, s55
	s_nop 0
	global_load_lds_dwordx4 v[204:205], off
	v_lshl_add_u64 v[204:205], s[46:47], 0, v[132:133]
	s_mov_b32 m0, s56
	s_nop 0
	global_load_lds_dwordx4 v[204:205], off
	s_waitcnt vmcnt(8)
	s_waitcnt lgkmcnt(0)
	s_barrier
	s_setprio 1
	v_mfma_f32_16x16x32_bf16 v[60:63], v[146:149], v[184:187], v[60:63]
	v_mfma_f32_16x16x32_bf16 v[56:59], v[160:163], v[184:187], v[56:59]
	v_mfma_f32_16x16x32_bf16 v[44:47], v[146:149], v[192:195], v[44:47]
	v_mfma_f32_16x16x32_bf16 v[40:43], v[160:163], v[192:195], v[40:43]
	v_mfma_f32_16x16x32_bf16 v[28:31], v[146:149], v[200:203], v[28:31]
	v_mfma_f32_16x16x32_bf16 v[24:27], v[160:163], v[200:203], v[24:27]
	v_mfma_f32_16x16x32_bf16 v[12:15], v[146:149], v[212:215], v[12:15]
	v_mfma_f32_16x16x32_bf16 v[8:11], v[160:163], v[212:215], v[8:11]
	v_mfma_f32_16x16x32_bf16 v[60:63], v[156:159], v[188:191], v[60:63]
	v_mfma_f32_16x16x32_bf16 v[56:59], v[164:167], v[188:191], v[56:59]
	v_mfma_f32_16x16x32_bf16 v[44:47], v[156:159], v[196:199], v[44:47]
	v_mfma_f32_16x16x32_bf16 v[40:43], v[164:167], v[196:199], v[40:43]
	v_mfma_f32_16x16x32_bf16 v[28:31], v[156:159], v[208:211], v[28:31]
	v_mfma_f32_16x16x32_bf16 v[24:27], v[164:167], v[208:211], v[24:27]
	v_mfma_f32_16x16x32_bf16 v[12:15], v[156:159], v[216:219], v[12:15]
	v_mfma_f32_16x16x32_bf16 v[8:11], v[164:167], v[216:219], v[8:11]
	s_setprio 0
	s_setprio 1
	v_mfma_f32_16x16x32_bf16 v[52:55], v[168:171], v[184:187], v[52:55]
	v_mfma_f32_16x16x32_bf16 v[48:51], v[176:179], v[184:187], v[48:51]
	v_mfma_f32_16x16x32_bf16 v[36:39], v[168:171], v[192:195], v[36:39]
	v_mfma_f32_16x16x32_bf16 v[32:35], v[176:179], v[192:195], v[32:35]
	v_mfma_f32_16x16x32_bf16 v[20:23], v[168:171], v[200:203], v[20:23]
	v_mfma_f32_16x16x32_bf16 v[16:19], v[176:179], v[200:203], v[16:19]
	v_mfma_f32_16x16x32_bf16 v[4:7], v[168:171], v[212:215], v[4:7]
	v_mfma_f32_16x16x32_bf16 v[0:3], v[176:179], v[212:215], v[0:3]
	v_mfma_f32_16x16x32_bf16 v[52:55], v[172:175], v[188:191], v[52:55]
	v_mfma_f32_16x16x32_bf16 v[48:51], v[180:183], v[188:191], v[48:51]
	v_mfma_f32_16x16x32_bf16 v[36:39], v[172:175], v[196:199], v[36:39]
	v_mfma_f32_16x16x32_bf16 v[32:35], v[180:183], v[196:199], v[32:35]
	v_mfma_f32_16x16x32_bf16 v[20:23], v[172:175], v[208:211], v[20:23]
	v_mfma_f32_16x16x32_bf16 v[16:19], v[180:183], v[208:211], v[16:19]
	v_mfma_f32_16x16x32_bf16 v[4:7], v[172:175], v[216:219], v[4:7]
	v_mfma_f32_16x16x32_bf16 v[0:3], v[180:183], v[216:219], v[0:3]
	s_setprio 0
	s_add_i32 s62, s62, 2
	s_add_u32 s60, s60, 0x100
	s_addc_u32 s61, s61, 0
	s_cmp_gt_u32 s62, 5
	s_mov_b64 s[42:43], s[44:45]
	s_barrier
	s_cbranch_scc0 .LBB0_842
	s_and_b64 vcc, exec, s[12:13]
	s_cbranch_vccz .LBB0_845
	s_barrier

; #define PG8_STAGE(bufoff, gbase, voff) do { _Pragma("unroll") for (int _i = 0; _i < 2; ++_i) \
;         __builtin_amdgcn_global_load_lds((const unsigned*)((const char*)(gbase) + (voff)[_i]), (LAS unsigned*)(lds + (bufoff) + ldsw + _i * 8192), 16, 0, 0); } while (0)
; #define PG8_LDA(dst, b, h) do { _Pragma("unroll") for (int m = 0; m < 4; ++m) _Pragma("unroll") for (int k = 0; k < 2; ++k) dst[m][k] = *(const LAS bf16x8*)(lds + PG8_SA(b, h) + aoff + m * 2048 + k * 1024); } while (0)
; #define PG8_LDB(dst, b, h) do { _Pragma("unroll") for (int n = 0; n < 2; ++n) _Pragma("unroll") for (int k = 0; k < 2; ++k) dst[n][k] = *(const LAS bf16x8*)(lds + PG8_SB(b, h) + boff + n * 2048 + k * 1024); } while (0)
; #define PG8_WAIT_V(n) asm volatile("s_waitcnt vmcnt(" #n ")" ::: "memory")
; #define PG8_WAIT_L(n) asm volatile("s_waitcnt lgkmcnt(" #n ")" ::: "memory")
; #define PG8_BAR __builtin_amdgcn_s_barrier()
; #define PG8_SCHED __builtin_amdgcn_sched_barrier(0)
; template <class Epi, class Sched, bool SWAPD = false>
; __device__ __forceinline__ void gemm_phase(LAS unsigned char* lds, const Gemm g, const Sched& S, const Epi& E) {
;     ...
;         for (int t = 0; t < nt; t += 2) {
;             const bool last = (t == nt - 2);
;             const char* a1 = cA + (size_t)(t + 1) * kstepA;
;             const char* a2 = last ? nA : cA + (size_t)(t + 2) * kstepA; const char* b2 = last ? nB : cB + (size_t)(t + 2) * kstep;
;             const char* a3 = a2 + kstepA; const char* b3 = b2 + kstep;
;             PG8_LDB(B0, 0, 0); PG8_LDB(B1, 0, 1); PG8_SCHED; PG8_LDA(At, 0, 0); PG8_STAGE(PG8_SA(1, 1), a1 + hstepA, voffA);
;             PG8_WAIT_V(8); PG8_WAIT_L(0); PG8_BAR; PG8_MMA(0, 0, At, B0); PG8_MMA(0, 1, At, B1); PG8_BAR; PG8_SCHED;
;             PG8_LDA(At, 0, 1); PG8_STAGE(PG8_SB(0, 0), b2, voffB); PG8_STAGE(PG8_SB(0, 1), b2 + hstepB, voffB); PG8_STAGE(PG8_SA(0, 0), a2, voffA);
;             PG8_WAIT_V(8); PG8_WAIT_L(0); PG8_BAR; PG8_MMA(1, 0, At, B0); PG8_MMA(1, 1, At, B1); PG8_BAR; PG8_SCHED;
.LBB0_918:
	ds_read_b128 v[128:131], v200
	ds_read_b128 v[132:135], v200 offset:1024
	ds_read_b128 v[136:139], v200 offset:2048
	ds_read_b128 v[140:143], v200 offset:3072
	ds_read_b128 v[144:147], v201
	ds_read_b128 v[148:151], v201 offset:1024
	ds_read_b128 v[152:155], v201 offset:2048
	ds_read_b128 v[156:159], v201 offset:3072
	s_add_u32 s44, s42, 0xfffc0080
	s_addc_u32 s45, s43, -1
	s_cmp_eq_u32 s60, 12
	s_cselect_b32 s47, s23, s45
	s_cselect_b32 s46, s25, s44
	s_cselect_b32 s45, s35, s59
	s_cselect_b32 s44, s41, s58
	v_lshl_add_u64 v[196:197], s[42:43], 0, v[180:181]
	s_add_i32 m0, s30, 0xc000
	ds_read_b128 v[188:191], v202
	ds_read_b128 v[192:195], v202 offset:1024
	ds_read_b128 v[208:211], v202 offset:2048
	ds_read_b128 v[212:215], v202 offset:3072
	ds_read_b128 v[216:219], v202 offset:4096
	ds_read_b128 v[220:223], v202 offset:5120
	ds_read_b128 v[224:227], v202 offset:6144
	ds_read_b128 v[228:231], v202 offset:7168
	global_load_lds_dwordx4 v[196:197], off
	v_lshl_add_u64 v[196:197], s[42:43], 0, v[182:183]
	s_add_i32 m0, s30, 0xe000
	s_nop 0
	global_load_lds_dwordx4 v[196:197], off
	s_waitcnt vmcnt(8)
	s_waitcnt lgkmcnt(0)
	s_barrier
	s_setprio 1
	v_mfma_f32_16x16x32_bf16 v[124:127], v[128:131], v[188:191], v[124:127]
	v_mfma_f32_16x16x32_bf16 v[120:123], v[136:139], v[188:191], v[120:123]
	v_mfma_f32_16x16x32_bf16 v[116:119], v[128:131], v[208:211], v[116:119]
	v_mfma_f32_16x16x32_bf16 v[112:115], v[136:139], v[208:211], v[112:115]
	v_mfma_f32_16x16x32_bf16 v[92:95], v[128:131], v[216:219], v[92:95]
	v_mfma_f32_16x16x32_bf16 v[88:91], v[136:139], v[216:219], v[88:91]
	v_mfma_f32_16x16x32_bf16 v[76:79], v[128:131], v[224:227], v[76:79]
	v_mfma_f32_16x16x32_bf16 v[72:75], v[136:139], v[224:227], v[72:75]
	v_mfma_f32_16x16x32_bf16 v[124:127], v[132:135], v[192:195], v[124:127]
	v_mfma_f32_16x16x32_bf16 v[120:123], v[140:143], v[192:195], v[120:123]
	v_mfma_f32_16x16x32_bf16 v[116:119], v[132:135], v[212:215], v[116:119]
	v_mfma_f32_16x16x32_bf16 v[112:115], v[140:143], v[212:215], v[112:115]
	v_mfma_f32_16x16x32_bf16 v[92:95], v[132:135], v[220:223], v[92:95]
	v_mfma_f32_16x16x32_bf16 v[88:91], v[140:143], v[220:223], v[88:91]
	v_mfma_f32_16x16x32_bf16 v[76:79], v[132:135], v[228:231], v[76:79]
	v_mfma_f32_16x16x32_bf16 v[72:75], v[140:143], v[228:231], v[72:75]
	s_setprio 0
	s_setprio 1
	v_mfma_f32_16x16x32_bf16 v[108:111], v[144:147], v[188:191], v[108:111]
	v_mfma_f32_16x16x32_bf16 v[104:107], v[152:155], v[188:191], v[104:107]
	v_mfma_f32_16x16x32_bf16 v[100:103], v[144:147], v[208:211], v[100:103]
	v_mfma_f32_16x16x32_bf16 v[96:99], v[152:155], v[208:211], v[96:99]
	v_mfma_f32_16x16x32_bf16 v[84:87], v[144:147], v[216:219], v[84:87]
	v_mfma_f32_16x16x32_bf16 v[80:83], v[152:155], v[216:219], v[80:83]
	v_mfma_f32_16x16x32_bf16 v[68:71], v[144:147], v[224:227], v[68:71]
	v_mfma_f32_16x16x32_bf16 v[64:67], v[152:155], v[224:227], v[64:67]
	v_mfma_f32_16x16x32_bf16 v[108:111], v[148:151], v[192:195], v[108:111]
	v_mfma_f32_16x16x32_bf16 v[104:107], v[156:159], v[192:195], v[104:107]
	v_mfma_f32_16x16x32_bf16 v[100:103], v[148:151], v[212:215], v[100:103]
	v_mfma_f32_16x16x32_bf16 v[96:99], v[156:159], v[212:215], v[96:99]
	v_mfma_f32_16x16x32_bf16 v[84:87], v[148:151], v[220:223], v[84:87]
	v_mfma_f32_16x16x32_bf16 v[80:83], v[156:159], v[220:223], v[80:83]
	v_mfma_f32_16x16x32_bf16 v[68:71], v[148:151], v[228:231], v[68:71]
	v_mfma_f32_16x16x32_bf16 v[64:67], v[156:159], v[228:231], v[64:67]
	s_setprio 0
	s_barrier
	s_add_i32 s61, s56, s21
	v_lshl_add_u64 v[196:197], s[44:45], 0, v[160:161]
	s_mov_b32 m0, s61
	ds_read_b128 v[188:191], v202 offset:16384
	ds_read_b128 v[192:195], v202 offset:17408
	ds_read_b128 v[208:211], v202 offset:18432
	ds_read_b128 v[212:215], v202 offset:19456
	ds_read_b128 v[216:219], v202 offset:20480
	ds_read_b128 v[220:223], v202 offset:21504
	ds_read_b128 v[224:227], v202 offset:22528
	ds_read_b128 v[228:231], v202 offset:23552
	global_load_lds_dwordx4 v[196:197], off
	s_add_i32 m0, s61, 0x2000
	s_add_u32 s62, s44, 0x40000
	v_lshl_add_u64 v[204:205], s[44:45], 0, v[162:163]
	s_addc_u32 s63, s45, 0
	s_add_i32 s61, s57, s21
	global_load_lds_dwordx4 v[204:205], off
	v_lshl_add_u64 v[232:233], s[62:63], 0, v[160:161]
	s_mov_b32 m0, s61
	v_lshl_add_u64 v[234:235], s[46:47], 0, v[162:163]
	global_load_lds_dwordx4 v[232:233], off
	v_lshl_add_u64 v[232:233], s[62:63], 0, v[162:163]
	s_add_i32 m0, s61, 0x2000
	s_nop 0
	global_load_lds_dwordx4 v[232:233], off
	v_lshl_add_u64 v[232:233], s[46:47], 0, v[160:161]
	s_mov_b32 m0, s30
	s_nop 0
	global_load_lds_dwordx4 v[232:233], off
	s_mov_b32 m0, s31
	s_nop 0
	global_load_lds_dwordx4 v[234:235], off
	s_waitcnt vmcnt(8)
	s_waitcnt lgkmcnt(0)
	s_barrier
; #define PG8_STAGE(bufoff, gbase, voff) do { _Pragma("unroll") for (int _i = 0; _i < 2; ++_i) \
;         __builtin_amdgcn_global_load_lds((const unsigned*)((const char*)(gbase) + (voff)[_i]), (LAS unsigned*)(lds + (bufoff) + ldsw + _i * 8192), 16, 0, 0); } while (0)
; #define PG8_LDA(dst, b, h) do { _Pragma("unroll") for (int m = 0; m < 4; ++m) _Pragma("unroll") for (int k = 0; k < 2; ++k) dst[m][k] = *(const LAS bf16x8*)(lds + PG8_SA(b, h) + aoff + m * 2048 + k * 1024); } while (0)
; #define PG8_LDB(dst, b, h) do { _Pragma("unroll") for (int n = 0; n < 2; ++n) _Pragma("unroll") for (int k = 0; k < 2; ++k) dst[n][k] = *(const LAS bf16x8*)(lds + PG8_SB(b, h) + boff + n * 2048 + k * 1024); } while (0)
; #define PG8_WAIT_V(n) asm volatile("s_waitcnt vmcnt(" #n ")" ::: "memory")
; #define PG8_WAIT_L(n) asm volatile("s_waitcnt lgkmcnt(" #n ")" ::: "memory")
; #define PG8_BAR __builtin_amdgcn_s_barrier()
; #define PG8_SCHED __builtin_amdgcn_sched_barrier(0)
; template <class Epi, class Sched, bool SWAPD = false>
; __device__ __forceinline__ void gemm_phase(LAS unsigned char* lds, const Gemm g, const Sched& S, const Epi& E) {
;     ...
;             PG8_WAIT_V(8); PG8_WAIT_L(0); PG8_BAR; PG8_MMA(1, 0, At, B0); PG8_MMA(1, 1, At, B1); PG8_BAR; PG8_SCHED;
;             PG8_LDB(B0, 1, 0); PG8_LDB(B1, 1, 1); PG8_SCHED; PG8_LDA(At, 1, 0); PG8_STAGE(PG8_SA(0, 1), a2 + hstepA, voffA);
;             PG8_WAIT_V(8); PG8_WAIT_L(0); PG8_BAR; PG8_MMA(0, 0, At, B0); PG8_MMA(0, 1, At, B1); PG8_BAR; PG8_SCHED;
;             PG8_LDA(At, 1, 1); PG8_STAGE(PG8_SB(1, 0), b3, voffB); PG8_STAGE(PG8_SB(1, 1), b3 + hstepB, voffB); PG8_STAGE(PG8_SA(1, 0), a3, voffA);
	s_setprio 1
	v_mfma_f32_16x16x32_bf16 v[60:63], v[128:131], v[188:191], v[60:63]
	v_mfma_f32_16x16x32_bf16 v[56:59], v[136:139], v[188:191], v[56:59]
	v_mfma_f32_16x16x32_bf16 v[44:47], v[128:131], v[208:211], v[44:47]
	v_mfma_f32_16x16x32_bf16 v[40:43], v[136:139], v[208:211], v[40:43]
	v_mfma_f32_16x16x32_bf16 v[36:39], v[128:131], v[216:219], v[36:39]
	v_mfma_f32_16x16x32_bf16 v[32:35], v[136:139], v[216:219], v[32:35]
	v_mfma_f32_16x16x32_bf16 v[20:23], v[128:131], v[224:227], v[20:23]
	v_mfma_f32_16x16x32_bf16 v[16:19], v[136:139], v[224:227], v[16:19]
	v_mfma_f32_16x16x32_bf16 v[60:63], v[132:135], v[192:195], v[60:63]
	v_mfma_f32_16x16x32_bf16 v[56:59], v[140:143], v[192:195], v[56:59]
	v_mfma_f32_16x16x32_bf16 v[44:47], v[132:135], v[212:215], v[44:47]
	v_mfma_f32_16x16x32_bf16 v[40:43], v[140:143], v[212:215], v[40:43]
	v_mfma_f32_16x16x32_bf16 v[36:39], v[132:135], v[220:223], v[36:39]
	v_mfma_f32_16x16x32_bf16 v[32:35], v[140:143], v[220:223], v[32:35]
	v_mfma_f32_16x16x32_bf16 v[20:23], v[132:135], v[228:231], v[20:23]
	v_mfma_f32_16x16x32_bf16 v[16:19], v[140:143], v[228:231], v[16:19]
	s_setprio 0
	s_setprio 1
	v_mfma_f32_16x16x32_bf16 v[52:55], v[144:147], v[188:191], v[52:55]
	v_mfma_f32_16x16x32_bf16 v[48:51], v[152:155], v[188:191], v[48:51]
	v_mfma_f32_16x16x32_bf16 v[28:31], v[144:147], v[208:211], v[28:31]
	v_mfma_f32_16x16x32_bf16 v[24:27], v[152:155], v[208:211], v[24:27]
	v_mfma_f32_16x16x32_bf16 v[12:15], v[144:147], v[216:219], v[12:15]
	v_mfma_f32_16x16x32_bf16 v[8:11], v[152:155], v[216:219], v[8:11]
	v_mfma_f32_16x16x32_bf16 v[4:7], v[144:147], v[224:227], v[4:7]
	v_mfma_f32_16x16x32_bf16 v[0:3], v[152:155], v[224:227], v[0:3]
	v_mfma_f32_16x16x32_bf16 v[52:55], v[148:151], v[192:195], v[52:55]
	v_mfma_f32_16x16x32_bf16 v[48:51], v[156:159], v[192:195], v[48:51]
	v_mfma_f32_16x16x32_bf16 v[28:31], v[148:151], v[212:215], v[28:31]
	v_mfma_f32_16x16x32_bf16 v[24:27], v[156:159], v[212:215], v[24:27]
	v_mfma_f32_16x16x32_bf16 v[12:15], v[148:151], v[220:223], v[12:15]
	v_mfma_f32_16x16x32_bf16 v[8:11], v[156:159], v[220:223], v[8:11]
	v_mfma_f32_16x16x32_bf16 v[4:7], v[148:151], v[228:231], v[4:7]
	v_mfma_f32_16x16x32_bf16 v[0:3], v[156:159], v[228:231], v[0:3]
	s_setprio 0
	s_barrier
	s_add_i32 s61, 0, 0x18000
	s_add_i32 s62, 0, 0x1c000
	v_add_u32_e32 v140, s61, v198
	v_add_u32_e32 v156, s62, v198
	ds_read_b128 v[128:131], v140
	ds_read_b128 v[132:135], v140 offset:1024
	ds_read_b128 v[136:139], v140 offset:2048
	ds_read_b128 v[140:143], v140 offset:3072
	ds_read_b128 v[144:147], v156
	ds_read_b128 v[148:151], v156 offset:1024
	ds_read_b128 v[152:155], v156 offset:2048
	ds_read_b128 v[156:159], v156 offset:3072
	s_add_u32 s46, s46, 0x40000
	s_addc_u32 s47, s47, 0
	s_mov_b32 m0, s33
	v_lshl_add_u64 v[236:237], s[46:47], 0, v[160:161]
	ds_read_b128 v[188:191], v202 offset:32768
	ds_read_b128 v[192:195], v202 offset:33792
	ds_read_b128 v[208:211], v202 offset:34816
	ds_read_b128 v[212:215], v202 offset:35840
	ds_read_b128 v[216:219], v202 offset:36864
	ds_read_b128 v[220:223], v202 offset:37888
	ds_read_b128 v[224:227], v202 offset:38912
	ds_read_b128 v[228:231], v202 offset:39936
	global_load_lds_dwordx4 v[236:237], off
	v_lshl_add_u64 v[236:237], s[46:47], 0, v[162:163]
	s_mov_b32 m0, s50
	s_nop 0
	global_load_lds_dwordx4 v[236:237], off
	s_waitcnt vmcnt(8)
	s_waitcnt lgkmcnt(0)
	s_barrier
	s_setprio 1
	v_mfma_f32_16x16x32_bf16 v[124:127], v[128:131], v[188:191], v[124:127]
	v_mfma_f32_16x16x32_bf16 v[120:123], v[136:139], v[188:191], v[120:123]
	v_mfma_f32_16x16x32_bf16 v[116:119], v[128:131], v[208:211], v[116:119]
	v_mfma_f32_16x16x32_bf16 v[112:115], v[136:139], v[208:211], v[112:115]
	v_mfma_f32_16x16x32_bf16 v[92:95], v[128:131], v[216:219], v[92:95]
	v_mfma_f32_16x16x32_bf16 v[88:91], v[136:139], v[216:219], v[88:91]
	v_mfma_f32_16x16x32_bf16 v[76:79], v[128:131], v[224:227], v[76:79]
	v_mfma_f32_16x16x32_bf16 v[72:75], v[136:139], v[224:227], v[72:75]
	v_mfma_f32_16x16x32_bf16 v[124:127], v[132:135], v[192:195], v[124:127]
	v_mfma_f32_16x16x32_bf16 v[120:123], v[140:143], v[192:195], v[120:123]
	v_mfma_f32_16x16x32_bf16 v[116:119], v[132:135], v[212:215], v[116:119]
	v_mfma_f32_16x16x32_bf16 v[112:115], v[140:143], v[212:215], v[112:115]
	v_mfma_f32_16x16x32_bf16 v[92:95], v[132:135], v[220:223], v[92:95]
	v_mfma_f32_16x16x32_bf16 v[88:91], v[140:143], v[220:223], v[88:91]
	v_mfma_f32_16x16x32_bf16 v[76:79], v[132:135], v[228:231], v[76:79]
	v_mfma_f32_16x16x32_bf16 v[72:75], v[140:143], v[228:231], v[72:75]
	s_setprio 0
	s_setprio 1
	v_mfma_f32_16x16x32_bf16 v[108:111], v[144:147], v[188:191], v[108:111]
	v_mfma_f32_16x16x32_bf16 v[104:107], v[152:155], v[188:191], v[104:107]
	v_mfma_f32_16x16x32_bf16 v[100:103], v[144:147], v[208:211], v[100:103]
	v_mfma_f32_16x16x32_bf16 v[96:99], v[152:155], v[208:211], v[96:99]
	v_mfma_f32_16x16x32_bf16 v[84:87], v[144:147], v[216:219], v[84:87]
	v_mfma_f32_16x16x32_bf16 v[80:83], v[152:155], v[216:219], v[80:83]
	v_mfma_f32_16x16x32_bf16 v[68:71], v[144:147], v[224:227], v[68:71]
	v_mfma_f32_16x16x32_bf16 v[64:67], v[152:155], v[224:227], v[64:67]
	v_mfma_f32_16x16x32_bf16 v[108:111], v[148:151], v[192:195], v[108:111]
	v_mfma_f32_16x16x32_bf16 v[104:107], v[156:159], v[192:195], v[104:107]
	v_mfma_f32_16x16x32_bf16 v[100:103], v[148:151], v[212:215], v[100:103]
	v_mfma_f32_16x16x32_bf16 v[96:99], v[156:159], v[212:215], v[96:99]
	v_mfma_f32_16x16x32_bf16 v[84:87], v[148:151], v[220:223], v[84:87]
	v_mfma_f32_16x16x32_bf16 v[80:83], v[156:159], v[220:223], v[80:83]
	v_mfma_f32_16x16x32_bf16 v[68:71], v[148:151], v[228:231], v[68:71]
	v_mfma_f32_16x16x32_bf16 v[64:67], v[156:159], v[228:231], v[64:67]
	s_setprio 0
	s_barrier
; #define PG8_STAGE(bufoff, gbase, voff) do { _Pragma("unroll") for (int _i = 0; _i < 2; ++_i) \
;         __builtin_amdgcn_global_load_lds((const unsigned*)((const char*)(gbase) + (voff)[_i]), (LAS unsigned*)(lds + (bufoff) + ldsw + _i * 8192), 16, 0, 0); } while (0)
; #define PG8_LDA(dst, b, h) do { _Pragma("unroll") for (int m = 0; m < 4; ++m) _Pragma("unroll") for (int k = 0; k < 2; ++k) dst[m][k] = *(const LAS bf16x8*)(lds + PG8_SA(b, h) + aoff + m * 2048 + k * 1024); } while (0)
; #define PG8_WAIT_V(n) asm volatile("s_waitcnt vmcnt(" #n ")" ::: "memory")
; #define PG8_WAIT_L(n) asm volatile("s_waitcnt lgkmcnt(" #n ")" ::: "memory")
; #define PG8_BAR __builtin_amdgcn_s_barrier()
; #define PG8_SCHED __builtin_amdgcn_sched_barrier(0)
; template <class Epi, class Sched, bool SWAPD = false>
; __device__ __forceinline__ void gemm_phase(LAS unsigned char* lds, const Gemm g, const Sched& S, const Epi& E) {
;     ...
;             PG8_WAIT_V(8); PG8_WAIT_L(0); PG8_BAR; PG8_MMA(0, 0, At, B0); PG8_MMA(0, 1, At, B1); PG8_BAR; PG8_SCHED;
;             PG8_LDA(At, 1, 1); PG8_STAGE(PG8_SB(1, 0), b3, voffB); PG8_STAGE(PG8_SB(1, 1), b3 + hstepB, voffB); PG8_STAGE(PG8_SA(1, 0), a3, voffA);
;             PG8_WAIT_V(8); PG8_WAIT_L(0); PG8_BAR; PG8_MMA(1, 0, At, B0); PG8_MMA(1, 1, At, B1); PG8_BAR; PG8_SCHED;
;         }
	s_add_i32 s46, s61, s21
	v_lshl_add_u64 v[196:197], v[196:197], 0, s[10:11]
	s_mov_b32 m0, s46
	ds_read_b128 v[188:191], v202 offset:49152
	ds_read_b128 v[192:195], v202 offset:50176
	ds_read_b128 v[208:211], v202 offset:51200
	ds_read_b128 v[212:215], v202 offset:52224
	ds_read_b128 v[216:219], v202 offset:53248
	ds_read_b128 v[220:223], v202 offset:54272
	ds_read_b128 v[224:227], v202 offset:55296
	ds_read_b128 v[228:231], v202 offset:56320
	global_load_lds_dwordx4 v[196:197], off
	s_add_i32 m0, s46, 0x2000
	s_add_u32 s44, s44, 0x40080
	v_lshl_add_u64 v[196:197], v[204:205], 0, s[10:11]
	s_addc_u32 s45, s45, 0
	s_add_i32 s46, s62, s21
	global_load_lds_dwordx4 v[196:197], off
	v_lshl_add_u64 v[196:197], s[44:45], 0, v[160:161]
	s_mov_b32 m0, s46
	s_nop 0
	global_load_lds_dwordx4 v[196:197], off
	v_lshl_add_u64 v[196:197], s[44:45], 0, v[162:163]
	s_add_i32 m0, s46, 0x2000
	s_nop 0
	global_load_lds_dwordx4 v[196:197], off
	v_lshl_add_u64 v[196:197], v[232:233], 0, s[10:11]
	s_mov_b32 m0, s54
	s_nop 0
	global_load_lds_dwordx4 v[196:197], off
	v_lshl_add_u64 v[196:197], v[234:235], 0, s[10:11]
	s_mov_b32 m0, s55
	s_nop 0
	global_load_lds_dwordx4 v[196:197], off
	s_waitcnt vmcnt(8)
	s_waitcnt lgkmcnt(0)
	s_barrier
	s_setprio 1
	v_mfma_f32_16x16x32_bf16 v[60:63], v[128:131], v[188:191], v[60:63]
	v_mfma_f32_16x16x32_bf16 v[56:59], v[136:139], v[188:191], v[56:59]
	v_mfma_f32_16x16x32_bf16 v[44:47], v[128:131], v[208:211], v[44:47]
	v_mfma_f32_16x16x32_bf16 v[40:43], v[136:139], v[208:211], v[40:43]
	v_mfma_f32_16x16x32_bf16 v[36:39], v[128:131], v[216:219], v[36:39]
	v_mfma_f32_16x16x32_bf16 v[32:35], v[136:139], v[216:219], v[32:35]
	v_mfma_f32_16x16x32_bf16 v[20:23], v[128:131], v[224:227], v[20:23]
	v_mfma_f32_16x16x32_bf16 v[16:19], v[136:139], v[224:227], v[16:19]
	v_mfma_f32_16x16x32_bf16 v[60:63], v[132:135], v[192:195], v[60:63]
	v_mfma_f32_16x16x32_bf16 v[56:59], v[140:143], v[192:195], v[56:59]
	v_mfma_f32_16x16x32_bf16 v[44:47], v[132:135], v[212:215], v[44:47]
	v_mfma_f32_16x16x32_bf16 v[40:43], v[140:143], v[212:215], v[40:43]
	v_mfma_f32_16x16x32_bf16 v[36:39], v[132:135], v[220:223], v[36:39]
	v_mfma_f32_16x16x32_bf16 v[32:35], v[140:143], v[220:223], v[32:35]
	v_mfma_f32_16x16x32_bf16 v[20:23], v[132:135], v[228:231], v[20:23]
	v_mfma_f32_16x16x32_bf16 v[16:19], v[140:143], v[228:231], v[16:19]
	s_setprio 0
	s_setprio 1
	v_mfma_f32_16x16x32_bf16 v[52:55], v[144:147], v[188:191], v[52:55]
	v_mfma_f32_16x16x32_bf16 v[48:51], v[152:155], v[188:191], v[48:51]
	v_mfma_f32_16x16x32_bf16 v[28:31], v[144:147], v[208:211], v[28:31]
	v_mfma_f32_16x16x32_bf16 v[24:27], v[152:155], v[208:211], v[24:27]
	v_mfma_f32_16x16x32_bf16 v[12:15], v[144:147], v[216:219], v[12:15]
	v_mfma_f32_16x16x32_bf16 v[8:11], v[152:155], v[216:219], v[8:11]
	v_mfma_f32_16x16x32_bf16 v[4:7], v[144:147], v[224:227], v[4:7]
	v_mfma_f32_16x16x32_bf16 v[0:3], v[152:155], v[224:227], v[0:3]
	v_mfma_f32_16x16x32_bf16 v[52:55], v[148:151], v[192:195], v[52:55]
	v_mfma_f32_16x16x32_bf16 v[48:51], v[156:159], v[192:195], v[48:51]
	v_mfma_f32_16x16x32_bf16 v[28:31], v[148:151], v[212:215], v[28:31]
	v_mfma_f32_16x16x32_bf16 v[24:27], v[156:159], v[212:215], v[24:27]
	v_mfma_f32_16x16x32_bf16 v[12:15], v[148:151], v[220:223], v[12:15]
	v_mfma_f32_16x16x32_bf16 v[8:11], v[156:159], v[220:223], v[8:11]
	v_mfma_f32_16x16x32_bf16 v[4:7], v[148:151], v[228:231], v[4:7]
	v_mfma_f32_16x16x32_bf16 v[0:3], v[156:159], v[228:231], v[0:3]
	s_setprio 0
	s_add_i32 s60, s60, 2
	s_add_u32 s42, s42, 0x100
	s_addc_u32 s43, s43, 0
	s_add_u32 s58, s58, 0x100
	s_addc_u32 s59, s59, 0
	s_cmp_gt_u32 s60, 13
	s_barrier
	s_cbranch_scc0 .LBB0_918
	s_and_b64 vcc, exec, s[12:13]
	s_cbranch_vccz .LBB0_921
	s_barrier

; #define PG8_STAGE(bufoff, gbase, voff) do { _Pragma("unroll") for (int _i = 0; _i < 2; ++_i) \
;         __builtin_amdgcn_global_load_lds((const unsigned*)((const char*)(gbase) + (voff)[_i]), (LAS unsigned*)(lds + (bufoff) + ldsw + _i * 8192), 16, 0, 0); } while (0)
; #define PG8_LDA(dst, b, h) do { _Pragma("unroll") for (int m = 0; m < 4; ++m) _Pragma("unroll") for (int k = 0; k < 2; ++k) dst[m][k] = *(const LAS bf16x8*)(lds + PG8_SA(b, h) + aoff + m * 2048 + k * 1024); } while (0)
; #define PG8_LDB(dst, b, h) do { _Pragma("unroll") for (int n = 0; n < 2; ++n) _Pragma("unroll") for (int k = 0; k < 2; ++k) dst[n][k] = *(const LAS bf16x8*)(lds + PG8_SB(b, h) + boff + n * 2048 + k * 1024); } while (0)
; #define PG8_WAIT_V(n) asm volatile("s_waitcnt vmcnt(" #n ")" ::: "memory")
; #define PG8_WAIT_L(n) asm volatile("s_waitcnt lgkmcnt(" #n ")" ::: "memory")
; #define PG8_BAR __builtin_amdgcn_s_barrier()
; #define PG8_SCHED __builtin_amdgcn_sched_barrier(0)
; template <class Epi, class Sched, bool SWAPD = false>
; __device__ __forceinline__ void gemm_phase(LAS unsigned char* lds, const Gemm g, const Sched& S, const Epi& E) {
;     ...
;         for (int t = 0; t < nt; t += 2) {
;             const bool last = (t == nt - 2);
;             const char* a1 = cA + (size_t)(t + 1) * kstepA;
;             const char* a2 = last ? nA : cA + (size_t)(t + 2) * kstepA; const char* b2 = last ? nB : cB + (size_t)(t + 2) * kstep;
;             const char* a3 = a2 + kstepA; const char* b3 = b2 + kstep;
;             PG8_LDB(B0, 0, 0); PG8_LDB(B1, 0, 1); PG8_SCHED; PG8_LDA(At, 0, 0); PG8_STAGE(PG8_SA(1, 1), a1 + hstepA, voffA);
;             PG8_WAIT_V(8); PG8_WAIT_L(0); PG8_BAR; PG8_MMA(0, 0, At, B0); PG8_MMA(0, 1, At, B1); PG8_BAR; PG8_SCHED;
;             PG8_LDA(At, 0, 1); PG8_STAGE(PG8_SB(0, 0), b2, voffB); PG8_STAGE(PG8_SB(0, 1), b2 + hstepB, voffB); PG8_STAGE(PG8_SA(0, 0), a2, voffA);
;             PG8_WAIT_V(8); PG8_WAIT_L(0); PG8_BAR; PG8_MMA(1, 0, At, B0); PG8_MMA(1, 1, At, B1); PG8_BAR; PG8_SCHED;
.LBB0_1044:
	ds_read_b128 v[148:151], v145
	ds_read_b128 v[152:155], v145 offset:1024
	ds_read_b128 v[156:159], v145 offset:2048
	ds_read_b128 v[160:163], v145 offset:3072
	ds_read_b128 v[164:167], v146
	ds_read_b128 v[168:171], v146 offset:1024
	ds_read_b128 v[172:175], v146 offset:2048
	ds_read_b128 v[176:179], v146 offset:3072
	s_add_u32 s44, s42, 0xfffc0080
	s_addc_u32 s45, s43, -1
	s_cmp_eq_u32 s63, 12
	s_cselect_b32 s47, s25, s45
	s_cselect_b32 s46, s27, s44
	s_cselect_b32 s45, s59, s62
	s_cselect_b32 s44, s60, s61
	v_lshl_add_u64 v[140:141], s[42:43], 0, v[132:133]
	s_add_i32 m0, s33, 0xc000
	ds_read_b128 v[180:183], v147
	ds_read_b128 v[184:187], v147 offset:1024
	ds_read_b128 v[188:191], v147 offset:2048
	ds_read_b128 v[192:195], v147 offset:3072
	ds_read_b128 v[196:199], v147 offset:4096
	ds_read_b128 v[200:203], v147 offset:5120
	ds_read_b128 v[208:211], v147 offset:6144
	ds_read_b128 v[212:215], v147 offset:7168
	global_load_lds_dwordx4 v[140:141], off
	v_lshl_add_u64 v[140:141], s[42:43], 0, v[134:135]
	s_add_i32 m0, s33, 0xe000
	s_nop 0
	global_load_lds_dwordx4 v[140:141], off
	s_waitcnt vmcnt(8)
	s_waitcnt lgkmcnt(0)
	s_barrier
	s_setprio 1
	v_mfma_f32_16x16x32_bf16 v[124:127], v[148:151], v[180:183], v[124:127]
	v_mfma_f32_16x16x32_bf16 v[116:119], v[156:159], v[180:183], v[116:119]
	v_mfma_f32_16x16x32_bf16 v[108:111], v[148:151], v[188:191], v[108:111]
	v_mfma_f32_16x16x32_bf16 v[100:103], v[156:159], v[188:191], v[100:103]
	v_mfma_f32_16x16x32_bf16 v[92:95], v[148:151], v[196:199], v[92:95]
	v_mfma_f32_16x16x32_bf16 v[84:87], v[156:159], v[196:199], v[84:87]
	v_mfma_f32_16x16x32_bf16 v[76:79], v[148:151], v[208:211], v[76:79]
	v_mfma_f32_16x16x32_bf16 v[68:71], v[156:159], v[208:211], v[68:71]
	v_mfma_f32_16x16x32_bf16 v[124:127], v[152:155], v[184:187], v[124:127]
	v_mfma_f32_16x16x32_bf16 v[116:119], v[160:163], v[184:187], v[116:119]
	v_mfma_f32_16x16x32_bf16 v[108:111], v[152:155], v[192:195], v[108:111]
	v_mfma_f32_16x16x32_bf16 v[100:103], v[160:163], v[192:195], v[100:103]
	v_mfma_f32_16x16x32_bf16 v[92:95], v[152:155], v[200:203], v[92:95]
	v_mfma_f32_16x16x32_bf16 v[84:87], v[160:163], v[200:203], v[84:87]
	v_mfma_f32_16x16x32_bf16 v[76:79], v[152:155], v[212:215], v[76:79]
	v_mfma_f32_16x16x32_bf16 v[68:71], v[160:163], v[212:215], v[68:71]
	s_setprio 0
	s_setprio 1
	v_mfma_f32_16x16x32_bf16 v[120:123], v[164:167], v[180:183], v[120:123]
	v_mfma_f32_16x16x32_bf16 v[112:115], v[172:175], v[180:183], v[112:115]
	v_mfma_f32_16x16x32_bf16 v[104:107], v[164:167], v[188:191], v[104:107]
	v_mfma_f32_16x16x32_bf16 v[96:99], v[172:175], v[188:191], v[96:99]
	v_mfma_f32_16x16x32_bf16 v[88:91], v[164:167], v[196:199], v[88:91]
	v_mfma_f32_16x16x32_bf16 v[80:83], v[172:175], v[196:199], v[80:83]
	v_mfma_f32_16x16x32_bf16 v[72:75], v[164:167], v[208:211], v[72:75]
	v_mfma_f32_16x16x32_bf16 v[64:67], v[172:175], v[208:211], v[64:67]
	v_mfma_f32_16x16x32_bf16 v[120:123], v[168:171], v[184:187], v[120:123]
	v_mfma_f32_16x16x32_bf16 v[112:115], v[176:179], v[184:187], v[112:115]
	v_mfma_f32_16x16x32_bf16 v[104:107], v[168:171], v[192:195], v[104:107]
	v_mfma_f32_16x16x32_bf16 v[96:99], v[176:179], v[192:195], v[96:99]
	v_mfma_f32_16x16x32_bf16 v[88:91], v[168:171], v[200:203], v[88:91]
	v_mfma_f32_16x16x32_bf16 v[80:83], v[176:179], v[200:203], v[80:83]
	v_mfma_f32_16x16x32_bf16 v[72:75], v[168:171], v[212:215], v[72:75]
	v_mfma_f32_16x16x32_bf16 v[64:67], v[176:179], v[212:215], v[64:67]
	s_setprio 0
	s_barrier
	s_add_i32 s64, s55, s30
	v_lshl_add_u64 v[140:141], s[44:45], 0, v[130:131]
	s_mov_b32 m0, s64
	ds_read_b128 v[180:183], v147 offset:16384
	ds_read_b128 v[184:187], v147 offset:17408
	ds_read_b128 v[188:191], v147 offset:18432
	ds_read_b128 v[192:195], v147 offset:19456
	ds_read_b128 v[196:199], v147 offset:20480
	ds_read_b128 v[200:203], v147 offset:21504
	ds_read_b128 v[208:211], v147 offset:22528
	ds_read_b128 v[212:215], v147 offset:23552
	global_load_lds_dwordx4 v[140:141], off
	s_add_i32 m0, s64, 0x2000
	s_add_u32 s64, s44, 0x40000
	v_lshl_add_u64 v[204:205], s[44:45], 0, v[128:129]
	s_addc_u32 s65, s45, 0
	s_add_i32 s66, s56, s30
	global_load_lds_dwordx4 v[204:205], off
	v_lshl_add_u64 v[216:217], s[64:65], 0, v[130:131]
	s_mov_b32 m0, s66
	v_lshl_add_u64 v[218:219], s[46:47], 0, v[128:129]
	global_load_lds_dwordx4 v[216:217], off
	v_lshl_add_u64 v[216:217], s[64:65], 0, v[128:129]
	s_add_i32 m0, s66, 0x2000
	s_nop 0
	global_load_lds_dwordx4 v[216:217], off
	v_lshl_add_u64 v[216:217], s[46:47], 0, v[130:131]
	s_mov_b32 m0, s33
	s_nop 0
	global_load_lds_dwordx4 v[216:217], off
	s_mov_b32 m0, s41
	s_nop 0
	global_load_lds_dwordx4 v[218:219], off
	s_waitcnt vmcnt(8)
	s_waitcnt lgkmcnt(0)
	s_barrier
; #define PG8_STAGE(bufoff, gbase, voff) do { _Pragma("unroll") for (int _i = 0; _i < 2; ++_i) \
;         __builtin_amdgcn_global_load_lds((const unsigned*)((const char*)(gbase) + (voff)[_i]), (LAS unsigned*)(lds + (bufoff) + ldsw + _i * 8192), 16, 0, 0); } while (0)
; #define PG8_LDA(dst, b, h) do { _Pragma("unroll") for (int m = 0; m < 4; ++m) _Pragma("unroll") for (int k = 0; k < 2; ++k) dst[m][k] = *(const LAS bf16x8*)(lds + PG8_SA(b, h) + aoff + m * 2048 + k * 1024); } while (0)
; #define PG8_LDB(dst, b, h) do { _Pragma("unroll") for (int n = 0; n < 2; ++n) _Pragma("unroll") for (int k = 0; k < 2; ++k) dst[n][k] = *(const LAS bf16x8*)(lds + PG8_SB(b, h) + boff + n * 2048 + k * 1024); } while (0)
; #define PG8_WAIT_V(n) asm volatile("s_waitcnt vmcnt(" #n ")" ::: "memory")
; #define PG8_WAIT_L(n) asm volatile("s_waitcnt lgkmcnt(" #n ")" ::: "memory")
; #define PG8_BAR __builtin_amdgcn_s_barrier()
; #define PG8_SCHED __builtin_amdgcn_sched_barrier(0)
; template <class Epi, class Sched, bool SWAPD = false>
; __device__ __forceinline__ void gemm_phase(LAS unsigned char* lds, const Gemm g, const Sched& S, const Epi& E) {
;     ...
;             PG8_WAIT_V(8); PG8_WAIT_L(0); PG8_BAR; PG8_MMA(1, 0, At, B0); PG8_MMA(1, 1, At, B1); PG8_BAR; PG8_SCHED;
;             PG8_LDB(B0, 1, 0); PG8_LDB(B1, 1, 1); PG8_SCHED; PG8_LDA(At, 1, 0); PG8_STAGE(PG8_SA(0, 1), a2 + hstepA, voffA);
;             PG8_WAIT_V(8); PG8_WAIT_L(0); PG8_BAR; PG8_MMA(0, 0, At, B0); PG8_MMA(0, 1, At, B1); PG8_BAR; PG8_SCHED;
;             PG8_LDA(At, 1, 1); PG8_STAGE(PG8_SB(1, 0), b3, voffB); PG8_STAGE(PG8_SB(1, 1), b3 + hstepB, voffB); PG8_STAGE(PG8_SA(1, 0), a3, voffA);
	s_setprio 1
	v_mfma_f32_16x16x32_bf16 v[60:63], v[148:151], v[180:183], v[60:63]
	v_mfma_f32_16x16x32_bf16 v[52:55], v[156:159], v[180:183], v[52:55]
	v_mfma_f32_16x16x32_bf16 v[44:47], v[148:151], v[188:191], v[44:47]
	v_mfma_f32_16x16x32_bf16 v[36:39], v[156:159], v[188:191], v[36:39]
	v_mfma_f32_16x16x32_bf16 v[28:31], v[148:151], v[196:199], v[28:31]
	v_mfma_f32_16x16x32_bf16 v[20:23], v[156:159], v[196:199], v[20:23]
	v_mfma_f32_16x16x32_bf16 v[12:15], v[148:151], v[208:211], v[12:15]
	v_mfma_f32_16x16x32_bf16 v[4:7], v[156:159], v[208:211], v[4:7]
	v_mfma_f32_16x16x32_bf16 v[60:63], v[152:155], v[184:187], v[60:63]
	v_mfma_f32_16x16x32_bf16 v[52:55], v[160:163], v[184:187], v[52:55]
	v_mfma_f32_16x16x32_bf16 v[44:47], v[152:155], v[192:195], v[44:47]
	v_mfma_f32_16x16x32_bf16 v[36:39], v[160:163], v[192:195], v[36:39]
	v_mfma_f32_16x16x32_bf16 v[28:31], v[152:155], v[200:203], v[28:31]
	v_mfma_f32_16x16x32_bf16 v[20:23], v[160:163], v[200:203], v[20:23]
	v_mfma_f32_16x16x32_bf16 v[12:15], v[152:155], v[212:215], v[12:15]
	v_mfma_f32_16x16x32_bf16 v[4:7], v[160:163], v[212:215], v[4:7]
	s_setprio 0
	s_setprio 1
	v_mfma_f32_16x16x32_bf16 v[56:59], v[164:167], v[180:183], v[56:59]
	v_mfma_f32_16x16x32_bf16 v[48:51], v[172:175], v[180:183], v[48:51]
	v_mfma_f32_16x16x32_bf16 v[40:43], v[164:167], v[188:191], v[40:43]
	v_mfma_f32_16x16x32_bf16 v[32:35], v[172:175], v[188:191], v[32:35]
	v_mfma_f32_16x16x32_bf16 v[24:27], v[164:167], v[196:199], v[24:27]
	v_mfma_f32_16x16x32_bf16 v[16:19], v[172:175], v[196:199], v[16:19]
	v_mfma_f32_16x16x32_bf16 v[8:11], v[164:167], v[208:211], v[8:11]
	v_mfma_f32_16x16x32_bf16 v[0:3], v[172:175], v[208:211], v[0:3]
	v_mfma_f32_16x16x32_bf16 v[56:59], v[168:171], v[184:187], v[56:59]
	v_mfma_f32_16x16x32_bf16 v[48:51], v[176:179], v[184:187], v[48:51]
	v_mfma_f32_16x16x32_bf16 v[40:43], v[168:171], v[192:195], v[40:43]
	v_mfma_f32_16x16x32_bf16 v[32:35], v[176:179], v[192:195], v[32:35]
	v_mfma_f32_16x16x32_bf16 v[24:27], v[168:171], v[200:203], v[24:27]
	v_mfma_f32_16x16x32_bf16 v[16:19], v[176:179], v[200:203], v[16:19]
	v_mfma_f32_16x16x32_bf16 v[8:11], v[168:171], v[212:215], v[8:11]
	v_mfma_f32_16x16x32_bf16 v[0:3], v[176:179], v[212:215], v[0:3]
	s_setprio 0
	s_barrier
	s_add_i32 s64, 0, 0x18000
	s_add_i32 s65, 0, 0x1c000
	v_add_u32_e32 v160, s64, v143
	v_add_u32_e32 v176, s65, v143
	ds_read_b128 v[148:151], v160
	ds_read_b128 v[152:155], v160 offset:1024
	ds_read_b128 v[156:159], v160 offset:2048
	ds_read_b128 v[160:163], v160 offset:3072
	ds_read_b128 v[164:167], v176
	ds_read_b128 v[168:171], v176 offset:1024
	ds_read_b128 v[172:175], v176 offset:2048
	ds_read_b128 v[176:179], v176 offset:3072
	s_add_u32 s46, s46, 0x40000
	s_addc_u32 s47, s47, 0
	s_mov_b32 m0, s50
	v_lshl_add_u64 v[220:221], s[46:47], 0, v[130:131]
	ds_read_b128 v[180:183], v147 offset:32768
	ds_read_b128 v[184:187], v147 offset:33792
	ds_read_b128 v[188:191], v147 offset:34816
	ds_read_b128 v[192:195], v147 offset:35840
	ds_read_b128 v[196:199], v147 offset:36864
	ds_read_b128 v[200:203], v147 offset:37888
	ds_read_b128 v[208:211], v147 offset:38912
	ds_read_b128 v[212:215], v147 offset:39936
	global_load_lds_dwordx4 v[220:221], off
	v_lshl_add_u64 v[220:221], s[46:47], 0, v[128:129]
	s_mov_b32 m0, s51
	s_nop 0
	global_load_lds_dwordx4 v[220:221], off
	s_waitcnt vmcnt(8)
	s_waitcnt lgkmcnt(0)
	s_barrier
	s_setprio 1
	v_mfma_f32_16x16x32_bf16 v[124:127], v[148:151], v[180:183], v[124:127]
	v_mfma_f32_16x16x32_bf16 v[116:119], v[156:159], v[180:183], v[116:119]
	v_mfma_f32_16x16x32_bf16 v[108:111], v[148:151], v[188:191], v[108:111]
	v_mfma_f32_16x16x32_bf16 v[100:103], v[156:159], v[188:191], v[100:103]
	v_mfma_f32_16x16x32_bf16 v[92:95], v[148:151], v[196:199], v[92:95]
	v_mfma_f32_16x16x32_bf16 v[84:87], v[156:159], v[196:199], v[84:87]
	v_mfma_f32_16x16x32_bf16 v[76:79], v[148:151], v[208:211], v[76:79]
	v_mfma_f32_16x16x32_bf16 v[68:71], v[156:159], v[208:211], v[68:71]
	v_mfma_f32_16x16x32_bf16 v[124:127], v[152:155], v[184:187], v[124:127]
	v_mfma_f32_16x16x32_bf16 v[116:119], v[160:163], v[184:187], v[116:119]
	v_mfma_f32_16x16x32_bf16 v[108:111], v[152:155], v[192:195], v[108:111]
	v_mfma_f32_16x16x32_bf16 v[100:103], v[160:163], v[192:195], v[100:103]
	v_mfma_f32_16x16x32_bf16 v[92:95], v[152:155], v[200:203], v[92:95]
	v_mfma_f32_16x16x32_bf16 v[84:87], v[160:163], v[200:203], v[84:87]
	v_mfma_f32_16x16x32_bf16 v[76:79], v[152:155], v[212:215], v[76:79]
	v_mfma_f32_16x16x32_bf16 v[68:71], v[160:163], v[212:215], v[68:71]
	s_setprio 0
	s_setprio 1
	v_mfma_f32_16x16x32_bf16 v[120:123], v[164:167], v[180:183], v[120:123]
	v_mfma_f32_16x16x32_bf16 v[112:115], v[172:175], v[180:183], v[112:115]
	v_mfma_f32_16x16x32_bf16 v[104:107], v[164:167], v[188:191], v[104:107]
	v_mfma_f32_16x16x32_bf16 v[96:99], v[172:175], v[188:191], v[96:99]
	v_mfma_f32_16x16x32_bf16 v[88:91], v[164:167], v[196:199], v[88:91]
	v_mfma_f32_16x16x32_bf16 v[80:83], v[172:175], v[196:199], v[80:83]
	v_mfma_f32_16x16x32_bf16 v[72:75], v[164:167], v[208:211], v[72:75]
	v_mfma_f32_16x16x32_bf16 v[64:67], v[172:175], v[208:211], v[64:67]
	v_mfma_f32_16x16x32_bf16 v[120:123], v[168:171], v[184:187], v[120:123]
	v_mfma_f32_16x16x32_bf16 v[112:115], v[176:179], v[184:187], v[112:115]
	v_mfma_f32_16x16x32_bf16 v[104:107], v[168:171], v[192:195], v[104:107]
	v_mfma_f32_16x16x32_bf16 v[96:99], v[176:179], v[192:195], v[96:99]
	v_mfma_f32_16x16x32_bf16 v[88:91], v[168:171], v[200:203], v[88:91]
	v_mfma_f32_16x16x32_bf16 v[80:83], v[176:179], v[200:203], v[80:83]
	v_mfma_f32_16x16x32_bf16 v[72:75], v[168:171], v[212:215], v[72:75]
	v_mfma_f32_16x16x32_bf16 v[64:67], v[176:179], v[212:215], v[64:67]
	s_setprio 0
	s_barrier
; #define PG8_STAGE(bufoff, gbase, voff) do { _Pragma("unroll") for (int _i = 0; _i < 2; ++_i) \
;         __builtin_amdgcn_global_load_lds((const unsigned*)((const char*)(gbase) + (voff)[_i]), (LAS unsigned*)(lds + (bufoff) + ldsw + _i * 8192), 16, 0, 0); } while (0)
; #define PG8_LDA(dst, b, h) do { _Pragma("unroll") for (int m = 0; m < 4; ++m) _Pragma("unroll") for (int k = 0; k < 2; ++k) dst[m][k] = *(const LAS bf16x8*)(lds + PG8_SA(b, h) + aoff + m * 2048 + k * 1024); } while (0)
; #define PG8_WAIT_V(n) asm volatile("s_waitcnt vmcnt(" #n ")" ::: "memory")
; #define PG8_WAIT_L(n) asm volatile("s_waitcnt lgkmcnt(" #n ")" ::: "memory")
; #define PG8_BAR __builtin_amdgcn_s_barrier()
; #define PG8_SCHED __builtin_amdgcn_sched_barrier(0)
; template <class Epi, class Sched, bool SWAPD = false>
; __device__ __forceinline__ void gemm_phase(LAS unsigned char* lds, const Gemm g, const Sched& S, const Epi& E) {
;     ...
;             PG8_WAIT_V(8); PG8_WAIT_L(0); PG8_BAR; PG8_MMA(0, 0, At, B0); PG8_MMA(0, 1, At, B1); PG8_BAR; PG8_SCHED;
;             PG8_LDA(At, 1, 1); PG8_STAGE(PG8_SB(1, 0), b3, voffB); PG8_STAGE(PG8_SB(1, 1), b3 + hstepB, voffB); PG8_STAGE(PG8_SA(1, 0), a3, voffA);
;             PG8_WAIT_V(8); PG8_WAIT_L(0); PG8_BAR; PG8_MMA(1, 0, At, B0); PG8_MMA(1, 1, At, B1); PG8_BAR; PG8_SCHED;
;         }
	s_add_i32 s46, s64, s30
	v_lshl_add_u64 v[140:141], v[140:141], 0, s[8:9]
	s_mov_b32 m0, s46
	ds_read_b128 v[180:183], v147 offset:49152
	ds_read_b128 v[184:187], v147 offset:50176
	ds_read_b128 v[188:191], v147 offset:51200
	ds_read_b128 v[192:195], v147 offset:52224
	ds_read_b128 v[196:199], v147 offset:53248
	ds_read_b128 v[200:203], v147 offset:54272
	ds_read_b128 v[208:211], v147 offset:55296
	ds_read_b128 v[212:215], v147 offset:56320
	global_load_lds_dwordx4 v[140:141], off
	s_add_i32 m0, s46, 0x2000
	s_add_u32 s44, s44, 0x40080
	v_lshl_add_u64 v[140:141], v[204:205], 0, s[8:9]
	s_addc_u32 s45, s45, 0
	s_add_i32 s46, s65, s30
	global_load_lds_dwordx4 v[140:141], off
	v_lshl_add_u64 v[140:141], s[44:45], 0, v[130:131]
	s_mov_b32 m0, s46
	s_nop 0
	global_load_lds_dwordx4 v[140:141], off
	v_lshl_add_u64 v[140:141], s[44:45], 0, v[128:129]
	s_add_i32 m0, s46, 0x2000
	s_nop 0
	global_load_lds_dwordx4 v[140:141], off
	v_lshl_add_u64 v[140:141], v[216:217], 0, s[8:9]
	s_mov_b32 m0, s53
	s_nop 0
	global_load_lds_dwordx4 v[140:141], off
	v_lshl_add_u64 v[140:141], v[218:219], 0, s[8:9]
	s_mov_b32 m0, s54
	s_nop 0
	global_load_lds_dwordx4 v[140:141], off
	s_waitcnt vmcnt(8)
	s_waitcnt lgkmcnt(0)
	s_barrier
	s_setprio 1
	v_mfma_f32_16x16x32_bf16 v[60:63], v[148:151], v[180:183], v[60:63]
	v_mfma_f32_16x16x32_bf16 v[52:55], v[156:159], v[180:183], v[52:55]
	v_mfma_f32_16x16x32_bf16 v[44:47], v[148:151], v[188:191], v[44:47]
	v_mfma_f32_16x16x32_bf16 v[36:39], v[156:159], v[188:191], v[36:39]
	v_mfma_f32_16x16x32_bf16 v[28:31], v[148:151], v[196:199], v[28:31]
	v_mfma_f32_16x16x32_bf16 v[20:23], v[156:159], v[196:199], v[20:23]
	v_mfma_f32_16x16x32_bf16 v[12:15], v[148:151], v[208:211], v[12:15]
	v_mfma_f32_16x16x32_bf16 v[4:7], v[156:159], v[208:211], v[4:7]
	v_mfma_f32_16x16x32_bf16 v[60:63], v[152:155], v[184:187], v[60:63]
	v_mfma_f32_16x16x32_bf16 v[52:55], v[160:163], v[184:187], v[52:55]
	v_mfma_f32_16x16x32_bf16 v[44:47], v[152:155], v[192:195], v[44:47]
	v_mfma_f32_16x16x32_bf16 v[36:39], v[160:163], v[192:195], v[36:39]
	v_mfma_f32_16x16x32_bf16 v[28:31], v[152:155], v[200:203], v[28:31]
	v_mfma_f32_16x16x32_bf16 v[20:23], v[160:163], v[200:203], v[20:23]
	v_mfma_f32_16x16x32_bf16 v[12:15], v[152:155], v[212:215], v[12:15]
	v_mfma_f32_16x16x32_bf16 v[4:7], v[160:163], v[212:215], v[4:7]
	s_setprio 0
	s_setprio 1
	v_mfma_f32_16x16x32_bf16 v[56:59], v[164:167], v[180:183], v[56:59]
	v_mfma_f32_16x16x32_bf16 v[48:51], v[172:175], v[180:183], v[48:51]
	v_mfma_f32_16x16x32_bf16 v[40:43], v[164:167], v[188:191], v[40:43]
	v_mfma_f32_16x16x32_bf16 v[32:35], v[172:175], v[188:191], v[32:35]
	v_mfma_f32_16x16x32_bf16 v[24:27], v[164:167], v[196:199], v[24:27]
	v_mfma_f32_16x16x32_bf16 v[16:19], v[172:175], v[196:199], v[16:19]
	v_mfma_f32_16x16x32_bf16 v[8:11], v[164:167], v[208:211], v[8:11]
	v_mfma_f32_16x16x32_bf16 v[0:3], v[172:175], v[208:211], v[0:3]
	v_mfma_f32_16x16x32_bf16 v[56:59], v[168:171], v[184:187], v[56:59]
	v_mfma_f32_16x16x32_bf16 v[48:51], v[176:179], v[184:187], v[48:51]
	v_mfma_f32_16x16x32_bf16 v[40:43], v[168:171], v[192:195], v[40:43]
	v_mfma_f32_16x16x32_bf16 v[32:35], v[176:179], v[192:195], v[32:35]
	v_mfma_f32_16x16x32_bf16 v[24:27], v[168:171], v[200:203], v[24:27]
	v_mfma_f32_16x16x32_bf16 v[16:19], v[176:179], v[200:203], v[16:19]
	v_mfma_f32_16x16x32_bf16 v[8:11], v[168:171], v[212:215], v[8:11]
	v_mfma_f32_16x16x32_bf16 v[0:3], v[176:179], v[212:215], v[0:3]
	s_setprio 0
	s_add_i32 s63, s63, 2
	s_add_u32 s42, s42, 0x100
	s_addc_u32 s43, s43, 0
	s_add_u32 s61, s61, 0x100
	s_addc_u32 s62, s62, 0
	s_cmp_gt_u32 s63, 13
	s_barrier
	s_cbranch_scc0 .LBB0_1044
	s_and_b64 vcc, exec, s[12:13]
	s_cbranch_vccz .LBB0_1047
	s_barrier

; #define PG8_STAGE(bufoff, gbase, voff) do { _Pragma("unroll") for (int _i = 0; _i < 2; ++_i) \
;         __builtin_amdgcn_global_load_lds((const unsigned*)((const char*)(gbase) + (voff)[_i]), (LAS unsigned*)(lds + (bufoff) + ldsw + _i * 8192), 16, 0, 0); } while (0)
; #define PG8_LDA(dst, b, h) do { _Pragma("unroll") for (int m = 0; m < 4; ++m) _Pragma("unroll") for (int k = 0; k < 2; ++k) dst[m][k] = *(const LAS bf16x8*)(lds + PG8_SA(b, h) + aoff + m * 2048 + k * 1024); } while (0)
; #define PG8_LDB(dst, b, h) do { _Pragma("unroll") for (int n = 0; n < 2; ++n) _Pragma("unroll") for (int k = 0; k < 2; ++k) dst[n][k] = *(const LAS bf16x8*)(lds + PG8_SB(b, h) + boff + n * 2048 + k * 1024); } while (0)
; #define PG8_WAIT_V(n) asm volatile("s_waitcnt vmcnt(" #n ")" ::: "memory")
; #define PG8_WAIT_L(n) asm volatile("s_waitcnt lgkmcnt(" #n ")" ::: "memory")
; #define PG8_BAR __builtin_amdgcn_s_barrier()
; #define PG8_SCHED __builtin_amdgcn_sched_barrier(0)
; template <class Epi, class Sched, bool SWAPD = false>
; __device__ __forceinline__ void gemm_phase(LAS unsigned char* lds, const Gemm g, const Sched& S, const Epi& E) {
;     ...
;         for (int t = 0; t < nt; t += 2) {
;             const bool last = (t == nt - 2);
;             const char* a1 = cA + (size_t)(t + 1) * kstepA;
;             const char* a2 = last ? nA : cA + (size_t)(t + 2) * kstepA; const char* b2 = last ? nB : cB + (size_t)(t + 2) * kstep;
;             const char* a3 = a2 + kstepA; const char* b3 = b2 + kstep;
;             PG8_LDB(B0, 0, 0); PG8_LDB(B1, 0, 1); PG8_SCHED; PG8_LDA(At, 0, 0); PG8_STAGE(PG8_SA(1, 1), a1 + hstepA, voffA);
;             PG8_WAIT_V(8); PG8_WAIT_L(0); PG8_BAR; PG8_MMA(0, 0, At, B0); PG8_MMA(0, 1, At, B1); PG8_BAR; PG8_SCHED;
;             PG8_LDA(At, 0, 1); PG8_STAGE(PG8_SB(0, 0), b2, voffB); PG8_STAGE(PG8_SB(0, 1), b2 + hstepB, voffB); PG8_STAGE(PG8_SA(0, 0), a2, voffA);
;             PG8_WAIT_V(8); PG8_WAIT_L(0); PG8_BAR; PG8_MMA(1, 0, At, B0); PG8_MMA(1, 1, At, B1); PG8_BAR; PG8_SCHED;
.LBB0_1121:
	ds_read_b128 v[128:131], v210
	ds_read_b128 v[132:135], v210 offset:1024
	ds_read_b128 v[136:139], v210 offset:2048
	ds_read_b128 v[140:143], v210 offset:3072
	ds_read_b128 v[144:147], v211
	ds_read_b128 v[148:151], v211 offset:1024
	ds_read_b128 v[152:155], v211 offset:2048
	ds_read_b128 v[156:159], v211 offset:3072
	s_add_u32 s36, s34, 0x100
	s_addc_u32 s37, s35, 0
	s_cmp_eq_u32 s64, 40
	s_cselect_b32 s41, s58, s37
	s_cselect_b32 s40, s59, s36
	s_cselect_b32 s39, s60, s63
	s_cselect_b32 s38, s61, s62
	v_lshl_add_u64 v[204:205], s[34:35], 0, v[180:181]
	s_add_i32 m0, s33, 0xc000
	ds_read_b128 v[188:191], v212
	ds_read_b128 v[192:195], v212 offset:1024
	ds_read_b128 v[196:199], v212 offset:2048
	ds_read_b128 v[200:203], v212 offset:3072
	ds_read_b128 v[214:217], v212 offset:4096
	ds_read_b128 v[218:221], v212 offset:5120
	ds_read_b128 v[222:225], v212 offset:6144
	ds_read_b128 v[226:229], v212 offset:7168
	global_load_lds_dwordx4 v[204:205], off
	v_lshl_add_u64 v[204:205], s[34:35], 0, v[182:183]
	s_add_i32 m0, s33, 0xe000
	s_nop 0
	global_load_lds_dwordx4 v[204:205], off
	s_waitcnt vmcnt(8)
	s_waitcnt lgkmcnt(0)
	s_barrier
	s_setprio 1
	v_mfma_f32_16x16x32_bf16 v[124:127], v[128:131], v[188:191], v[124:127]
	v_mfma_f32_16x16x32_bf16 v[120:123], v[136:139], v[188:191], v[120:123]
	v_mfma_f32_16x16x32_bf16 v[116:119], v[128:131], v[196:199], v[116:119]
	v_mfma_f32_16x16x32_bf16 v[112:115], v[136:139], v[196:199], v[112:115]
	v_mfma_f32_16x16x32_bf16 v[92:95], v[128:131], v[214:217], v[92:95]
	v_mfma_f32_16x16x32_bf16 v[88:91], v[136:139], v[214:217], v[88:91]
	v_mfma_f32_16x16x32_bf16 v[76:79], v[128:131], v[222:225], v[76:79]
	v_mfma_f32_16x16x32_bf16 v[72:75], v[136:139], v[222:225], v[72:75]
	v_mfma_f32_16x16x32_bf16 v[124:127], v[132:135], v[192:195], v[124:127]
	v_mfma_f32_16x16x32_bf16 v[120:123], v[140:143], v[192:195], v[120:123]
	v_mfma_f32_16x16x32_bf16 v[116:119], v[132:135], v[200:203], v[116:119]
	v_mfma_f32_16x16x32_bf16 v[112:115], v[140:143], v[200:203], v[112:115]
	v_mfma_f32_16x16x32_bf16 v[92:95], v[132:135], v[218:221], v[92:95]
	v_mfma_f32_16x16x32_bf16 v[88:91], v[140:143], v[218:221], v[88:91]
	v_mfma_f32_16x16x32_bf16 v[76:79], v[132:135], v[226:229], v[76:79]
	v_mfma_f32_16x16x32_bf16 v[72:75], v[140:143], v[226:229], v[72:75]
	s_setprio 0
	s_setprio 1
	v_mfma_f32_16x16x32_bf16 v[108:111], v[144:147], v[188:191], v[108:111]
	v_mfma_f32_16x16x32_bf16 v[104:107], v[152:155], v[188:191], v[104:107]
	v_mfma_f32_16x16x32_bf16 v[100:103], v[144:147], v[196:199], v[100:103]
	v_mfma_f32_16x16x32_bf16 v[96:99], v[152:155], v[196:199], v[96:99]
	v_mfma_f32_16x16x32_bf16 v[84:87], v[144:147], v[214:217], v[84:87]
	v_mfma_f32_16x16x32_bf16 v[80:83], v[152:155], v[214:217], v[80:83]
	v_mfma_f32_16x16x32_bf16 v[68:71], v[144:147], v[222:225], v[68:71]
	v_mfma_f32_16x16x32_bf16 v[64:67], v[152:155], v[222:225], v[64:67]
	v_mfma_f32_16x16x32_bf16 v[108:111], v[148:151], v[192:195], v[108:111]
	v_mfma_f32_16x16x32_bf16 v[104:107], v[156:159], v[192:195], v[104:107]
	v_mfma_f32_16x16x32_bf16 v[100:103], v[148:151], v[200:203], v[100:103]
	v_mfma_f32_16x16x32_bf16 v[96:99], v[156:159], v[200:203], v[96:99]
	v_mfma_f32_16x16x32_bf16 v[84:87], v[148:151], v[218:221], v[84:87]
	v_mfma_f32_16x16x32_bf16 v[80:83], v[156:159], v[218:221], v[80:83]
	v_mfma_f32_16x16x32_bf16 v[68:71], v[148:151], v[226:229], v[68:71]
	v_mfma_f32_16x16x32_bf16 v[64:67], v[156:159], v[226:229], v[64:67]
	s_setprio 0
	s_barrier
	s_add_i32 s34, s52, s31
	v_lshl_add_u64 v[204:205], s[38:39], 0, v[160:161]
	s_mov_b32 m0, s34
	ds_read_b128 v[188:191], v212 offset:16384
	ds_read_b128 v[192:195], v212 offset:17408
	ds_read_b128 v[196:199], v212 offset:18432
	ds_read_b128 v[200:203], v212 offset:19456
	ds_read_b128 v[214:217], v212 offset:20480
	ds_read_b128 v[218:221], v212 offset:21504
	ds_read_b128 v[222:225], v212 offset:22528
	ds_read_b128 v[226:229], v212 offset:23552
	global_load_lds_dwordx4 v[204:205], off
	s_add_i32 m0, s34, 0x2000
	s_add_u32 s34, s38, 0xb0000
	v_lshl_add_u64 v[230:231], s[38:39], 0, v[162:163]
	s_addc_u32 s35, s39, 0
	s_add_i32 s65, s53, s31
	global_load_lds_dwordx4 v[230:231], off
	v_lshl_add_u64 v[232:233], s[34:35], 0, v[160:161]
	s_mov_b32 m0, s65
	v_lshl_add_u64 v[234:235], s[40:41], 0, v[162:163]
	global_load_lds_dwordx4 v[232:233], off
	v_lshl_add_u64 v[232:233], s[34:35], 0, v[162:163]
	s_add_i32 m0, s65, 0x2000
	s_nop 0
	global_load_lds_dwordx4 v[232:233], off
	v_lshl_add_u64 v[232:233], s[40:41], 0, v[160:161]
	s_mov_b32 m0, s33
	s_nop 0
	global_load_lds_dwordx4 v[232:233], off
	s_mov_b32 m0, s42
	s_nop 0
	global_load_lds_dwordx4 v[234:235], off
	s_waitcnt vmcnt(8)
	s_waitcnt lgkmcnt(0)
	s_barrier
; #define PG8_STAGE(bufoff, gbase, voff) do { _Pragma("unroll") for (int _i = 0; _i < 2; ++_i) \
;         __builtin_amdgcn_global_load_lds((const unsigned*)((const char*)(gbase) + (voff)[_i]), (LAS unsigned*)(lds + (bufoff) + ldsw + _i * 8192), 16, 0, 0); } while (0)
; #define PG8_LDA(dst, b, h) do { _Pragma("unroll") for (int m = 0; m < 4; ++m) _Pragma("unroll") for (int k = 0; k < 2; ++k) dst[m][k] = *(const LAS bf16x8*)(lds + PG8_SA(b, h) + aoff + m * 2048 + k * 1024); } while (0)
; #define PG8_LDB(dst, b, h) do { _Pragma("unroll") for (int n = 0; n < 2; ++n) _Pragma("unroll") for (int k = 0; k < 2; ++k) dst[n][k] = *(const LAS bf16x8*)(lds + PG8_SB(b, h) + boff + n * 2048 + k * 1024); } while (0)
; #define PG8_WAIT_V(n) asm volatile("s_waitcnt vmcnt(" #n ")" ::: "memory")
; #define PG8_WAIT_L(n) asm volatile("s_waitcnt lgkmcnt(" #n ")" ::: "memory")
; #define PG8_BAR __builtin_amdgcn_s_barrier()
; #define PG8_SCHED __builtin_amdgcn_sched_barrier(0)
; template <class Epi, class Sched, bool SWAPD = false>
; __device__ __forceinline__ void gemm_phase(LAS unsigned char* lds, const Gemm g, const Sched& S, const Epi& E) {
;     ...
;             PG8_WAIT_V(8); PG8_WAIT_L(0); PG8_BAR; PG8_MMA(1, 0, At, B0); PG8_MMA(1, 1, At, B1); PG8_BAR; PG8_SCHED;
;             PG8_LDB(B0, 1, 0); PG8_LDB(B1, 1, 1); PG8_SCHED; PG8_LDA(At, 1, 0); PG8_STAGE(PG8_SA(0, 1), a2 + hstepA, voffA);
;             PG8_WAIT_V(8); PG8_WAIT_L(0); PG8_BAR; PG8_MMA(0, 0, At, B0); PG8_MMA(0, 1, At, B1); PG8_BAR; PG8_SCHED;
	s_setprio 1
	v_mfma_f32_16x16x32_bf16 v[60:63], v[128:131], v[188:191], v[60:63]
	v_mfma_f32_16x16x32_bf16 v[56:59], v[136:139], v[188:191], v[56:59]
	v_mfma_f32_16x16x32_bf16 v[44:47], v[128:131], v[196:199], v[44:47]
	v_mfma_f32_16x16x32_bf16 v[40:43], v[136:139], v[196:199], v[40:43]
	v_mfma_f32_16x16x32_bf16 v[36:39], v[128:131], v[214:217], v[36:39]
	v_mfma_f32_16x16x32_bf16 v[32:35], v[136:139], v[214:217], v[32:35]
	v_mfma_f32_16x16x32_bf16 v[20:23], v[128:131], v[222:225], v[20:23]
	v_mfma_f32_16x16x32_bf16 v[16:19], v[136:139], v[222:225], v[16:19]
	v_mfma_f32_16x16x32_bf16 v[60:63], v[132:135], v[192:195], v[60:63]
	v_mfma_f32_16x16x32_bf16 v[56:59], v[140:143], v[192:195], v[56:59]
	v_mfma_f32_16x16x32_bf16 v[44:47], v[132:135], v[200:203], v[44:47]
	v_mfma_f32_16x16x32_bf16 v[40:43], v[140:143], v[200:203], v[40:43]
	v_mfma_f32_16x16x32_bf16 v[36:39], v[132:135], v[218:221], v[36:39]
	v_mfma_f32_16x16x32_bf16 v[32:35], v[140:143], v[218:221], v[32:35]
	v_mfma_f32_16x16x32_bf16 v[20:23], v[132:135], v[226:229], v[20:23]
	v_mfma_f32_16x16x32_bf16 v[16:19], v[140:143], v[226:229], v[16:19]
	s_setprio 0
	s_setprio 1
	v_mfma_f32_16x16x32_bf16 v[52:55], v[144:147], v[188:191], v[52:55]
	v_mfma_f32_16x16x32_bf16 v[48:51], v[152:155], v[188:191], v[48:51]
	v_mfma_f32_16x16x32_bf16 v[28:31], v[144:147], v[196:199], v[28:31]
	v_mfma_f32_16x16x32_bf16 v[24:27], v[152:155], v[196:199], v[24:27]
	v_mfma_f32_16x16x32_bf16 v[12:15], v[144:147], v[214:217], v[12:15]
	v_mfma_f32_16x16x32_bf16 v[8:11], v[152:155], v[214:217], v[8:11]
	v_mfma_f32_16x16x32_bf16 v[4:7], v[144:147], v[222:225], v[4:7]
	v_mfma_f32_16x16x32_bf16 v[0:3], v[152:155], v[222:225], v[0:3]
	v_mfma_f32_16x16x32_bf16 v[52:55], v[148:151], v[192:195], v[52:55]
	v_mfma_f32_16x16x32_bf16 v[48:51], v[156:159], v[192:195], v[48:51]
	v_mfma_f32_16x16x32_bf16 v[28:31], v[148:151], v[200:203], v[28:31]
	v_mfma_f32_16x16x32_bf16 v[24:27], v[156:159], v[200:203], v[24:27]
	v_mfma_f32_16x16x32_bf16 v[12:15], v[148:151], v[218:221], v[12:15]
	v_mfma_f32_16x16x32_bf16 v[8:11], v[156:159], v[218:221], v[8:11]
	v_mfma_f32_16x16x32_bf16 v[4:7], v[148:151], v[226:229], v[4:7]
	v_mfma_f32_16x16x32_bf16 v[0:3], v[156:159], v[226:229], v[0:3]
	s_setprio 0
	s_barrier
	s_add_i32 s65, 0, 0x18000
	s_add_i32 s66, 0, 0x1c000
	v_add_u32_e32 v140, s65, v208
	v_add_u32_e32 v156, s66, v208
	ds_read_b128 v[128:131], v140
	ds_read_b128 v[132:135], v140 offset:1024
	ds_read_b128 v[136:139], v140 offset:2048
	ds_read_b128 v[140:143], v140 offset:3072
	ds_read_b128 v[144:147], v156
	ds_read_b128 v[148:151], v156 offset:1024
	ds_read_b128 v[152:155], v156 offset:2048
	ds_read_b128 v[156:159], v156 offset:3072
	s_add_u32 s34, s40, 0xb0000
	s_addc_u32 s35, s41, 0
	s_mov_b32 m0, s43
	v_lshl_add_u64 v[236:237], s[34:35], 0, v[160:161]
	ds_read_b128 v[188:191], v212 offset:32768
	ds_read_b128 v[192:195], v212 offset:33792
	ds_read_b128 v[196:199], v212 offset:34816
	ds_read_b128 v[200:203], v212 offset:35840
	ds_read_b128 v[214:217], v212 offset:36864
	ds_read_b128 v[218:221], v212 offset:37888
	ds_read_b128 v[222:225], v212 offset:38912
	ds_read_b128 v[226:229], v212 offset:39936
	global_load_lds_dwordx4 v[236:237], off
	v_lshl_add_u64 v[236:237], s[34:35], 0, v[162:163]
	s_mov_b32 m0, s44
	s_nop 0
	global_load_lds_dwordx4 v[236:237], off
	s_waitcnt vmcnt(8)
	s_waitcnt lgkmcnt(0)
	s_barrier
	s_setprio 1
	v_mfma_f32_16x16x32_bf16 v[124:127], v[128:131], v[188:191], v[124:127]
	v_mfma_f32_16x16x32_bf16 v[120:123], v[136:139], v[188:191], v[120:123]
	v_mfma_f32_16x16x32_bf16 v[116:119], v[128:131], v[196:199], v[116:119]
	v_mfma_f32_16x16x32_bf16 v[112:115], v[136:139], v[196:199], v[112:115]
	v_mfma_f32_16x16x32_bf16 v[92:95], v[128:131], v[214:217], v[92:95]
	v_mfma_f32_16x16x32_bf16 v[88:91], v[136:139], v[214:217], v[88:91]
	v_mfma_f32_16x16x32_bf16 v[76:79], v[128:131], v[222:225], v[76:79]
	v_mfma_f32_16x16x32_bf16 v[72:75], v[136:139], v[222:225], v[72:75]
	v_mfma_f32_16x16x32_bf16 v[124:127], v[132:135], v[192:195], v[124:127]
	v_mfma_f32_16x16x32_bf16 v[120:123], v[140:143], v[192:195], v[120:123]
	v_mfma_f32_16x16x32_bf16 v[116:119], v[132:135], v[200:203], v[116:119]
	v_mfma_f32_16x16x32_bf16 v[112:115], v[140:143], v[200:203], v[112:115]
	v_mfma_f32_16x16x32_bf16 v[92:95], v[132:135], v[218:221], v[92:95]
	v_mfma_f32_16x16x32_bf16 v[88:91], v[140:143], v[218:221], v[88:91]
	v_mfma_f32_16x16x32_bf16 v[76:79], v[132:135], v[226:229], v[76:79]
	v_mfma_f32_16x16x32_bf16 v[72:75], v[140:143], v[226:229], v[72:75]
	s_setprio 0
	s_setprio 1
	v_mfma_f32_16x16x32_bf16 v[108:111], v[144:147], v[188:191], v[108:111]
	v_mfma_f32_16x16x32_bf16 v[104:107], v[152:155], v[188:191], v[104:107]
	v_mfma_f32_16x16x32_bf16 v[100:103], v[144:147], v[196:199], v[100:103]
	v_mfma_f32_16x16x32_bf16 v[96:99], v[152:155], v[196:199], v[96:99]
	v_mfma_f32_16x16x32_bf16 v[84:87], v[144:147], v[214:217], v[84:87]
	v_mfma_f32_16x16x32_bf16 v[80:83], v[152:155], v[214:217], v[80:83]
	v_mfma_f32_16x16x32_bf16 v[68:71], v[144:147], v[222:225], v[68:71]
	v_mfma_f32_16x16x32_bf16 v[64:67], v[152:155], v[222:225], v[64:67]
	v_mfma_f32_16x16x32_bf16 v[108:111], v[148:151], v[192:195], v[108:111]
	v_mfma_f32_16x16x32_bf16 v[104:107], v[156:159], v[192:195], v[104:107]
	v_mfma_f32_16x16x32_bf16 v[100:103], v[148:151], v[200:203], v[100:103]
	v_mfma_f32_16x16x32_bf16 v[96:99], v[156:159], v[200:203], v[96:99]
	v_mfma_f32_16x16x32_bf16 v[84:87], v[148:151], v[218:221], v[84:87]
	v_mfma_f32_16x16x32_bf16 v[80:83], v[156:159], v[218:221], v[80:83]
	v_mfma_f32_16x16x32_bf16 v[68:71], v[148:151], v[226:229], v[68:71]
	v_mfma_f32_16x16x32_bf16 v[64:67], v[156:159], v[226:229], v[64:67]
	s_setprio 0
	s_barrier
; #define PG8_STAGE(bufoff, gbase, voff) do { _Pragma("unroll") for (int _i = 0; _i < 2; ++_i) \
;         __builtin_amdgcn_global_load_lds((const unsigned*)((const char*)(gbase) + (voff)[_i]), (LAS unsigned*)(lds + (bufoff) + ldsw + _i * 8192), 16, 0, 0); } while (0)
; #define PG8_LDA(dst, b, h) do { _Pragma("unroll") for (int m = 0; m < 4; ++m) _Pragma("unroll") for (int k = 0; k < 2; ++k) dst[m][k] = *(const LAS bf16x8*)(lds + PG8_SA(b, h) + aoff + m * 2048 + k * 1024); } while (0)
; #define PG8_WAIT_V(n) asm volatile("s_waitcnt vmcnt(" #n ")" ::: "memory")
; #define PG8_WAIT_L(n) asm volatile("s_waitcnt lgkmcnt(" #n ")" ::: "memory")
; #define PG8_BAR __builtin_amdgcn_s_barrier()
; #define PG8_SCHED __builtin_amdgcn_sched_barrier(0)
; template <class Epi, class Sched, bool SWAPD = false>
; __device__ __forceinline__ void gemm_phase(LAS unsigned char* lds, const Gemm g, const Sched& S, const Epi& E) {
;     ...
;             PG8_LDA(At, 1, 1); PG8_STAGE(PG8_SB(1, 0), b3, voffB); PG8_STAGE(PG8_SB(1, 1), b3 + hstepB, voffB); PG8_STAGE(PG8_SA(1, 0), a3, voffA);
;             PG8_WAIT_V(8); PG8_WAIT_L(0); PG8_BAR; PG8_MMA(1, 0, At, B0); PG8_MMA(1, 1, At, B1); PG8_BAR; PG8_SCHED;
;         }
	s_add_i32 s34, s65, s31
	v_lshl_add_u64 v[204:205], v[204:205], 0, s[8:9]
	s_mov_b32 m0, s34
	ds_read_b128 v[188:191], v212 offset:49152
	ds_read_b128 v[192:195], v212 offset:50176
	ds_read_b128 v[196:199], v212 offset:51200
	ds_read_b128 v[200:203], v212 offset:52224
	ds_read_b128 v[214:217], v212 offset:53248
	ds_read_b128 v[218:221], v212 offset:54272
	ds_read_b128 v[222:225], v212 offset:55296
	ds_read_b128 v[226:229], v212 offset:56320
	global_load_lds_dwordx4 v[204:205], off
	s_add_i32 m0, s34, 0x2000
	s_add_u32 s34, s38, 0xb0080
	v_lshl_add_u64 v[204:205], v[230:231], 0, s[8:9]
	s_addc_u32 s35, s39, 0
	s_add_i32 s38, s66, s31
	global_load_lds_dwordx4 v[204:205], off
	v_lshl_add_u64 v[204:205], s[34:35], 0, v[160:161]
	s_mov_b32 m0, s38
	s_nop 0
	global_load_lds_dwordx4 v[204:205], off
	v_lshl_add_u64 v[204:205], s[34:35], 0, v[162:163]
	s_add_i32 m0, s38, 0x2000
	s_nop 0
	global_load_lds_dwordx4 v[204:205], off
	v_lshl_add_u64 v[204:205], v[232:233], 0, s[8:9]
	s_mov_b32 m0, s50
	s_nop 0
	global_load_lds_dwordx4 v[204:205], off
	v_lshl_add_u64 v[204:205], v[234:235], 0, s[8:9]
	s_mov_b32 m0, s51
	s_nop 0
	global_load_lds_dwordx4 v[204:205], off
	s_waitcnt vmcnt(8)
	s_waitcnt lgkmcnt(0)
	s_barrier
	s_setprio 1
	v_mfma_f32_16x16x32_bf16 v[60:63], v[128:131], v[188:191], v[60:63]
	v_mfma_f32_16x16x32_bf16 v[56:59], v[136:139], v[188:191], v[56:59]
	v_mfma_f32_16x16x32_bf16 v[44:47], v[128:131], v[196:199], v[44:47]
	v_mfma_f32_16x16x32_bf16 v[40:43], v[136:139], v[196:199], v[40:43]
	v_mfma_f32_16x16x32_bf16 v[36:39], v[128:131], v[214:217], v[36:39]
	v_mfma_f32_16x16x32_bf16 v[32:35], v[136:139], v[214:217], v[32:35]
	v_mfma_f32_16x16x32_bf16 v[20:23], v[128:131], v[222:225], v[20:23]
	v_mfma_f32_16x16x32_bf16 v[16:19], v[136:139], v[222:225], v[16:19]
	v_mfma_f32_16x16x32_bf16 v[60:63], v[132:135], v[192:195], v[60:63]
	v_mfma_f32_16x16x32_bf16 v[56:59], v[140:143], v[192:195], v[56:59]
	v_mfma_f32_16x16x32_bf16 v[44:47], v[132:135], v[200:203], v[44:47]
	v_mfma_f32_16x16x32_bf16 v[40:43], v[140:143], v[200:203], v[40:43]
	v_mfma_f32_16x16x32_bf16 v[36:39], v[132:135], v[218:221], v[36:39]
	v_mfma_f32_16x16x32_bf16 v[32:35], v[140:143], v[218:221], v[32:35]
	v_mfma_f32_16x16x32_bf16 v[20:23], v[132:135], v[226:229], v[20:23]
	v_mfma_f32_16x16x32_bf16 v[16:19], v[140:143], v[226:229], v[16:19]
	s_setprio 0
	s_setprio 1
	v_mfma_f32_16x16x32_bf16 v[52:55], v[144:147], v[188:191], v[52:55]
	v_mfma_f32_16x16x32_bf16 v[48:51], v[152:155], v[188:191], v[48:51]
	v_mfma_f32_16x16x32_bf16 v[28:31], v[144:147], v[196:199], v[28:31]
	v_mfma_f32_16x16x32_bf16 v[24:27], v[152:155], v[196:199], v[24:27]
	v_mfma_f32_16x16x32_bf16 v[12:15], v[144:147], v[214:217], v[12:15]
	v_mfma_f32_16x16x32_bf16 v[8:11], v[152:155], v[214:217], v[8:11]
	v_mfma_f32_16x16x32_bf16 v[4:7], v[144:147], v[222:225], v[4:7]
	v_mfma_f32_16x16x32_bf16 v[0:3], v[152:155], v[222:225], v[0:3]
	v_mfma_f32_16x16x32_bf16 v[52:55], v[148:151], v[192:195], v[52:55]
	v_mfma_f32_16x16x32_bf16 v[48:51], v[156:159], v[192:195], v[48:51]
	v_mfma_f32_16x16x32_bf16 v[28:31], v[148:151], v[200:203], v[28:31]
	v_mfma_f32_16x16x32_bf16 v[24:27], v[156:159], v[200:203], v[24:27]
	v_mfma_f32_16x16x32_bf16 v[12:15], v[148:151], v[218:221], v[12:15]
	v_mfma_f32_16x16x32_bf16 v[8:11], v[156:159], v[218:221], v[8:11]
	v_mfma_f32_16x16x32_bf16 v[4:7], v[148:151], v[226:229], v[4:7]
	v_mfma_f32_16x16x32_bf16 v[0:3], v[156:159], v[226:229], v[0:3]
	s_setprio 0
	s_add_i32 s64, s64, 2
	s_add_u32 s62, s62, 0x100
	s_addc_u32 s63, s63, 0
	s_cmp_gt_u32 s64, 41
	s_mov_b64 s[34:35], s[36:37]
	s_barrier
	s_cbranch_scc0 .LBB0_1121
	s_and_b64 vcc, exec, s[12:13]
	s_cbranch_vccz .LBB0_1124
	s_barrier

; #define PG8_STAGE(bufoff, gbase, voff) do { _Pragma("unroll") for (int _i = 0; _i < 2; ++_i) \
;         __builtin_amdgcn_global_load_lds((const unsigned*)((const char*)(gbase) + (voff)[_i]), (LAS unsigned*)(lds + (bufoff) + ldsw + _i * 8192), 16, 0, 0); } while (0)
; #define PG8_LDA(dst, b, h) do { _Pragma("unroll") for (int m = 0; m < 4; ++m) _Pragma("unroll") for (int k = 0; k < 2; ++k) dst[m][k] = *(const LAS bf16x8*)(lds + PG8_SA(b, h) + aoff + m * 2048 + k * 1024); } while (0)
; #define PG8_LDB(dst, b, h) do { _Pragma("unroll") for (int n = 0; n < 2; ++n) _Pragma("unroll") for (int k = 0; k < 2; ++k) dst[n][k] = *(const LAS bf16x8*)(lds + PG8_SB(b, h) + boff + n * 2048 + k * 1024); } while (0)
; #define PG8_WAIT_V(n) asm volatile("s_waitcnt vmcnt(" #n ")" ::: "memory")
; #define PG8_WAIT_L(n) asm volatile("s_waitcnt lgkmcnt(" #n ")" ::: "memory")
; #define PG8_BAR __builtin_amdgcn_s_barrier()
; #define PG8_SCHED __builtin_amdgcn_sched_barrier(0)
; template <class Epi, class Sched, bool SWAPD = false>
; __device__ __forceinline__ void gemm_phase(LAS unsigned char* lds, const Gemm g, const Sched& S, const Epi& E) {
;     ...
;             const bool last = (t == nt - 2);
;             const char* a1 = cA + (size_t)(t + 1) * kstepA;
;             const char* a2 = last ? nA : cA + (size_t)(t + 2) * kstepA; const char* b2 = last ? nB : cB + (size_t)(t + 2) * kstep;
;             const char* a3 = a2 + kstepA; const char* b3 = b2 + kstep;
;             PG8_LDB(B0, 0, 0); PG8_LDB(B1, 0, 1); PG8_SCHED; PG8_LDA(At, 0, 0); PG8_STAGE(PG8_SA(1, 1), a1 + hstepA, voffA);
;             PG8_WAIT_V(8); PG8_WAIT_L(0); PG8_BAR; PG8_MMA(0, 0, At, B0); PG8_MMA(0, 1, At, B1); PG8_BAR; PG8_SCHED;
;             PG8_LDA(At, 0, 1); PG8_STAGE(PG8_SB(0, 0), b2, voffB); PG8_STAGE(PG8_SB(0, 1), b2 + hstepB, voffB); PG8_STAGE(PG8_SA(0, 0), a2, voffA);
.LBB0_1531:
	ds_read_b128 v[142:145], v151
	ds_read_b128 v[154:157], v151 offset:1024
	ds_read_b128 v[158:161], v151 offset:2048
	ds_read_b128 v[162:165], v151 offset:3072
	ds_read_b128 v[166:169], v152
	ds_read_b128 v[170:173], v152 offset:1024
	ds_read_b128 v[174:177], v152 offset:2048
	ds_read_b128 v[178:181], v152 offset:3072
	s_add_u32 s42, s40, 0xfffe0080
	s_addc_u32 s43, s41, -1
	s_cmp_eq_u32 s61, 4
	s_cselect_b32 s45, s9, s43
	s_cselect_b32 s44, s25, s42
	s_cselect_b32 s43, s27, s60
	s_cselect_b32 s42, s58, s59
	v_lshl_add_u64 v[216:217], s[40:41], 0, v[134:135]
	s_add_i32 m0, s33, 0xc000
	ds_read_b128 v[182:185], v153
	ds_read_b128 v[186:189], v153 offset:1024
	ds_read_b128 v[190:193], v153 offset:2048
	ds_read_b128 v[194:197], v153 offset:3072
	ds_read_b128 v[198:201], v153 offset:4096
	ds_read_b128 v[202:205], v153 offset:5120
	ds_read_b128 v[208:211], v153 offset:6144
	ds_read_b128 v[212:215], v153 offset:7168
	global_load_lds_dwordx4 v[216:217], off
	v_lshl_add_u64 v[216:217], s[40:41], 0, v[136:137]
	s_add_i32 m0, s33, 0xe000
	s_nop 0
	global_load_lds_dwordx4 v[216:217], off
	s_waitcnt vmcnt(8)
	s_waitcnt lgkmcnt(0)
	s_barrier
	s_setprio 1
	v_mfma_f32_16x16x32_bf16 v[124:127], v[182:185], v[142:145], v[124:127]
	v_mfma_f32_16x16x32_bf16 v[120:123], v[182:185], v[158:161], v[120:123]
	v_mfma_f32_16x16x32_bf16 v[108:111], v[190:193], v[142:145], v[108:111]
	v_mfma_f32_16x16x32_bf16 v[104:107], v[190:193], v[158:161], v[104:107]
	v_mfma_f32_16x16x32_bf16 v[96:99], v[198:201], v[142:145], v[96:99]
	v_mfma_f32_16x16x32_bf16 v[88:91], v[198:201], v[158:161], v[88:91]
	v_mfma_f32_16x16x32_bf16 v[80:83], v[208:211], v[142:145], v[80:83]
	v_mfma_f32_16x16x32_bf16 v[72:75], v[208:211], v[158:161], v[72:75]
	v_mfma_f32_16x16x32_bf16 v[124:127], v[186:189], v[154:157], v[124:127]
	v_mfma_f32_16x16x32_bf16 v[120:123], v[186:189], v[162:165], v[120:123]
	v_mfma_f32_16x16x32_bf16 v[108:111], v[194:197], v[154:157], v[108:111]
	v_mfma_f32_16x16x32_bf16 v[104:107], v[194:197], v[162:165], v[104:107]
	v_mfma_f32_16x16x32_bf16 v[96:99], v[202:205], v[154:157], v[96:99]
	v_mfma_f32_16x16x32_bf16 v[88:91], v[202:205], v[162:165], v[88:91]
	v_mfma_f32_16x16x32_bf16 v[80:83], v[212:215], v[154:157], v[80:83]
	v_mfma_f32_16x16x32_bf16 v[72:75], v[212:215], v[162:165], v[72:75]
	s_setprio 0
	s_setprio 1
	v_mfma_f32_16x16x32_bf16 v[116:119], v[182:185], v[166:169], v[116:119]
	v_mfma_f32_16x16x32_bf16 v[112:115], v[182:185], v[174:177], v[112:115]
	v_mfma_f32_16x16x32_bf16 v[100:103], v[190:193], v[166:169], v[100:103]
	v_mfma_f32_16x16x32_bf16 v[92:95], v[190:193], v[174:177], v[92:95]
	v_mfma_f32_16x16x32_bf16 v[84:87], v[198:201], v[166:169], v[84:87]
	v_mfma_f32_16x16x32_bf16 v[76:79], v[198:201], v[174:177], v[76:79]
	v_mfma_f32_16x16x32_bf16 v[68:71], v[208:211], v[166:169], v[68:71]
	v_mfma_f32_16x16x32_bf16 v[64:67], v[208:211], v[174:177], v[64:67]
	v_mfma_f32_16x16x32_bf16 v[116:119], v[186:189], v[170:173], v[116:119]
	v_mfma_f32_16x16x32_bf16 v[112:115], v[186:189], v[178:181], v[112:115]
	v_mfma_f32_16x16x32_bf16 v[100:103], v[194:197], v[170:173], v[100:103]
	v_mfma_f32_16x16x32_bf16 v[92:95], v[194:197], v[178:181], v[92:95]
	v_mfma_f32_16x16x32_bf16 v[84:87], v[202:205], v[170:173], v[84:87]
	v_mfma_f32_16x16x32_bf16 v[76:79], v[202:205], v[178:181], v[76:79]
	v_mfma_f32_16x16x32_bf16 v[68:71], v[212:215], v[170:173], v[68:71]
	v_mfma_f32_16x16x32_bf16 v[64:67], v[212:215], v[178:181], v[64:67]
	s_setprio 0
	s_barrier
	s_add_i32 s62, s55, s21
	v_lshl_add_u64 v[216:217], s[42:43], 0, v[128:129]
	s_mov_b32 m0, s62
	ds_read_b128 v[182:185], v153 offset:16384
	ds_read_b128 v[186:189], v153 offset:17408
	ds_read_b128 v[190:193], v153 offset:18432
	ds_read_b128 v[194:197], v153 offset:19456
	ds_read_b128 v[198:201], v153 offset:20480
	ds_read_b128 v[202:205], v153 offset:21504
	ds_read_b128 v[208:211], v153 offset:22528
	ds_read_b128 v[212:215], v153 offset:23552
	global_load_lds_dwordx4 v[216:217], off
	s_add_i32 m0, s62, 0x2000
	s_add_u32 s62, s42, 0x20000
	v_lshl_add_u64 v[218:219], s[42:43], 0, v[130:131]
	s_addc_u32 s63, s43, 0
	s_add_i32 s64, s56, s21
	global_load_lds_dwordx4 v[218:219], off
	v_lshl_add_u64 v[220:221], s[62:63], 0, v[128:129]
	s_mov_b32 m0, s64
	v_lshl_add_u64 v[222:223], s[44:45], 0, v[130:131]
	global_load_lds_dwordx4 v[220:221], off
	v_lshl_add_u64 v[220:221], s[62:63], 0, v[130:131]
	s_add_i32 m0, s64, 0x2000
	s_nop 0
	global_load_lds_dwordx4 v[220:221], off
	v_lshl_add_u64 v[220:221], s[44:45], 0, v[128:129]
	s_mov_b32 m0, s33
	s_nop 0
	global_load_lds_dwordx4 v[220:221], off
	s_mov_b32 m0, s46
	s_nop 0
	global_load_lds_dwordx4 v[222:223], off
	s_waitcnt vmcnt(8)
	s_waitcnt lgkmcnt(0)
	s_barrier
; #define PG8_STAGE(bufoff, gbase, voff) do { _Pragma("unroll") for (int _i = 0; _i < 2; ++_i) \
;         __builtin_amdgcn_global_load_lds((const unsigned*)((const char*)(gbase) + (voff)[_i]), (LAS unsigned*)(lds + (bufoff) + ldsw + _i * 8192), 16, 0, 0); } while (0)
; #define PG8_LDA(dst, b, h) do { _Pragma("unroll") for (int m = 0; m < 4; ++m) _Pragma("unroll") for (int k = 0; k < 2; ++k) dst[m][k] = *(const LAS bf16x8*)(lds + PG8_SA(b, h) + aoff + m * 2048 + k * 1024); } while (0)
; #define PG8_LDB(dst, b, h) do { _Pragma("unroll") for (int n = 0; n < 2; ++n) _Pragma("unroll") for (int k = 0; k < 2; ++k) dst[n][k] = *(const LAS bf16x8*)(lds + PG8_SB(b, h) + boff + n * 2048 + k * 1024); } while (0)
; #define PG8_WAIT_V(n) asm volatile("s_waitcnt vmcnt(" #n ")" ::: "memory")
; #define PG8_WAIT_L(n) asm volatile("s_waitcnt lgkmcnt(" #n ")" ::: "memory")
; #define PG8_BAR __builtin_amdgcn_s_barrier()
; #define PG8_SCHED __builtin_amdgcn_sched_barrier(0)
; template <class Epi, class Sched, bool SWAPD = false>
; __device__ __forceinline__ void gemm_phase(LAS unsigned char* lds, const Gemm g, const Sched& S, const Epi& E) {
;     ...
;             PG8_WAIT_V(8); PG8_WAIT_L(0); PG8_BAR; PG8_MMA(1, 0, At, B0); PG8_MMA(1, 1, At, B1); PG8_BAR; PG8_SCHED;
;             PG8_LDB(B0, 1, 0); PG8_LDB(B1, 1, 1); PG8_SCHED; PG8_LDA(At, 1, 0); PG8_STAGE(PG8_SA(0, 1), a2 + hstepA, voffA);
;             PG8_WAIT_V(8); PG8_WAIT_L(0); PG8_BAR; PG8_MMA(0, 0, At, B0); PG8_MMA(0, 1, At, B1); PG8_BAR; PG8_SCHED;
	s_setprio 1
	v_mfma_f32_16x16x32_bf16 v[60:63], v[182:185], v[142:145], v[60:63]
	v_mfma_f32_16x16x32_bf16 v[56:59], v[182:185], v[158:161], v[56:59]
	v_mfma_f32_16x16x32_bf16 v[48:51], v[190:193], v[142:145], v[48:51]
	v_mfma_f32_16x16x32_bf16 v[40:43], v[190:193], v[158:161], v[40:43]
	v_mfma_f32_16x16x32_bf16 v[32:35], v[198:201], v[142:145], v[32:35]
	v_mfma_f32_16x16x32_bf16 v[24:27], v[198:201], v[158:161], v[24:27]
	v_mfma_f32_16x16x32_bf16 v[16:19], v[208:211], v[142:145], v[16:19]
	v_mfma_f32_16x16x32_bf16 v[8:11], v[208:211], v[158:161], v[8:11]
	v_mfma_f32_16x16x32_bf16 v[60:63], v[186:189], v[154:157], v[60:63]
	v_mfma_f32_16x16x32_bf16 v[56:59], v[186:189], v[162:165], v[56:59]
	v_mfma_f32_16x16x32_bf16 v[48:51], v[194:197], v[154:157], v[48:51]
	v_mfma_f32_16x16x32_bf16 v[40:43], v[194:197], v[162:165], v[40:43]
	v_mfma_f32_16x16x32_bf16 v[32:35], v[202:205], v[154:157], v[32:35]
	v_mfma_f32_16x16x32_bf16 v[24:27], v[202:205], v[162:165], v[24:27]
	v_mfma_f32_16x16x32_bf16 v[16:19], v[212:215], v[154:157], v[16:19]
	v_mfma_f32_16x16x32_bf16 v[8:11], v[212:215], v[162:165], v[8:11]
	s_setprio 0
	s_setprio 1
	v_mfma_f32_16x16x32_bf16 v[52:55], v[182:185], v[166:169], v[52:55]
	v_mfma_f32_16x16x32_bf16 v[44:47], v[182:185], v[174:177], v[44:47]
	v_mfma_f32_16x16x32_bf16 v[36:39], v[190:193], v[166:169], v[36:39]
	v_mfma_f32_16x16x32_bf16 v[28:31], v[190:193], v[174:177], v[28:31]
	v_mfma_f32_16x16x32_bf16 v[20:23], v[198:201], v[166:169], v[20:23]
	v_mfma_f32_16x16x32_bf16 v[12:15], v[198:201], v[174:177], v[12:15]
	v_mfma_f32_16x16x32_bf16 v[4:7], v[208:211], v[166:169], v[4:7]
	v_mfma_f32_16x16x32_bf16 v[0:3], v[208:211], v[174:177], v[0:3]
	v_mfma_f32_16x16x32_bf16 v[52:55], v[186:189], v[170:173], v[52:55]
	v_mfma_f32_16x16x32_bf16 v[44:47], v[186:189], v[178:181], v[44:47]
	v_mfma_f32_16x16x32_bf16 v[36:39], v[194:197], v[170:173], v[36:39]
	v_mfma_f32_16x16x32_bf16 v[28:31], v[194:197], v[178:181], v[28:31]
	v_mfma_f32_16x16x32_bf16 v[20:23], v[202:205], v[170:173], v[20:23]
	v_mfma_f32_16x16x32_bf16 v[12:15], v[202:205], v[178:181], v[12:15]
	v_mfma_f32_16x16x32_bf16 v[4:7], v[212:215], v[170:173], v[4:7]
	v_mfma_f32_16x16x32_bf16 v[0:3], v[212:215], v[178:181], v[0:3]
	s_setprio 0
	s_barrier
	s_add_i32 s62, 0, 0x18000
	s_add_i32 s63, 0, 0x1c000
	v_add_u32_e32 v162, s62, v146
	v_add_u32_e32 v178, s63, v146
	ds_read_b128 v[142:145], v162
	ds_read_b128 v[154:157], v162 offset:1024
	ds_read_b128 v[158:161], v162 offset:2048
	ds_read_b128 v[162:165], v162 offset:3072
	ds_read_b128 v[166:169], v178
	ds_read_b128 v[170:173], v178 offset:1024
	ds_read_b128 v[174:177], v178 offset:2048
	ds_read_b128 v[178:181], v178 offset:3072
	s_add_u32 s44, s44, 0x20000
	s_addc_u32 s45, s45, 0
	s_mov_b32 m0, s47
	v_lshl_add_u64 v[224:225], s[44:45], 0, v[128:129]
	ds_read_b128 v[182:185], v153 offset:32768
	ds_read_b128 v[186:189], v153 offset:33792
	ds_read_b128 v[190:193], v153 offset:34816
	ds_read_b128 v[194:197], v153 offset:35840
	ds_read_b128 v[198:201], v153 offset:36864
	ds_read_b128 v[202:205], v153 offset:37888
	ds_read_b128 v[208:211], v153 offset:38912
	ds_read_b128 v[212:215], v153 offset:39936
	global_load_lds_dwordx4 v[224:225], off
	v_lshl_add_u64 v[224:225], s[44:45], 0, v[130:131]
	s_mov_b32 m0, s50
	s_nop 0
	global_load_lds_dwordx4 v[224:225], off
	s_waitcnt vmcnt(8)
	s_waitcnt lgkmcnt(0)
	s_barrier
	s_setprio 1
	v_mfma_f32_16x16x32_bf16 v[124:127], v[182:185], v[142:145], v[124:127]
	v_mfma_f32_16x16x32_bf16 v[120:123], v[182:185], v[158:161], v[120:123]
	v_mfma_f32_16x16x32_bf16 v[108:111], v[190:193], v[142:145], v[108:111]
	v_mfma_f32_16x16x32_bf16 v[104:107], v[190:193], v[158:161], v[104:107]
	v_mfma_f32_16x16x32_bf16 v[96:99], v[198:201], v[142:145], v[96:99]
	v_mfma_f32_16x16x32_bf16 v[88:91], v[198:201], v[158:161], v[88:91]
	v_mfma_f32_16x16x32_bf16 v[80:83], v[208:211], v[142:145], v[80:83]
	v_mfma_f32_16x16x32_bf16 v[72:75], v[208:211], v[158:161], v[72:75]
	v_mfma_f32_16x16x32_bf16 v[124:127], v[186:189], v[154:157], v[124:127]
	v_mfma_f32_16x16x32_bf16 v[120:123], v[186:189], v[162:165], v[120:123]
	v_mfma_f32_16x16x32_bf16 v[108:111], v[194:197], v[154:157], v[108:111]
	v_mfma_f32_16x16x32_bf16 v[104:107], v[194:197], v[162:165], v[104:107]
	v_mfma_f32_16x16x32_bf16 v[96:99], v[202:205], v[154:157], v[96:99]
	v_mfma_f32_16x16x32_bf16 v[88:91], v[202:205], v[162:165], v[88:91]
	v_mfma_f32_16x16x32_bf16 v[80:83], v[212:215], v[154:157], v[80:83]
	v_mfma_f32_16x16x32_bf16 v[72:75], v[212:215], v[162:165], v[72:75]
	s_setprio 0
	s_setprio 1
	v_mfma_f32_16x16x32_bf16 v[116:119], v[182:185], v[166:169], v[116:119]
	v_mfma_f32_16x16x32_bf16 v[112:115], v[182:185], v[174:177], v[112:115]
	v_mfma_f32_16x16x32_bf16 v[100:103], v[190:193], v[166:169], v[100:103]
	v_mfma_f32_16x16x32_bf16 v[92:95], v[190:193], v[174:177], v[92:95]
	v_mfma_f32_16x16x32_bf16 v[84:87], v[198:201], v[166:169], v[84:87]
	v_mfma_f32_16x16x32_bf16 v[76:79], v[198:201], v[174:177], v[76:79]
	v_mfma_f32_16x16x32_bf16 v[68:71], v[208:211], v[166:169], v[68:71]
	v_mfma_f32_16x16x32_bf16 v[64:67], v[208:211], v[174:177], v[64:67]
	v_mfma_f32_16x16x32_bf16 v[116:119], v[186:189], v[170:173], v[116:119]
	v_mfma_f32_16x16x32_bf16 v[112:115], v[186:189], v[178:181], v[112:115]
	v_mfma_f32_16x16x32_bf16 v[100:103], v[194:197], v[170:173], v[100:103]
	v_mfma_f32_16x16x32_bf16 v[92:95], v[194:197], v[178:181], v[92:95]
	v_mfma_f32_16x16x32_bf16 v[84:87], v[202:205], v[170:173], v[84:87]
	v_mfma_f32_16x16x32_bf16 v[76:79], v[202:205], v[178:181], v[76:79]
	v_mfma_f32_16x16x32_bf16 v[68:71], v[212:215], v[170:173], v[68:71]
	v_mfma_f32_16x16x32_bf16 v[64:67], v[212:215], v[178:181], v[64:67]
	s_setprio 0
	s_barrier
; #define PG8_STAGE(bufoff, gbase, voff) do { _Pragma("unroll") for (int _i = 0; _i < 2; ++_i) \
;         __builtin_amdgcn_global_load_lds((const unsigned*)((const char*)(gbase) + (voff)[_i]), (LAS unsigned*)(lds + (bufoff) + ldsw + _i * 8192), 16, 0, 0); } while (0)
; #define PG8_LDA(dst, b, h) do { _Pragma("unroll") for (int m = 0; m < 4; ++m) _Pragma("unroll") for (int k = 0; k < 2; ++k) dst[m][k] = *(const LAS bf16x8*)(lds + PG8_SA(b, h) + aoff + m * 2048 + k * 1024); } while (0)
; #define PG8_WAIT_V(n) asm volatile("s_waitcnt vmcnt(" #n ")" ::: "memory")
; #define PG8_WAIT_L(n) asm volatile("s_waitcnt lgkmcnt(" #n ")" ::: "memory")
; #define PG8_BAR __builtin_amdgcn_s_barrier()
; #define PG8_SCHED __builtin_amdgcn_sched_barrier(0)
; template <class Epi, class Sched, bool SWAPD = false>
; __device__ __forceinline__ void gemm_phase(LAS unsigned char* lds, const Gemm g, const Sched& S, const Epi& E) {
;     ...
;             PG8_LDA(At, 1, 1); PG8_STAGE(PG8_SB(1, 0), b3, voffB); PG8_STAGE(PG8_SB(1, 1), b3 + hstepB, voffB); PG8_STAGE(PG8_SA(1, 0), a3, voffA);
;             PG8_WAIT_V(8); PG8_WAIT_L(0); PG8_BAR; PG8_MMA(1, 0, At, B0); PG8_MMA(1, 1, At, B1); PG8_BAR; PG8_SCHED;
;         }
	s_add_i32 s44, s62, s21
	v_lshl_add_u64 v[216:217], v[216:217], 0, s[12:13]
	s_mov_b32 m0, s44
	ds_read_b128 v[182:185], v153 offset:49152
	ds_read_b128 v[186:189], v153 offset:50176
	ds_read_b128 v[190:193], v153 offset:51200
	ds_read_b128 v[194:197], v153 offset:52224
	ds_read_b128 v[198:201], v153 offset:53248
	ds_read_b128 v[202:205], v153 offset:54272
	ds_read_b128 v[208:211], v153 offset:55296
	ds_read_b128 v[212:215], v153 offset:56320
	global_load_lds_dwordx4 v[216:217], off
	s_add_i32 m0, s44, 0x2000
	s_add_u32 s42, s42, 0x20080
	v_lshl_add_u64 v[216:217], v[218:219], 0, s[12:13]
	s_addc_u32 s43, s43, 0
	s_add_i32 s44, s63, s21
	global_load_lds_dwordx4 v[216:217], off
	v_lshl_add_u64 v[216:217], s[42:43], 0, v[128:129]
	s_mov_b32 m0, s44
	s_nop 0
	global_load_lds_dwordx4 v[216:217], off
	v_lshl_add_u64 v[216:217], s[42:43], 0, v[130:131]
	s_add_i32 m0, s44, 0x2000
	s_nop 0
	global_load_lds_dwordx4 v[216:217], off
	v_lshl_add_u64 v[216:217], v[220:221], 0, s[12:13]
	s_mov_b32 m0, s52
	s_nop 0
	global_load_lds_dwordx4 v[216:217], off
	v_lshl_add_u64 v[216:217], v[222:223], 0, s[12:13]
	s_mov_b32 m0, s53
	s_nop 0
	global_load_lds_dwordx4 v[216:217], off
	s_waitcnt vmcnt(8)
	s_waitcnt lgkmcnt(0)
	s_barrier
	s_setprio 1
	v_mfma_f32_16x16x32_bf16 v[60:63], v[182:185], v[142:145], v[60:63]
	v_mfma_f32_16x16x32_bf16 v[56:59], v[182:185], v[158:161], v[56:59]
	v_mfma_f32_16x16x32_bf16 v[48:51], v[190:193], v[142:145], v[48:51]
	v_mfma_f32_16x16x32_bf16 v[40:43], v[190:193], v[158:161], v[40:43]
	v_mfma_f32_16x16x32_bf16 v[32:35], v[198:201], v[142:145], v[32:35]
	v_mfma_f32_16x16x32_bf16 v[24:27], v[198:201], v[158:161], v[24:27]
	v_mfma_f32_16x16x32_bf16 v[16:19], v[208:211], v[142:145], v[16:19]
	v_mfma_f32_16x16x32_bf16 v[8:11], v[208:211], v[158:161], v[8:11]
	v_mfma_f32_16x16x32_bf16 v[60:63], v[186:189], v[154:157], v[60:63]
	v_mfma_f32_16x16x32_bf16 v[56:59], v[186:189], v[162:165], v[56:59]
	v_mfma_f32_16x16x32_bf16 v[48:51], v[194:197], v[154:157], v[48:51]
	v_mfma_f32_16x16x32_bf16 v[40:43], v[194:197], v[162:165], v[40:43]
	v_mfma_f32_16x16x32_bf16 v[32:35], v[202:205], v[154:157], v[32:35]
	v_mfma_f32_16x16x32_bf16 v[24:27], v[202:205], v[162:165], v[24:27]
	v_mfma_f32_16x16x32_bf16 v[16:19], v[212:215], v[154:157], v[16:19]
	v_mfma_f32_16x16x32_bf16 v[8:11], v[212:215], v[162:165], v[8:11]
	s_setprio 0
	s_setprio 1
	v_mfma_f32_16x16x32_bf16 v[52:55], v[182:185], v[166:169], v[52:55]
	v_mfma_f32_16x16x32_bf16 v[44:47], v[182:185], v[174:177], v[44:47]
	v_mfma_f32_16x16x32_bf16 v[36:39], v[190:193], v[166:169], v[36:39]
	v_mfma_f32_16x16x32_bf16 v[28:31], v[190:193], v[174:177], v[28:31]
	v_mfma_f32_16x16x32_bf16 v[20:23], v[198:201], v[166:169], v[20:23]
	v_mfma_f32_16x16x32_bf16 v[12:15], v[198:201], v[174:177], v[12:15]
	v_mfma_f32_16x16x32_bf16 v[4:7], v[208:211], v[166:169], v[4:7]
	v_mfma_f32_16x16x32_bf16 v[0:3], v[208:211], v[174:177], v[0:3]
	v_mfma_f32_16x16x32_bf16 v[52:55], v[186:189], v[170:173], v[52:55]
	v_mfma_f32_16x16x32_bf16 v[44:47], v[186:189], v[178:181], v[44:47]
	v_mfma_f32_16x16x32_bf16 v[36:39], v[194:197], v[170:173], v[36:39]
	v_mfma_f32_16x16x32_bf16 v[28:31], v[194:197], v[178:181], v[28:31]
	v_mfma_f32_16x16x32_bf16 v[20:23], v[202:205], v[170:173], v[20:23]
	v_mfma_f32_16x16x32_bf16 v[12:15], v[202:205], v[178:181], v[12:15]
	v_mfma_f32_16x16x32_bf16 v[4:7], v[212:215], v[170:173], v[4:7]
	v_mfma_f32_16x16x32_bf16 v[0:3], v[212:215], v[178:181], v[0:3]
	s_setprio 0
	s_add_i32 s61, s61, 2
	s_add_u32 s40, s40, 0x100
	s_addc_u32 s41, s41, 0
	s_add_u32 s59, s59, 0x100
	s_addc_u32 s60, s60, 0
	s_cmp_gt_u32 s61, 5
	s_barrier
	s_cbranch_scc0 .LBB0_1531
	s_and_b64 vcc, exec, s[22:23]
	s_cbranch_vccz .LBB0_1534
	s_barrier

; #define PG8_STAGE(bufoff, gbase, voff) do { _Pragma("unroll") for (int _i = 0; _i < 2; ++_i) \
;         __builtin_amdgcn_global_load_lds((const unsigned*)((const char*)(gbase) + (voff)[_i]), (LAS unsigned*)(lds + (bufoff) + ldsw + _i * 8192), 16, 0, 0); } while (0)
; #define PG8_LDA(dst, b, h) do { _Pragma("unroll") for (int m = 0; m < 4; ++m) _Pragma("unroll") for (int k = 0; k < 2; ++k) dst[m][k] = *(const LAS bf16x8*)(lds + PG8_SA(b, h) + aoff + m * 2048 + k * 1024); } while (0)
; #define PG8_LDB(dst, b, h) do { _Pragma("unroll") for (int n = 0; n < 2; ++n) _Pragma("unroll") for (int k = 0; k < 2; ++k) dst[n][k] = *(const LAS bf16x8*)(lds + PG8_SB(b, h) + boff + n * 2048 + k * 1024); } while (0)
; #define PG8_WAIT_V(n) asm volatile("s_waitcnt vmcnt(" #n ")" ::: "memory")
; #define PG8_WAIT_L(n) asm volatile("s_waitcnt lgkmcnt(" #n ")" ::: "memory")
; #define PG8_BAR __builtin_amdgcn_s_barrier()
; #define PG8_SCHED __builtin_amdgcn_sched_barrier(0)
; template <class Epi, class Sched, bool SWAPD = false>
; __device__ __forceinline__ void gemm_phase(LAS unsigned char* lds, const Gemm g, const Sched& S, const Epi& E) {
;     ...
;             const bool last = (t == nt - 2);
;             const char* a1 = cA + (size_t)(t + 1) * kstepA;
;             const char* a2 = last ? nA : cA + (size_t)(t + 2) * kstepA; const char* b2 = last ? nB : cB + (size_t)(t + 2) * kstep;
;             const char* a3 = a2 + kstepA; const char* b3 = b2 + kstep;
;             PG8_LDB(B0, 0, 0); PG8_LDB(B1, 0, 1); PG8_SCHED; PG8_LDA(At, 0, 0); PG8_STAGE(PG8_SA(1, 1), a1 + hstepA, voffA);
;             PG8_WAIT_V(8); PG8_WAIT_L(0); PG8_BAR; PG8_MMA(0, 0, At, B0); PG8_MMA(0, 1, At, B1); PG8_BAR; PG8_SCHED;
;             PG8_LDA(At, 0, 1); PG8_STAGE(PG8_SB(0, 0), b2, voffB); PG8_STAGE(PG8_SB(0, 1), b2 + hstepB, voffB); PG8_STAGE(PG8_SA(0, 0), a2, voffA);
.LBB0_1661:
	ds_read_b128 v[154:157], v150
	ds_read_b128 v[158:161], v150 offset:1024
	ds_read_b128 v[162:165], v150 offset:2048
	ds_read_b128 v[166:169], v150 offset:3072
	ds_read_b128 v[170:173], v151
	ds_read_b128 v[174:177], v151 offset:1024
	ds_read_b128 v[178:181], v151 offset:2048
	ds_read_b128 v[182:185], v151 offset:3072
	s_add_u32 s46, s44, 0x100
	s_addc_u32 s47, s45, 0
	s_add_u32 s50, s75, s44
	s_addc_u32 s51, s76, s45
	s_cmp_eq_u32 s77, 4
	s_cselect_b32 s52, s74, s50
	s_cselect_b32 s50, 0, s46
	s_cselect_b32 s53, s9, s51
	s_cselect_b32 s51, 0, s47
	s_add_u32 s50, s0, s50
	s_addc_u32 s51, s1, s51
	s_mov_b32 m0, s62
	v_lshl_add_u64 v[220:221], v[144:145], 0, s[44:45]
	ds_read_b128 v[186:189], v152
	ds_read_b128 v[190:193], v152 offset:1024
	ds_read_b128 v[194:197], v152 offset:2048
	ds_read_b128 v[198:201], v152 offset:3072
	ds_read_b128 v[202:205], v152 offset:4096
	ds_read_b128 v[208:211], v152 offset:5120
	ds_read_b128 v[212:215], v152 offset:6144
	ds_read_b128 v[216:219], v152 offset:7168
	global_load_lds_dwordx4 v[220:221], off
	v_lshl_add_u64 v[220:221], v[146:147], 0, s[44:45]
	s_mov_b32 m0, s63
	s_nop 0
	global_load_lds_dwordx4 v[220:221], off
	s_waitcnt vmcnt(8)
	s_waitcnt lgkmcnt(0)
	s_barrier
	s_setprio 1
	v_mfma_f32_16x16x32_bf16 v[124:127], v[154:157], v[186:189], v[124:127]
	v_mfma_f32_16x16x32_bf16 v[120:123], v[162:165], v[186:189], v[120:123]
	v_mfma_f32_16x16x32_bf16 v[112:115], v[154:157], v[194:197], v[112:115]
	v_mfma_f32_16x16x32_bf16 v[104:107], v[162:165], v[194:197], v[104:107]
	v_mfma_f32_16x16x32_bf16 v[96:99], v[154:157], v[202:205], v[96:99]
	v_mfma_f32_16x16x32_bf16 v[88:91], v[162:165], v[202:205], v[88:91]
	v_mfma_f32_16x16x32_bf16 v[80:83], v[154:157], v[212:215], v[80:83]
	v_mfma_f32_16x16x32_bf16 v[72:75], v[162:165], v[212:215], v[72:75]
	v_mfma_f32_16x16x32_bf16 v[124:127], v[158:161], v[190:193], v[124:127]
	v_mfma_f32_16x16x32_bf16 v[120:123], v[166:169], v[190:193], v[120:123]
	v_mfma_f32_16x16x32_bf16 v[112:115], v[158:161], v[198:201], v[112:115]
	v_mfma_f32_16x16x32_bf16 v[104:107], v[166:169], v[198:201], v[104:107]
	v_mfma_f32_16x16x32_bf16 v[96:99], v[158:161], v[208:211], v[96:99]
	v_mfma_f32_16x16x32_bf16 v[88:91], v[166:169], v[208:211], v[88:91]
	v_mfma_f32_16x16x32_bf16 v[80:83], v[158:161], v[216:219], v[80:83]
	v_mfma_f32_16x16x32_bf16 v[72:75], v[166:169], v[216:219], v[72:75]
	s_setprio 0
	s_setprio 1
	v_mfma_f32_16x16x32_bf16 v[116:119], v[170:173], v[186:189], v[116:119]
	v_mfma_f32_16x16x32_bf16 v[108:111], v[178:181], v[186:189], v[108:111]
	v_mfma_f32_16x16x32_bf16 v[100:103], v[170:173], v[194:197], v[100:103]
	v_mfma_f32_16x16x32_bf16 v[92:95], v[178:181], v[194:197], v[92:95]
	v_mfma_f32_16x16x32_bf16 v[84:87], v[170:173], v[202:205], v[84:87]
	v_mfma_f32_16x16x32_bf16 v[76:79], v[178:181], v[202:205], v[76:79]
	v_mfma_f32_16x16x32_bf16 v[68:71], v[170:173], v[212:215], v[68:71]
	v_mfma_f32_16x16x32_bf16 v[64:67], v[178:181], v[212:215], v[64:67]
	v_mfma_f32_16x16x32_bf16 v[116:119], v[174:177], v[190:193], v[116:119]
	v_mfma_f32_16x16x32_bf16 v[108:111], v[182:185], v[190:193], v[108:111]
	v_mfma_f32_16x16x32_bf16 v[100:103], v[174:177], v[198:201], v[100:103]
	v_mfma_f32_16x16x32_bf16 v[92:95], v[182:185], v[198:201], v[92:95]
	v_mfma_f32_16x16x32_bf16 v[84:87], v[174:177], v[208:211], v[84:87]
	v_mfma_f32_16x16x32_bf16 v[76:79], v[182:185], v[208:211], v[76:79]
	v_mfma_f32_16x16x32_bf16 v[68:71], v[174:177], v[216:219], v[68:71]
	v_mfma_f32_16x16x32_bf16 v[64:67], v[182:185], v[216:219], v[64:67]
	s_setprio 0
	s_barrier
	s_mov_b32 m0, s64
	v_lshl_add_u64 v[220:221], s[50:51], 0, v[132:133]
	s_add_u32 s44, s50, 0x20000
	ds_read_b128 v[186:189], v152 offset:16384
	ds_read_b128 v[190:193], v152 offset:17408
	ds_read_b128 v[194:197], v152 offset:18432
	ds_read_b128 v[198:201], v152 offset:19456
	ds_read_b128 v[202:205], v152 offset:20480
	ds_read_b128 v[208:211], v152 offset:21504
	ds_read_b128 v[212:215], v152 offset:22528
	ds_read_b128 v[216:219], v152 offset:23552
	global_load_lds_dwordx4 v[220:221], off
	v_lshl_add_u64 v[222:223], s[50:51], 0, v[128:129]
	s_mov_b32 m0, s65
	s_addc_u32 s45, s51, 0
	global_load_lds_dwordx4 v[222:223], off
	v_lshl_add_u64 v[224:225], s[44:45], 0, v[132:133]
	s_mov_b32 m0, s66
	v_lshl_add_u64 v[226:227], s[52:53], 0, v[130:131]
	global_load_lds_dwordx4 v[224:225], off
	v_lshl_add_u64 v[224:225], s[44:45], 0, v[128:129]
	s_mov_b32 m0, s67
	s_nop 0
	global_load_lds_dwordx4 v[224:225], off
	v_lshl_add_u64 v[224:225], s[52:53], 0, v[134:135]
	s_mov_b32 m0, s30
	s_nop 0
	global_load_lds_dwordx4 v[224:225], off
	s_mov_b32 m0, s31
	s_nop 0
	global_load_lds_dwordx4 v[226:227], off
	s_waitcnt vmcnt(8)
	s_waitcnt lgkmcnt(0)
	s_barrier
; #define PG8_STAGE(bufoff, gbase, voff) do { _Pragma("unroll") for (int _i = 0; _i < 2; ++_i) \
;         __builtin_amdgcn_global_load_lds((const unsigned*)((const char*)(gbase) + (voff)[_i]), (LAS unsigned*)(lds + (bufoff) + ldsw + _i * 8192), 16, 0, 0); } while (0)
; #define PG8_LDA(dst, b, h) do { _Pragma("unroll") for (int m = 0; m < 4; ++m) _Pragma("unroll") for (int k = 0; k < 2; ++k) dst[m][k] = *(const LAS bf16x8*)(lds + PG8_SA(b, h) + aoff + m * 2048 + k * 1024); } while (0)
; #define PG8_LDB(dst, b, h) do { _Pragma("unroll") for (int n = 0; n < 2; ++n) _Pragma("unroll") for (int k = 0; k < 2; ++k) dst[n][k] = *(const LAS bf16x8*)(lds + PG8_SB(b, h) + boff + n * 2048 + k * 1024); } while (0)
; #define PG8_WAIT_V(n) asm volatile("s_waitcnt vmcnt(" #n ")" ::: "memory")
; #define PG8_WAIT_L(n) asm volatile("s_waitcnt lgkmcnt(" #n ")" ::: "memory")
; #define PG8_BAR __builtin_amdgcn_s_barrier()
; #define PG8_SCHED __builtin_amdgcn_sched_barrier(0)
; template <class Epi, class Sched, bool SWAPD = false>
; __device__ __forceinline__ void gemm_phase(LAS unsigned char* lds, const Gemm g, const Sched& S, const Epi& E) {
;     ...
;             PG8_WAIT_V(8); PG8_WAIT_L(0); PG8_BAR; PG8_MMA(1, 0, At, B0); PG8_MMA(1, 1, At, B1); PG8_BAR; PG8_SCHED;
;             PG8_LDB(B0, 1, 0); PG8_LDB(B1, 1, 1); PG8_SCHED; PG8_LDA(At, 1, 0); PG8_STAGE(PG8_SA(0, 1), a2 + hstepA, voffA);
;             PG8_WAIT_V(8); PG8_WAIT_L(0); PG8_BAR; PG8_MMA(0, 0, At, B0); PG8_MMA(0, 1, At, B1); PG8_BAR; PG8_SCHED;
	s_setprio 1
	v_mfma_f32_16x16x32_bf16 v[60:63], v[154:157], v[186:189], v[60:63]
	v_mfma_f32_16x16x32_bf16 v[56:59], v[162:165], v[186:189], v[56:59]
	v_mfma_f32_16x16x32_bf16 v[48:51], v[154:157], v[194:197], v[48:51]
	v_mfma_f32_16x16x32_bf16 v[40:43], v[162:165], v[194:197], v[40:43]
	v_mfma_f32_16x16x32_bf16 v[32:35], v[154:157], v[202:205], v[32:35]
	v_mfma_f32_16x16x32_bf16 v[24:27], v[162:165], v[202:205], v[24:27]
	v_mfma_f32_16x16x32_bf16 v[16:19], v[154:157], v[212:215], v[16:19]
	v_mfma_f32_16x16x32_bf16 v[8:11], v[162:165], v[212:215], v[8:11]
	v_mfma_f32_16x16x32_bf16 v[60:63], v[158:161], v[190:193], v[60:63]
	v_mfma_f32_16x16x32_bf16 v[56:59], v[166:169], v[190:193], v[56:59]
	v_mfma_f32_16x16x32_bf16 v[48:51], v[158:161], v[198:201], v[48:51]
	v_mfma_f32_16x16x32_bf16 v[40:43], v[166:169], v[198:201], v[40:43]
	v_mfma_f32_16x16x32_bf16 v[32:35], v[158:161], v[208:211], v[32:35]
	v_mfma_f32_16x16x32_bf16 v[24:27], v[166:169], v[208:211], v[24:27]
	v_mfma_f32_16x16x32_bf16 v[16:19], v[158:161], v[216:219], v[16:19]
	v_mfma_f32_16x16x32_bf16 v[8:11], v[166:169], v[216:219], v[8:11]
	s_setprio 0
	s_setprio 1
	v_mfma_f32_16x16x32_bf16 v[52:55], v[170:173], v[186:189], v[52:55]
	v_mfma_f32_16x16x32_bf16 v[44:47], v[178:181], v[186:189], v[44:47]
	v_mfma_f32_16x16x32_bf16 v[36:39], v[170:173], v[194:197], v[36:39]
	v_mfma_f32_16x16x32_bf16 v[28:31], v[178:181], v[194:197], v[28:31]
	v_mfma_f32_16x16x32_bf16 v[20:23], v[170:173], v[202:205], v[20:23]
	v_mfma_f32_16x16x32_bf16 v[12:15], v[178:181], v[202:205], v[12:15]
	v_mfma_f32_16x16x32_bf16 v[4:7], v[170:173], v[212:215], v[4:7]
	v_mfma_f32_16x16x32_bf16 v[0:3], v[178:181], v[212:215], v[0:3]
	v_mfma_f32_16x16x32_bf16 v[52:55], v[174:177], v[190:193], v[52:55]
	v_mfma_f32_16x16x32_bf16 v[44:47], v[182:185], v[190:193], v[44:47]
	v_mfma_f32_16x16x32_bf16 v[36:39], v[174:177], v[198:201], v[36:39]
	v_mfma_f32_16x16x32_bf16 v[28:31], v[182:185], v[198:201], v[28:31]
	v_mfma_f32_16x16x32_bf16 v[20:23], v[174:177], v[208:211], v[20:23]
	v_mfma_f32_16x16x32_bf16 v[12:15], v[182:185], v[208:211], v[12:15]
	v_mfma_f32_16x16x32_bf16 v[4:7], v[174:177], v[216:219], v[4:7]
	v_mfma_f32_16x16x32_bf16 v[0:3], v[182:185], v[216:219], v[0:3]
	s_setprio 0
	s_barrier
	s_add_i32 s78, 0, 0x18000
	v_add_u32_e32 v136, s78, v149
	s_add_i32 s79, 0, 0x1c000
	ds_read_b128 v[154:157], v136
	ds_read_b128 v[158:161], v136 offset:1024
	ds_read_b128 v[162:165], v136 offset:2048
	ds_read_b128 v[166:169], v136 offset:3072
	v_add_u32_e32 v136, s79, v149
	ds_read_b128 v[170:173], v136
	ds_read_b128 v[174:177], v136 offset:1024
	ds_read_b128 v[178:181], v136 offset:2048
	ds_read_b128 v[182:185], v136 offset:3072
	s_add_u32 s44, s52, 0x80000
	s_addc_u32 s45, s53, 0
	s_mov_b32 m0, s33
	v_lshl_add_u64 v[228:229], s[44:45], 0, v[134:135]
	ds_read_b128 v[186:189], v152 offset:32768
	ds_read_b128 v[190:193], v152 offset:33792
	ds_read_b128 v[194:197], v152 offset:34816
	ds_read_b128 v[198:201], v152 offset:35840
	ds_read_b128 v[202:205], v152 offset:36864
	ds_read_b128 v[208:211], v152 offset:37888
	ds_read_b128 v[212:215], v152 offset:38912
	ds_read_b128 v[216:219], v152 offset:39936
	global_load_lds_dwordx4 v[228:229], off
	v_lshl_add_u64 v[228:229], s[44:45], 0, v[130:131]
	s_mov_b32 m0, s54
	s_nop 0
	global_load_lds_dwordx4 v[228:229], off
	s_waitcnt vmcnt(8)
	s_waitcnt lgkmcnt(0)
	s_barrier
	s_setprio 1
	v_mfma_f32_16x16x32_bf16 v[124:127], v[154:157], v[186:189], v[124:127]
	v_mfma_f32_16x16x32_bf16 v[120:123], v[162:165], v[186:189], v[120:123]
	v_mfma_f32_16x16x32_bf16 v[112:115], v[154:157], v[194:197], v[112:115]
	v_mfma_f32_16x16x32_bf16 v[104:107], v[162:165], v[194:197], v[104:107]
	v_mfma_f32_16x16x32_bf16 v[96:99], v[154:157], v[202:205], v[96:99]
	v_mfma_f32_16x16x32_bf16 v[88:91], v[162:165], v[202:205], v[88:91]
	v_mfma_f32_16x16x32_bf16 v[80:83], v[154:157], v[212:215], v[80:83]
	v_mfma_f32_16x16x32_bf16 v[72:75], v[162:165], v[212:215], v[72:75]
	v_mfma_f32_16x16x32_bf16 v[124:127], v[158:161], v[190:193], v[124:127]
	v_mfma_f32_16x16x32_bf16 v[120:123], v[166:169], v[190:193], v[120:123]
	v_mfma_f32_16x16x32_bf16 v[112:115], v[158:161], v[198:201], v[112:115]
	v_mfma_f32_16x16x32_bf16 v[104:107], v[166:169], v[198:201], v[104:107]
	v_mfma_f32_16x16x32_bf16 v[96:99], v[158:161], v[208:211], v[96:99]
	v_mfma_f32_16x16x32_bf16 v[88:91], v[166:169], v[208:211], v[88:91]
	v_mfma_f32_16x16x32_bf16 v[80:83], v[158:161], v[216:219], v[80:83]
	v_mfma_f32_16x16x32_bf16 v[72:75], v[166:169], v[216:219], v[72:75]
	s_setprio 0
	s_setprio 1
	v_mfma_f32_16x16x32_bf16 v[116:119], v[170:173], v[186:189], v[116:119]
	v_mfma_f32_16x16x32_bf16 v[108:111], v[178:181], v[186:189], v[108:111]
	v_mfma_f32_16x16x32_bf16 v[100:103], v[170:173], v[194:197], v[100:103]
	v_mfma_f32_16x16x32_bf16 v[92:95], v[178:181], v[194:197], v[92:95]
	v_mfma_f32_16x16x32_bf16 v[84:87], v[170:173], v[202:205], v[84:87]
	v_mfma_f32_16x16x32_bf16 v[76:79], v[178:181], v[202:205], v[76:79]
	v_mfma_f32_16x16x32_bf16 v[68:71], v[170:173], v[212:215], v[68:71]
	v_mfma_f32_16x16x32_bf16 v[64:67], v[178:181], v[212:215], v[64:67]
	v_mfma_f32_16x16x32_bf16 v[116:119], v[174:177], v[190:193], v[116:119]
	v_mfma_f32_16x16x32_bf16 v[108:111], v[182:185], v[190:193], v[108:111]
	v_mfma_f32_16x16x32_bf16 v[100:103], v[174:177], v[198:201], v[100:103]
	v_mfma_f32_16x16x32_bf16 v[92:95], v[182:185], v[198:201], v[92:95]
	v_mfma_f32_16x16x32_bf16 v[84:87], v[174:177], v[208:211], v[84:87]
	v_mfma_f32_16x16x32_bf16 v[76:79], v[182:185], v[208:211], v[76:79]
	v_mfma_f32_16x16x32_bf16 v[68:71], v[174:177], v[216:219], v[68:71]
	v_mfma_f32_16x16x32_bf16 v[64:67], v[182:185], v[216:219], v[64:67]
	s_setprio 0
	s_barrier
; #define PG8_STAGE(bufoff, gbase, voff) do { _Pragma("unroll") for (int _i = 0; _i < 2; ++_i) \
;         __builtin_amdgcn_global_load_lds((const unsigned*)((const char*)(gbase) + (voff)[_i]), (LAS unsigned*)(lds + (bufoff) + ldsw + _i * 8192), 16, 0, 0); } while (0)
; #define PG8_LDA(dst, b, h) do { _Pragma("unroll") for (int m = 0; m < 4; ++m) _Pragma("unroll") for (int k = 0; k < 2; ++k) dst[m][k] = *(const LAS bf16x8*)(lds + PG8_SA(b, h) + aoff + m * 2048 + k * 1024); } while (0)
; #define PG8_WAIT_V(n) asm volatile("s_waitcnt vmcnt(" #n ")" ::: "memory")
; #define PG8_WAIT_L(n) asm volatile("s_waitcnt lgkmcnt(" #n ")" ::: "memory")
; #define PG8_BAR __builtin_amdgcn_s_barrier()
; #define PG8_SCHED __builtin_amdgcn_sched_barrier(0)
; template <class Epi, class Sched, bool SWAPD = false>
; __device__ __forceinline__ void gemm_phase(LAS unsigned char* lds, const Gemm g, const Sched& S, const Epi& E) {
;     ...
;             PG8_LDA(At, 1, 1); PG8_STAGE(PG8_SB(1, 0), b3, voffB); PG8_STAGE(PG8_SB(1, 1), b3 + hstepB, voffB); PG8_STAGE(PG8_SA(1, 0), a3, voffA);
;             PG8_WAIT_V(8); PG8_WAIT_L(0); PG8_BAR; PG8_MMA(1, 0, At, B0); PG8_MMA(1, 1, At, B1); PG8_BAR; PG8_SCHED;
;         }
	s_add_i32 s44, s78, s21
	v_lshl_add_u64 v[220:221], v[220:221], 0, s[24:25]
	s_mov_b32 m0, s44
	ds_read_b128 v[186:189], v152 offset:49152
	ds_read_b128 v[190:193], v152 offset:50176
	ds_read_b128 v[194:197], v152 offset:51200
	ds_read_b128 v[198:201], v152 offset:52224
	ds_read_b128 v[202:205], v152 offset:53248
	ds_read_b128 v[208:211], v152 offset:54272
	ds_read_b128 v[212:215], v152 offset:55296
	ds_read_b128 v[216:219], v152 offset:56320
	global_load_lds_dwordx4 v[220:221], off
	s_add_i32 m0, s44, 0x2000
	s_add_u32 s44, s50, 0x20080
	v_lshl_add_u64 v[220:221], v[222:223], 0, s[24:25]
	s_addc_u32 s45, s51, 0
	s_add_i32 s50, s79, s21
	global_load_lds_dwordx4 v[220:221], off
	v_lshl_add_u64 v[220:221], s[44:45], 0, v[132:133]
	s_mov_b32 m0, s50
	s_nop 0
	global_load_lds_dwordx4 v[220:221], off
	v_lshl_add_u64 v[220:221], s[44:45], 0, v[128:129]
	s_add_i32 m0, s50, 0x2000
	s_nop 0
	global_load_lds_dwordx4 v[220:221], off
	v_lshl_add_u64 v[220:221], v[224:225], 0, s[24:25]
	s_mov_b32 m0, s56
	s_nop 0
	global_load_lds_dwordx4 v[220:221], off
	v_lshl_add_u64 v[220:221], v[226:227], 0, s[24:25]
	s_mov_b32 m0, s57
	s_nop 0
	global_load_lds_dwordx4 v[220:221], off
	s_waitcnt vmcnt(8)
	s_waitcnt lgkmcnt(0)
	s_barrier
	s_setprio 1
	v_mfma_f32_16x16x32_bf16 v[60:63], v[154:157], v[186:189], v[60:63]
	v_mfma_f32_16x16x32_bf16 v[56:59], v[162:165], v[186:189], v[56:59]
	v_mfma_f32_16x16x32_bf16 v[48:51], v[154:157], v[194:197], v[48:51]
	v_mfma_f32_16x16x32_bf16 v[40:43], v[162:165], v[194:197], v[40:43]
	v_mfma_f32_16x16x32_bf16 v[32:35], v[154:157], v[202:205], v[32:35]
	v_mfma_f32_16x16x32_bf16 v[24:27], v[162:165], v[202:205], v[24:27]
	v_mfma_f32_16x16x32_bf16 v[16:19], v[154:157], v[212:215], v[16:19]
	v_mfma_f32_16x16x32_bf16 v[8:11], v[162:165], v[212:215], v[8:11]
	v_mfma_f32_16x16x32_bf16 v[60:63], v[158:161], v[190:193], v[60:63]
	v_mfma_f32_16x16x32_bf16 v[56:59], v[166:169], v[190:193], v[56:59]
	v_mfma_f32_16x16x32_bf16 v[48:51], v[158:161], v[198:201], v[48:51]
	v_mfma_f32_16x16x32_bf16 v[40:43], v[166:169], v[198:201], v[40:43]
	v_mfma_f32_16x16x32_bf16 v[32:35], v[158:161], v[208:211], v[32:35]
	v_mfma_f32_16x16x32_bf16 v[24:27], v[166:169], v[208:211], v[24:27]
	v_mfma_f32_16x16x32_bf16 v[16:19], v[158:161], v[216:219], v[16:19]
	v_mfma_f32_16x16x32_bf16 v[8:11], v[166:169], v[216:219], v[8:11]
	s_setprio 0
	s_setprio 1
	v_mfma_f32_16x16x32_bf16 v[52:55], v[170:173], v[186:189], v[52:55]
	v_mfma_f32_16x16x32_bf16 v[44:47], v[178:181], v[186:189], v[44:47]
	v_mfma_f32_16x16x32_bf16 v[36:39], v[170:173], v[194:197], v[36:39]
	v_mfma_f32_16x16x32_bf16 v[28:31], v[178:181], v[194:197], v[28:31]
	v_mfma_f32_16x16x32_bf16 v[20:23], v[170:173], v[202:205], v[20:23]
	v_mfma_f32_16x16x32_bf16 v[12:15], v[178:181], v[202:205], v[12:15]
	v_mfma_f32_16x16x32_bf16 v[4:7], v[170:173], v[212:215], v[4:7]
	v_mfma_f32_16x16x32_bf16 v[0:3], v[178:181], v[212:215], v[0:3]
	v_mfma_f32_16x16x32_bf16 v[52:55], v[174:177], v[190:193], v[52:55]
	v_mfma_f32_16x16x32_bf16 v[44:47], v[182:185], v[190:193], v[44:47]
	v_mfma_f32_16x16x32_bf16 v[36:39], v[174:177], v[198:201], v[36:39]
	v_mfma_f32_16x16x32_bf16 v[28:31], v[182:185], v[198:201], v[28:31]
	v_mfma_f32_16x16x32_bf16 v[20:23], v[174:177], v[208:211], v[20:23]
	v_mfma_f32_16x16x32_bf16 v[12:15], v[182:185], v[208:211], v[12:15]
	v_mfma_f32_16x16x32_bf16 v[4:7], v[174:177], v[216:219], v[4:7]
	v_mfma_f32_16x16x32_bf16 v[0:3], v[182:185], v[216:219], v[0:3]
	s_setprio 0
	s_add_i32 s77, s77, 2
	s_cmp_gt_u32 s77, 5
	s_mov_b64 s[44:45], s[46:47]
	s_barrier
	s_cbranch_scc0 .LBB0_1661
	s_and_b64 vcc, exec, s[26:27]
	s_cbranch_vccz .LBB0_1664
	s_barrier

; #define PG8_STAGE(bufoff, gbase, voff) do { _Pragma("unroll") for (int _i = 0; _i < 2; ++_i) \
;         __builtin_amdgcn_global_load_lds((const unsigned*)((const char*)(gbase) + (voff)[_i]), (LAS unsigned*)(lds + (bufoff) + ldsw + _i * 8192), 16, 0, 0); } while (0)
; #define PG8_LDA(dst, b, h) do { _Pragma("unroll") for (int m = 0; m < 4; ++m) _Pragma("unroll") for (int k = 0; k < 2; ++k) dst[m][k] = *(const LAS bf16x8*)(lds + PG8_SA(b, h) + aoff + m * 2048 + k * 1024); } while (0)
; #define PG8_LDB(dst, b, h) do { _Pragma("unroll") for (int n = 0; n < 2; ++n) _Pragma("unroll") for (int k = 0; k < 2; ++k) dst[n][k] = *(const LAS bf16x8*)(lds + PG8_SB(b, h) + boff + n * 2048 + k * 1024); } while (0)
; #define PG8_WAIT_V(n) asm volatile("s_waitcnt vmcnt(" #n ")" ::: "memory")
; #define PG8_WAIT_L(n) asm volatile("s_waitcnt lgkmcnt(" #n ")" ::: "memory")
; #define PG8_BAR __builtin_amdgcn_s_barrier()
; #define PG8_SCHED __builtin_amdgcn_sched_barrier(0)
; template <class Epi, class Sched, bool SWAPD = false>
; __device__ __forceinline__ void gemm_phase(LAS unsigned char* lds, const Gemm g, const Sched& S, const Epi& E) {
;     ...
;             const bool last = (t == nt - 2);
;             const char* a1 = cA + (size_t)(t + 1) * kstepA;
;             const char* a2 = last ? nA : cA + (size_t)(t + 2) * kstepA; const char* b2 = last ? nB : cB + (size_t)(t + 2) * kstep;
;             const char* a3 = a2 + kstepA; const char* b3 = b2 + kstep;
;             PG8_LDB(B0, 0, 0); PG8_LDB(B1, 0, 1); PG8_SCHED; PG8_LDA(At, 0, 0); PG8_STAGE(PG8_SA(1, 1), a1 + hstepA, voffA);
;             PG8_WAIT_V(8); PG8_WAIT_L(0); PG8_BAR; PG8_MMA(0, 0, At, B0); PG8_MMA(0, 1, At, B1); PG8_BAR; PG8_SCHED;
;             PG8_LDA(At, 0, 1); PG8_STAGE(PG8_SB(0, 0), b2, voffB); PG8_STAGE(PG8_SB(0, 1), b2 + hstepB, voffB); PG8_STAGE(PG8_SA(0, 0), a2, voffA);
.LBB0_1737:
	ds_read_b128 v[104:107], v176
	ds_read_b128 v[108:111], v176 offset:1024
	ds_read_b128 v[124:127], v176 offset:2048
	ds_read_b128 v[128:131], v176 offset:3072
	ds_read_b128 v[180:183], v177
	ds_read_b128 v[184:187], v177 offset:1024
	ds_read_b128 v[188:191], v177 offset:2048
	ds_read_b128 v[192:195], v177 offset:3072
	s_add_u32 s42, s40, 0xfffc0080
	s_addc_u32 s43, s41, -1
	s_cmp_eq_u32 s60, 12
	s_cselect_b32 s45, s23, s43
	s_cselect_b32 s44, s25, s42
	s_cselect_b32 s43, s56, s59
	s_cselect_b32 s42, s57, s58
	v_lshl_add_u64 v[172:173], s[40:41], 0, v[164:165]
	s_add_i32 m0, s30, 0xc000
	ds_read_b128 v[196:199], v178
	ds_read_b128 v[200:203], v178 offset:1024
	ds_read_b128 v[208:211], v178 offset:2048
	ds_read_b128 v[212:215], v178 offset:3072
	ds_read_b128 v[216:219], v178 offset:4096
	ds_read_b128 v[220:223], v178 offset:5120
	ds_read_b128 v[224:227], v178 offset:6144
	ds_read_b128 v[228:231], v178 offset:7168
	global_load_lds_dwordx4 v[172:173], off
	v_lshl_add_u64 v[172:173], s[40:41], 0, v[166:167]
	s_add_i32 m0, s30, 0xe000
	s_nop 0
	global_load_lds_dwordx4 v[172:173], off
	s_waitcnt vmcnt(8)
	s_waitcnt lgkmcnt(0)
	s_barrier
	s_setprio 1
	v_mfma_f32_16x16x32_bf16 v[140:143], v[104:107], v[196:199], v[140:143]
	v_mfma_f32_16x16x32_bf16 v[136:139], v[124:127], v[196:199], v[136:139]
	v_mfma_f32_16x16x32_bf16 v[116:119], v[104:107], v[208:211], v[116:119]
	v_mfma_f32_16x16x32_bf16 v[112:115], v[124:127], v[208:211], v[112:115]
	v_mfma_f32_16x16x32_bf16 v[92:95], v[104:107], v[216:219], v[92:95]
	v_mfma_f32_16x16x32_bf16 v[88:91], v[124:127], v[216:219], v[88:91]
	v_mfma_f32_16x16x32_bf16 v[76:79], v[104:107], v[224:227], v[76:79]
	v_mfma_f32_16x16x32_bf16 v[72:75], v[124:127], v[224:227], v[72:75]
	v_mfma_f32_16x16x32_bf16 v[140:143], v[108:111], v[200:203], v[140:143]
	v_mfma_f32_16x16x32_bf16 v[136:139], v[128:131], v[200:203], v[136:139]
	v_mfma_f32_16x16x32_bf16 v[116:119], v[108:111], v[212:215], v[116:119]
	v_mfma_f32_16x16x32_bf16 v[112:115], v[128:131], v[212:215], v[112:115]
	v_mfma_f32_16x16x32_bf16 v[92:95], v[108:111], v[220:223], v[92:95]
	v_mfma_f32_16x16x32_bf16 v[88:91], v[128:131], v[220:223], v[88:91]
	v_mfma_f32_16x16x32_bf16 v[76:79], v[108:111], v[228:231], v[76:79]
	v_mfma_f32_16x16x32_bf16 v[72:75], v[128:131], v[228:231], v[72:75]
	s_setprio 0
	s_setprio 1
	v_mfma_f32_16x16x32_bf16 v[132:135], v[180:183], v[196:199], v[132:135]
	v_mfma_f32_16x16x32_bf16 v[120:123], v[188:191], v[196:199], v[120:123]
	v_mfma_f32_16x16x32_bf16 v[100:103], v[180:183], v[208:211], v[100:103]
	v_mfma_f32_16x16x32_bf16 v[96:99], v[188:191], v[208:211], v[96:99]
	v_mfma_f32_16x16x32_bf16 v[84:87], v[180:183], v[216:219], v[84:87]
	v_mfma_f32_16x16x32_bf16 v[80:83], v[188:191], v[216:219], v[80:83]
	v_mfma_f32_16x16x32_bf16 v[68:71], v[180:183], v[224:227], v[68:71]
	v_mfma_f32_16x16x32_bf16 v[64:67], v[188:191], v[224:227], v[64:67]
	v_mfma_f32_16x16x32_bf16 v[132:135], v[184:187], v[200:203], v[132:135]
	v_mfma_f32_16x16x32_bf16 v[120:123], v[192:195], v[200:203], v[120:123]
	v_mfma_f32_16x16x32_bf16 v[100:103], v[184:187], v[212:215], v[100:103]
	v_mfma_f32_16x16x32_bf16 v[96:99], v[192:195], v[212:215], v[96:99]
	v_mfma_f32_16x16x32_bf16 v[84:87], v[184:187], v[220:223], v[84:87]
	v_mfma_f32_16x16x32_bf16 v[80:83], v[192:195], v[220:223], v[80:83]
	v_mfma_f32_16x16x32_bf16 v[68:71], v[184:187], v[228:231], v[68:71]
	v_mfma_f32_16x16x32_bf16 v[64:67], v[192:195], v[228:231], v[64:67]
	s_setprio 0
	s_barrier
	s_add_i32 s61, s54, s21
	v_lshl_add_u64 v[172:173], s[42:43], 0, v[144:145]
	s_mov_b32 m0, s61
	ds_read_b128 v[196:199], v178 offset:16384
	ds_read_b128 v[200:203], v178 offset:17408
	ds_read_b128 v[208:211], v178 offset:18432
	ds_read_b128 v[212:215], v178 offset:19456
	ds_read_b128 v[216:219], v178 offset:20480
	ds_read_b128 v[220:223], v178 offset:21504
	ds_read_b128 v[224:227], v178 offset:22528
	ds_read_b128 v[228:231], v178 offset:23552
	global_load_lds_dwordx4 v[172:173], off
	s_add_i32 m0, s61, 0x2000
	s_add_u32 s62, s42, 0x40000
	v_lshl_add_u64 v[204:205], s[42:43], 0, v[146:147]
	s_addc_u32 s63, s43, 0
	s_add_i32 s61, s55, s21
	global_load_lds_dwordx4 v[204:205], off
	v_lshl_add_u64 v[232:233], s[62:63], 0, v[144:145]
	s_mov_b32 m0, s61
	v_lshl_add_u64 v[234:235], s[44:45], 0, v[146:147]
	global_load_lds_dwordx4 v[232:233], off
	v_lshl_add_u64 v[232:233], s[62:63], 0, v[146:147]
	s_add_i32 m0, s61, 0x2000
	s_nop 0
	global_load_lds_dwordx4 v[232:233], off
	v_lshl_add_u64 v[232:233], s[44:45], 0, v[144:145]
	s_mov_b32 m0, s30
	s_nop 0
	global_load_lds_dwordx4 v[232:233], off
	s_mov_b32 m0, s31
	s_nop 0
	global_load_lds_dwordx4 v[234:235], off
	s_waitcnt vmcnt(8)
	s_waitcnt lgkmcnt(0)
	s_barrier
; #define PG8_STAGE(bufoff, gbase, voff) do { _Pragma("unroll") for (int _i = 0; _i < 2; ++_i) \
;         __builtin_amdgcn_global_load_lds((const unsigned*)((const char*)(gbase) + (voff)[_i]), (LAS unsigned*)(lds + (bufoff) + ldsw + _i * 8192), 16, 0, 0); } while (0)
; #define PG8_LDA(dst, b, h) do { _Pragma("unroll") for (int m = 0; m < 4; ++m) _Pragma("unroll") for (int k = 0; k < 2; ++k) dst[m][k] = *(const LAS bf16x8*)(lds + PG8_SA(b, h) + aoff + m * 2048 + k * 1024); } while (0)
; #define PG8_LDB(dst, b, h) do { _Pragma("unroll") for (int n = 0; n < 2; ++n) _Pragma("unroll") for (int k = 0; k < 2; ++k) dst[n][k] = *(const LAS bf16x8*)(lds + PG8_SB(b, h) + boff + n * 2048 + k * 1024); } while (0)
; #define PG8_WAIT_V(n) asm volatile("s_waitcnt vmcnt(" #n ")" ::: "memory")
; #define PG8_WAIT_L(n) asm volatile("s_waitcnt lgkmcnt(" #n ")" ::: "memory")
; #define PG8_BAR __builtin_amdgcn_s_barrier()
; #define PG8_SCHED __builtin_amdgcn_sched_barrier(0)
; template <class Epi, class Sched, bool SWAPD = false>
; __device__ __forceinline__ void gemm_phase(LAS unsigned char* lds, const Gemm g, const Sched& S, const Epi& E) {
;     ...
;             PG8_WAIT_V(8); PG8_WAIT_L(0); PG8_BAR; PG8_MMA(1, 0, At, B0); PG8_MMA(1, 1, At, B1); PG8_BAR; PG8_SCHED;
;             PG8_LDB(B0, 1, 0); PG8_LDB(B1, 1, 1); PG8_SCHED; PG8_LDA(At, 1, 0); PG8_STAGE(PG8_SA(0, 1), a2 + hstepA, voffA);
;             PG8_WAIT_V(8); PG8_WAIT_L(0); PG8_BAR; PG8_MMA(0, 0, At, B0); PG8_MMA(0, 1, At, B1); PG8_BAR; PG8_SCHED;
	s_setprio 1
	v_mfma_f32_16x16x32_bf16 v[60:63], v[104:107], v[196:199], v[60:63]
	v_mfma_f32_16x16x32_bf16 v[56:59], v[124:127], v[196:199], v[56:59]
	v_mfma_f32_16x16x32_bf16 v[44:47], v[104:107], v[208:211], v[44:47]
	v_mfma_f32_16x16x32_bf16 v[40:43], v[124:127], v[208:211], v[40:43]
	v_mfma_f32_16x16x32_bf16 v[28:31], v[104:107], v[216:219], v[28:31]
	v_mfma_f32_16x16x32_bf16 v[24:27], v[124:127], v[216:219], v[24:27]
	v_mfma_f32_16x16x32_bf16 v[12:15], v[104:107], v[224:227], v[12:15]
	v_mfma_f32_16x16x32_bf16 v[8:11], v[124:127], v[224:227], v[8:11]
	v_mfma_f32_16x16x32_bf16 v[60:63], v[108:111], v[200:203], v[60:63]
	v_mfma_f32_16x16x32_bf16 v[56:59], v[128:131], v[200:203], v[56:59]
	v_mfma_f32_16x16x32_bf16 v[44:47], v[108:111], v[212:215], v[44:47]
	v_mfma_f32_16x16x32_bf16 v[40:43], v[128:131], v[212:215], v[40:43]
	v_mfma_f32_16x16x32_bf16 v[28:31], v[108:111], v[220:223], v[28:31]
	v_mfma_f32_16x16x32_bf16 v[24:27], v[128:131], v[220:223], v[24:27]
	v_mfma_f32_16x16x32_bf16 v[12:15], v[108:111], v[228:231], v[12:15]
	v_mfma_f32_16x16x32_bf16 v[8:11], v[128:131], v[228:231], v[8:11]
	s_setprio 0
	s_setprio 1
	v_mfma_f32_16x16x32_bf16 v[52:55], v[180:183], v[196:199], v[52:55]
	v_mfma_f32_16x16x32_bf16 v[48:51], v[188:191], v[196:199], v[48:51]
	v_mfma_f32_16x16x32_bf16 v[36:39], v[180:183], v[208:211], v[36:39]
	v_mfma_f32_16x16x32_bf16 v[32:35], v[188:191], v[208:211], v[32:35]
	v_mfma_f32_16x16x32_bf16 v[20:23], v[180:183], v[216:219], v[20:23]
	v_mfma_f32_16x16x32_bf16 v[16:19], v[188:191], v[216:219], v[16:19]
	v_mfma_f32_16x16x32_bf16 v[4:7], v[180:183], v[224:227], v[4:7]
	v_mfma_f32_16x16x32_bf16 v[0:3], v[188:191], v[224:227], v[0:3]
	v_mfma_f32_16x16x32_bf16 v[52:55], v[184:187], v[200:203], v[52:55]
	v_mfma_f32_16x16x32_bf16 v[48:51], v[192:195], v[200:203], v[48:51]
	v_mfma_f32_16x16x32_bf16 v[36:39], v[184:187], v[212:215], v[36:39]
	v_mfma_f32_16x16x32_bf16 v[32:35], v[192:195], v[212:215], v[32:35]
	v_mfma_f32_16x16x32_bf16 v[20:23], v[184:187], v[220:223], v[20:23]
	v_mfma_f32_16x16x32_bf16 v[16:19], v[192:195], v[220:223], v[16:19]
	v_mfma_f32_16x16x32_bf16 v[4:7], v[184:187], v[228:231], v[4:7]
	v_mfma_f32_16x16x32_bf16 v[0:3], v[192:195], v[228:231], v[0:3]
	s_setprio 0
	s_barrier
	s_add_i32 s61, 0, 0x18000
	s_add_i32 s62, 0, 0x1c000
	v_add_u32_e32 v128, s61, v174
	v_add_u32_e32 v179, s62, v174
	ds_read_b128 v[104:107], v128
	ds_read_b128 v[108:111], v128 offset:1024
	ds_read_b128 v[124:127], v128 offset:2048
	ds_read_b128 v[128:131], v128 offset:3072
	ds_read_b128 v[180:183], v179
	ds_read_b128 v[184:187], v179 offset:1024
	ds_read_b128 v[188:191], v179 offset:2048
	ds_read_b128 v[192:195], v179 offset:3072
	s_add_u32 s44, s44, 0x40000
	s_addc_u32 s45, s45, 0
	s_mov_b32 m0, s33
	v_lshl_add_u64 v[236:237], s[44:45], 0, v[144:145]
	ds_read_b128 v[196:199], v178 offset:32768
	ds_read_b128 v[200:203], v178 offset:33792
	ds_read_b128 v[208:211], v178 offset:34816
	ds_read_b128 v[212:215], v178 offset:35840
	ds_read_b128 v[216:219], v178 offset:36864
	ds_read_b128 v[220:223], v178 offset:37888
	ds_read_b128 v[224:227], v178 offset:38912
	ds_read_b128 v[228:231], v178 offset:39936
	global_load_lds_dwordx4 v[236:237], off
	v_lshl_add_u64 v[236:237], s[44:45], 0, v[146:147]
	s_mov_b32 m0, s46
	s_nop 0
	global_load_lds_dwordx4 v[236:237], off
	s_waitcnt vmcnt(8)
	s_waitcnt lgkmcnt(0)
	s_barrier
	s_setprio 1
	v_mfma_f32_16x16x32_bf16 v[140:143], v[104:107], v[196:199], v[140:143]
	v_mfma_f32_16x16x32_bf16 v[136:139], v[124:127], v[196:199], v[136:139]
	v_mfma_f32_16x16x32_bf16 v[116:119], v[104:107], v[208:211], v[116:119]
	v_mfma_f32_16x16x32_bf16 v[112:115], v[124:127], v[208:211], v[112:115]
	v_mfma_f32_16x16x32_bf16 v[92:95], v[104:107], v[216:219], v[92:95]
	v_mfma_f32_16x16x32_bf16 v[88:91], v[124:127], v[216:219], v[88:91]
	v_mfma_f32_16x16x32_bf16 v[76:79], v[104:107], v[224:227], v[76:79]
	v_mfma_f32_16x16x32_bf16 v[72:75], v[124:127], v[224:227], v[72:75]
	v_mfma_f32_16x16x32_bf16 v[140:143], v[108:111], v[200:203], v[140:143]
	v_mfma_f32_16x16x32_bf16 v[136:139], v[128:131], v[200:203], v[136:139]
	v_mfma_f32_16x16x32_bf16 v[116:119], v[108:111], v[212:215], v[116:119]
	v_mfma_f32_16x16x32_bf16 v[112:115], v[128:131], v[212:215], v[112:115]
	v_mfma_f32_16x16x32_bf16 v[92:95], v[108:111], v[220:223], v[92:95]
	v_mfma_f32_16x16x32_bf16 v[88:91], v[128:131], v[220:223], v[88:91]
	v_mfma_f32_16x16x32_bf16 v[76:79], v[108:111], v[228:231], v[76:79]
	v_mfma_f32_16x16x32_bf16 v[72:75], v[128:131], v[228:231], v[72:75]
	s_setprio 0
	s_setprio 1
	v_mfma_f32_16x16x32_bf16 v[132:135], v[180:183], v[196:199], v[132:135]
	v_mfma_f32_16x16x32_bf16 v[120:123], v[188:191], v[196:199], v[120:123]
	v_mfma_f32_16x16x32_bf16 v[100:103], v[180:183], v[208:211], v[100:103]
	v_mfma_f32_16x16x32_bf16 v[96:99], v[188:191], v[208:211], v[96:99]
	v_mfma_f32_16x16x32_bf16 v[84:87], v[180:183], v[216:219], v[84:87]
	v_mfma_f32_16x16x32_bf16 v[80:83], v[188:191], v[216:219], v[80:83]
	v_mfma_f32_16x16x32_bf16 v[68:71], v[180:183], v[224:227], v[68:71]
	v_mfma_f32_16x16x32_bf16 v[64:67], v[188:191], v[224:227], v[64:67]
	v_mfma_f32_16x16x32_bf16 v[132:135], v[184:187], v[200:203], v[132:135]
	v_mfma_f32_16x16x32_bf16 v[120:123], v[192:195], v[200:203], v[120:123]
	v_mfma_f32_16x16x32_bf16 v[100:103], v[184:187], v[212:215], v[100:103]
	v_mfma_f32_16x16x32_bf16 v[96:99], v[192:195], v[212:215], v[96:99]
	v_mfma_f32_16x16x32_bf16 v[84:87], v[184:187], v[220:223], v[84:87]
	v_mfma_f32_16x16x32_bf16 v[80:83], v[192:195], v[220:223], v[80:83]
	v_mfma_f32_16x16x32_bf16 v[68:71], v[184:187], v[228:231], v[68:71]
	v_mfma_f32_16x16x32_bf16 v[64:67], v[192:195], v[228:231], v[64:67]
	s_setprio 0
	s_barrier
; #define PG8_STAGE(bufoff, gbase, voff) do { _Pragma("unroll") for (int _i = 0; _i < 2; ++_i) \
;         __builtin_amdgcn_global_load_lds((const unsigned*)((const char*)(gbase) + (voff)[_i]), (LAS unsigned*)(lds + (bufoff) + ldsw + _i * 8192), 16, 0, 0); } while (0)
; #define PG8_LDA(dst, b, h) do { _Pragma("unroll") for (int m = 0; m < 4; ++m) _Pragma("unroll") for (int k = 0; k < 2; ++k) dst[m][k] = *(const LAS bf16x8*)(lds + PG8_SA(b, h) + aoff + m * 2048 + k * 1024); } while (0)
; #define PG8_WAIT_V(n) asm volatile("s_waitcnt vmcnt(" #n ")" ::: "memory")
; #define PG8_WAIT_L(n) asm volatile("s_waitcnt lgkmcnt(" #n ")" ::: "memory")
; #define PG8_BAR __builtin_amdgcn_s_barrier()
; #define PG8_SCHED __builtin_amdgcn_sched_barrier(0)
; template <class Epi, class Sched, bool SWAPD = false>
; __device__ __forceinline__ void gemm_phase(LAS unsigned char* lds, const Gemm g, const Sched& S, const Epi& E) {
;     ...
;             PG8_LDA(At, 1, 1); PG8_STAGE(PG8_SB(1, 0), b3, voffB); PG8_STAGE(PG8_SB(1, 1), b3 + hstepB, voffB); PG8_STAGE(PG8_SA(1, 0), a3, voffA);
;             PG8_WAIT_V(8); PG8_WAIT_L(0); PG8_BAR; PG8_MMA(1, 0, At, B0); PG8_MMA(1, 1, At, B1); PG8_BAR; PG8_SCHED;
;         }
	s_add_i32 s44, s61, s21
	v_lshl_add_u64 v[172:173], v[172:173], 0, s[8:9]
	s_mov_b32 m0, s44
	ds_read_b128 v[196:199], v178 offset:49152
	ds_read_b128 v[200:203], v178 offset:50176
	ds_read_b128 v[208:211], v178 offset:51200
	ds_read_b128 v[212:215], v178 offset:52224
	ds_read_b128 v[216:219], v178 offset:53248
	ds_read_b128 v[220:223], v178 offset:54272
	ds_read_b128 v[224:227], v178 offset:55296
	ds_read_b128 v[228:231], v178 offset:56320
	global_load_lds_dwordx4 v[172:173], off
	s_add_i32 m0, s44, 0x2000
	s_add_u32 s42, s42, 0x40080
	v_lshl_add_u64 v[172:173], v[204:205], 0, s[8:9]
	s_addc_u32 s43, s43, 0
	s_add_i32 s44, s62, s21
	global_load_lds_dwordx4 v[172:173], off
	v_lshl_add_u64 v[172:173], s[42:43], 0, v[144:145]
	s_mov_b32 m0, s44
	s_nop 0
	global_load_lds_dwordx4 v[172:173], off
	v_lshl_add_u64 v[172:173], s[42:43], 0, v[146:147]
	s_add_i32 m0, s44, 0x2000
	s_nop 0
	global_load_lds_dwordx4 v[172:173], off
	v_lshl_add_u64 v[172:173], v[232:233], 0, s[8:9]
	s_mov_b32 m0, s52
	s_nop 0
	global_load_lds_dwordx4 v[172:173], off
	v_lshl_add_u64 v[172:173], v[234:235], 0, s[8:9]
	s_mov_b32 m0, s53
	s_nop 0
	global_load_lds_dwordx4 v[172:173], off
	s_waitcnt vmcnt(8)
	s_waitcnt lgkmcnt(0)
	s_barrier
	s_setprio 1
	v_mfma_f32_16x16x32_bf16 v[60:63], v[104:107], v[196:199], v[60:63]
	v_mfma_f32_16x16x32_bf16 v[56:59], v[124:127], v[196:199], v[56:59]
	v_mfma_f32_16x16x32_bf16 v[44:47], v[104:107], v[208:211], v[44:47]
	v_mfma_f32_16x16x32_bf16 v[40:43], v[124:127], v[208:211], v[40:43]
	v_mfma_f32_16x16x32_bf16 v[28:31], v[104:107], v[216:219], v[28:31]
	v_mfma_f32_16x16x32_bf16 v[24:27], v[124:127], v[216:219], v[24:27]
	v_mfma_f32_16x16x32_bf16 v[12:15], v[104:107], v[224:227], v[12:15]
	v_mfma_f32_16x16x32_bf16 v[8:11], v[124:127], v[224:227], v[8:11]
	v_mfma_f32_16x16x32_bf16 v[60:63], v[108:111], v[200:203], v[60:63]
	v_mfma_f32_16x16x32_bf16 v[56:59], v[128:131], v[200:203], v[56:59]
	v_mfma_f32_16x16x32_bf16 v[44:47], v[108:111], v[212:215], v[44:47]
	v_mfma_f32_16x16x32_bf16 v[40:43], v[128:131], v[212:215], v[40:43]
	v_mfma_f32_16x16x32_bf16 v[28:31], v[108:111], v[220:223], v[28:31]
	v_mfma_f32_16x16x32_bf16 v[24:27], v[128:131], v[220:223], v[24:27]
	v_mfma_f32_16x16x32_bf16 v[12:15], v[108:111], v[228:231], v[12:15]
	v_mfma_f32_16x16x32_bf16 v[8:11], v[128:131], v[228:231], v[8:11]
	s_setprio 0
	s_setprio 1
	v_mfma_f32_16x16x32_bf16 v[52:55], v[180:183], v[196:199], v[52:55]
	v_mfma_f32_16x16x32_bf16 v[48:51], v[188:191], v[196:199], v[48:51]
	v_mfma_f32_16x16x32_bf16 v[36:39], v[180:183], v[208:211], v[36:39]
	v_mfma_f32_16x16x32_bf16 v[32:35], v[188:191], v[208:211], v[32:35]
	v_mfma_f32_16x16x32_bf16 v[20:23], v[180:183], v[216:219], v[20:23]
	v_mfma_f32_16x16x32_bf16 v[16:19], v[188:191], v[216:219], v[16:19]
	v_mfma_f32_16x16x32_bf16 v[4:7], v[180:183], v[224:227], v[4:7]
	v_mfma_f32_16x16x32_bf16 v[0:3], v[188:191], v[224:227], v[0:3]
	v_mfma_f32_16x16x32_bf16 v[52:55], v[184:187], v[200:203], v[52:55]
	v_mfma_f32_16x16x32_bf16 v[48:51], v[192:195], v[200:203], v[48:51]
	v_mfma_f32_16x16x32_bf16 v[36:39], v[184:187], v[212:215], v[36:39]
	v_mfma_f32_16x16x32_bf16 v[32:35], v[192:195], v[212:215], v[32:35]
	v_mfma_f32_16x16x32_bf16 v[20:23], v[184:187], v[220:223], v[20:23]
	v_mfma_f32_16x16x32_bf16 v[16:19], v[192:195], v[220:223], v[16:19]
	v_mfma_f32_16x16x32_bf16 v[4:7], v[184:187], v[228:231], v[4:7]
	v_mfma_f32_16x16x32_bf16 v[0:3], v[192:195], v[228:231], v[0:3]
	s_setprio 0
	s_add_i32 s60, s60, 2
	s_add_u32 s40, s40, 0x100
	s_addc_u32 s41, s41, 0
	s_add_u32 s58, s58, 0x100
	s_addc_u32 s59, s59, 0
	s_cmp_gt_u32 s60, 13
	s_barrier
	s_cbranch_scc0 .LBB0_1737
	s_and_b64 vcc, exec, s[12:13]
	s_cbranch_vccz .LBB0_1740
	s_barrier

; #define PG8_STAGE(bufoff, gbase, voff) do { _Pragma("unroll") for (int _i = 0; _i < 2; ++_i) \
;         __builtin_amdgcn_global_load_lds((const unsigned*)((const char*)(gbase) + (voff)[_i]), (LAS unsigned*)(lds + (bufoff) + ldsw + _i * 8192), 16, 0, 0); } while (0)
; #define PG8_LDA(dst, b, h) do { _Pragma("unroll") for (int m = 0; m < 4; ++m) _Pragma("unroll") for (int k = 0; k < 2; ++k) dst[m][k] = *(const LAS bf16x8*)(lds + PG8_SA(b, h) + aoff + m * 2048 + k * 1024); } while (0)
; #define PG8_LDB(dst, b, h) do { _Pragma("unroll") for (int n = 0; n < 2; ++n) _Pragma("unroll") for (int k = 0; k < 2; ++k) dst[n][k] = *(const LAS bf16x8*)(lds + PG8_SB(b, h) + boff + n * 2048 + k * 1024); } while (0)
; #define PG8_WAIT_V(n) asm volatile("s_waitcnt vmcnt(" #n ")" ::: "memory")
; #define PG8_WAIT_L(n) asm volatile("s_waitcnt lgkmcnt(" #n ")" ::: "memory")
; #define PG8_BAR __builtin_amdgcn_s_barrier()
; #define PG8_SCHED __builtin_amdgcn_sched_barrier(0)
; template <class Epi, class Sched, bool SWAPD = false>
; __device__ __forceinline__ void gemm_phase(LAS unsigned char* lds, const Gemm g, const Sched& S, const Epi& E) {
;     ...
;             const bool last = (t == nt - 2);
;             const char* a1 = cA + (size_t)(t + 1) * kstepA;
;             const char* a2 = last ? nA : cA + (size_t)(t + 2) * kstepA; const char* b2 = last ? nB : cB + (size_t)(t + 2) * kstep;
;             const char* a3 = a2 + kstepA; const char* b3 = b2 + kstep;
;             PG8_LDB(B0, 0, 0); PG8_LDB(B1, 0, 1); PG8_SCHED; PG8_LDA(At, 0, 0); PG8_STAGE(PG8_SA(1, 1), a1 + hstepA, voffA);
;             PG8_WAIT_V(8); PG8_WAIT_L(0); PG8_BAR; PG8_MMA(0, 0, At, B0); PG8_MMA(0, 1, At, B1); PG8_BAR; PG8_SCHED;
;             PG8_LDA(At, 0, 1); PG8_STAGE(PG8_SB(0, 0), b2, voffB); PG8_STAGE(PG8_SB(0, 1), b2 + hstepB, voffB); PG8_STAGE(PG8_SA(0, 0), a2, voffA);
.LBB0_1863:
	ds_read_b128 v[148:151], v145
	ds_read_b128 v[152:155], v145 offset:1024
	ds_read_b128 v[156:159], v145 offset:2048
	ds_read_b128 v[160:163], v145 offset:3072
	ds_read_b128 v[164:167], v146
	ds_read_b128 v[168:171], v146 offset:1024
	ds_read_b128 v[172:175], v146 offset:2048
	ds_read_b128 v[176:179], v146 offset:3072
	s_add_u32 s38, s36, 0xfffc0080
	s_addc_u32 s39, s37, -1
	s_cmp_eq_u32 s58, 12
	s_cselect_b32 s41, s21, s39
	s_cselect_b32 s40, s23, s38
	s_cselect_b32 s39, s54, s57
	s_cselect_b32 s38, s55, s56
	v_lshl_add_u64 v[140:141], s[36:37], 0, v[132:133]
	s_add_i32 m0, s35, 0xc000
	ds_read_b128 v[180:183], v147
	ds_read_b128 v[184:187], v147 offset:1024
	ds_read_b128 v[188:191], v147 offset:2048
	ds_read_b128 v[192:195], v147 offset:3072
	ds_read_b128 v[196:199], v147 offset:4096
	ds_read_b128 v[200:203], v147 offset:5120
	ds_read_b128 v[208:211], v147 offset:6144
	ds_read_b128 v[212:215], v147 offset:7168
	global_load_lds_dwordx4 v[140:141], off
	v_lshl_add_u64 v[140:141], s[36:37], 0, v[134:135]
	s_add_i32 m0, s35, 0xe000
	s_nop 0
	global_load_lds_dwordx4 v[140:141], off
	s_waitcnt vmcnt(8)
	s_waitcnt lgkmcnt(0)
	s_barrier
	s_setprio 1
	v_mfma_f32_16x16x32_bf16 v[124:127], v[148:151], v[180:183], v[124:127]
	v_mfma_f32_16x16x32_bf16 v[116:119], v[156:159], v[180:183], v[116:119]
	v_mfma_f32_16x16x32_bf16 v[108:111], v[148:151], v[188:191], v[108:111]
	v_mfma_f32_16x16x32_bf16 v[100:103], v[156:159], v[188:191], v[100:103]
	v_mfma_f32_16x16x32_bf16 v[92:95], v[148:151], v[196:199], v[92:95]
	v_mfma_f32_16x16x32_bf16 v[84:87], v[156:159], v[196:199], v[84:87]
	v_mfma_f32_16x16x32_bf16 v[76:79], v[148:151], v[208:211], v[76:79]
	v_mfma_f32_16x16x32_bf16 v[68:71], v[156:159], v[208:211], v[68:71]
	v_mfma_f32_16x16x32_bf16 v[124:127], v[152:155], v[184:187], v[124:127]
	v_mfma_f32_16x16x32_bf16 v[116:119], v[160:163], v[184:187], v[116:119]
	v_mfma_f32_16x16x32_bf16 v[108:111], v[152:155], v[192:195], v[108:111]
	v_mfma_f32_16x16x32_bf16 v[100:103], v[160:163], v[192:195], v[100:103]
	v_mfma_f32_16x16x32_bf16 v[92:95], v[152:155], v[200:203], v[92:95]
	v_mfma_f32_16x16x32_bf16 v[84:87], v[160:163], v[200:203], v[84:87]
	v_mfma_f32_16x16x32_bf16 v[76:79], v[152:155], v[212:215], v[76:79]
	v_mfma_f32_16x16x32_bf16 v[68:71], v[160:163], v[212:215], v[68:71]
	s_setprio 0
	s_setprio 1
	v_mfma_f32_16x16x32_bf16 v[120:123], v[164:167], v[180:183], v[120:123]
	v_mfma_f32_16x16x32_bf16 v[112:115], v[172:175], v[180:183], v[112:115]
	v_mfma_f32_16x16x32_bf16 v[104:107], v[164:167], v[188:191], v[104:107]
	v_mfma_f32_16x16x32_bf16 v[96:99], v[172:175], v[188:191], v[96:99]
	v_mfma_f32_16x16x32_bf16 v[88:91], v[164:167], v[196:199], v[88:91]
	v_mfma_f32_16x16x32_bf16 v[80:83], v[172:175], v[196:199], v[80:83]
	v_mfma_f32_16x16x32_bf16 v[72:75], v[164:167], v[208:211], v[72:75]
	v_mfma_f32_16x16x32_bf16 v[64:67], v[172:175], v[208:211], v[64:67]
	v_mfma_f32_16x16x32_bf16 v[120:123], v[168:171], v[184:187], v[120:123]
	v_mfma_f32_16x16x32_bf16 v[112:115], v[176:179], v[184:187], v[112:115]
	v_mfma_f32_16x16x32_bf16 v[104:107], v[168:171], v[192:195], v[104:107]
	v_mfma_f32_16x16x32_bf16 v[96:99], v[176:179], v[192:195], v[96:99]
	v_mfma_f32_16x16x32_bf16 v[88:91], v[168:171], v[200:203], v[88:91]
	v_mfma_f32_16x16x32_bf16 v[80:83], v[176:179], v[200:203], v[80:83]
	v_mfma_f32_16x16x32_bf16 v[72:75], v[168:171], v[212:215], v[72:75]
	v_mfma_f32_16x16x32_bf16 v[64:67], v[176:179], v[212:215], v[64:67]
	s_setprio 0
	s_barrier
	s_add_i32 s59, s50, s42
	v_lshl_add_u64 v[140:141], s[38:39], 0, v[130:131]
	s_mov_b32 m0, s59
	ds_read_b128 v[180:183], v147 offset:16384
	ds_read_b128 v[184:187], v147 offset:17408
	ds_read_b128 v[188:191], v147 offset:18432
	ds_read_b128 v[192:195], v147 offset:19456
	ds_read_b128 v[196:199], v147 offset:20480
	ds_read_b128 v[200:203], v147 offset:21504
	ds_read_b128 v[208:211], v147 offset:22528
	ds_read_b128 v[212:215], v147 offset:23552
	global_load_lds_dwordx4 v[140:141], off
	s_add_i32 m0, s59, 0x2000
	s_add_u32 s60, s38, 0x40000
	v_lshl_add_u64 v[204:205], s[38:39], 0, v[128:129]
	s_addc_u32 s61, s39, 0
	s_add_i32 s59, s51, s42
	global_load_lds_dwordx4 v[204:205], off
	v_lshl_add_u64 v[216:217], s[60:61], 0, v[130:131]
	s_mov_b32 m0, s59
	v_lshl_add_u64 v[218:219], s[40:41], 0, v[128:129]
	global_load_lds_dwordx4 v[216:217], off
	v_lshl_add_u64 v[216:217], s[60:61], 0, v[128:129]
	s_add_i32 m0, s59, 0x2000
	s_nop 0
	global_load_lds_dwordx4 v[216:217], off
	v_lshl_add_u64 v[216:217], s[40:41], 0, v[130:131]
	s_mov_b32 m0, s35
	s_nop 0
	global_load_lds_dwordx4 v[216:217], off
	s_mov_b32 m0, s44
	s_nop 0
	global_load_lds_dwordx4 v[218:219], off
	s_waitcnt vmcnt(8)
	s_waitcnt lgkmcnt(0)
	s_barrier
; #define PG8_STAGE(bufoff, gbase, voff) do { _Pragma("unroll") for (int _i = 0; _i < 2; ++_i) \
;         __builtin_amdgcn_global_load_lds((const unsigned*)((const char*)(gbase) + (voff)[_i]), (LAS unsigned*)(lds + (bufoff) + ldsw + _i * 8192), 16, 0, 0); } while (0)
; #define PG8_LDA(dst, b, h) do { _Pragma("unroll") for (int m = 0; m < 4; ++m) _Pragma("unroll") for (int k = 0; k < 2; ++k) dst[m][k] = *(const LAS bf16x8*)(lds + PG8_SA(b, h) + aoff + m * 2048 + k * 1024); } while (0)
; #define PG8_LDB(dst, b, h) do { _Pragma("unroll") for (int n = 0; n < 2; ++n) _Pragma("unroll") for (int k = 0; k < 2; ++k) dst[n][k] = *(const LAS bf16x8*)(lds + PG8_SB(b, h) + boff + n * 2048 + k * 1024); } while (0)
; #define PG8_WAIT_V(n) asm volatile("s_waitcnt vmcnt(" #n ")" ::: "memory")
; #define PG8_WAIT_L(n) asm volatile("s_waitcnt lgkmcnt(" #n ")" ::: "memory")
; #define PG8_BAR __builtin_amdgcn_s_barrier()
; #define PG8_SCHED __builtin_amdgcn_sched_barrier(0)
; template <class Epi, class Sched, bool SWAPD = false>
; __device__ __forceinline__ void gemm_phase(LAS unsigned char* lds, const Gemm g, const Sched& S, const Epi& E) {
;     ...
;             PG8_WAIT_V(8); PG8_WAIT_L(0); PG8_BAR; PG8_MMA(1, 0, At, B0); PG8_MMA(1, 1, At, B1); PG8_BAR; PG8_SCHED;
;             PG8_LDB(B0, 1, 0); PG8_LDB(B1, 1, 1); PG8_SCHED; PG8_LDA(At, 1, 0); PG8_STAGE(PG8_SA(0, 1), a2 + hstepA, voffA);
;             PG8_WAIT_V(8); PG8_WAIT_L(0); PG8_BAR; PG8_MMA(0, 0, At, B0); PG8_MMA(0, 1, At, B1); PG8_BAR; PG8_SCHED;
	s_setprio 1
	v_mfma_f32_16x16x32_bf16 v[60:63], v[148:151], v[180:183], v[60:63]
	v_mfma_f32_16x16x32_bf16 v[52:55], v[156:159], v[180:183], v[52:55]
	v_mfma_f32_16x16x32_bf16 v[44:47], v[148:151], v[188:191], v[44:47]
	v_mfma_f32_16x16x32_bf16 v[36:39], v[156:159], v[188:191], v[36:39]
	v_mfma_f32_16x16x32_bf16 v[28:31], v[148:151], v[196:199], v[28:31]
	v_mfma_f32_16x16x32_bf16 v[20:23], v[156:159], v[196:199], v[20:23]
	v_mfma_f32_16x16x32_bf16 v[12:15], v[148:151], v[208:211], v[12:15]
	v_mfma_f32_16x16x32_bf16 v[4:7], v[156:159], v[208:211], v[4:7]
	v_mfma_f32_16x16x32_bf16 v[60:63], v[152:155], v[184:187], v[60:63]
	v_mfma_f32_16x16x32_bf16 v[52:55], v[160:163], v[184:187], v[52:55]
	v_mfma_f32_16x16x32_bf16 v[44:47], v[152:155], v[192:195], v[44:47]
	v_mfma_f32_16x16x32_bf16 v[36:39], v[160:163], v[192:195], v[36:39]
	v_mfma_f32_16x16x32_bf16 v[28:31], v[152:155], v[200:203], v[28:31]
	v_mfma_f32_16x16x32_bf16 v[20:23], v[160:163], v[200:203], v[20:23]
	v_mfma_f32_16x16x32_bf16 v[12:15], v[152:155], v[212:215], v[12:15]
	v_mfma_f32_16x16x32_bf16 v[4:7], v[160:163], v[212:215], v[4:7]
	s_setprio 0
	s_setprio 1
	v_mfma_f32_16x16x32_bf16 v[56:59], v[164:167], v[180:183], v[56:59]
	v_mfma_f32_16x16x32_bf16 v[48:51], v[172:175], v[180:183], v[48:51]
	v_mfma_f32_16x16x32_bf16 v[40:43], v[164:167], v[188:191], v[40:43]
	v_mfma_f32_16x16x32_bf16 v[32:35], v[172:175], v[188:191], v[32:35]
	v_mfma_f32_16x16x32_bf16 v[24:27], v[164:167], v[196:199], v[24:27]
	v_mfma_f32_16x16x32_bf16 v[16:19], v[172:175], v[196:199], v[16:19]
	v_mfma_f32_16x16x32_bf16 v[8:11], v[164:167], v[208:211], v[8:11]
	v_mfma_f32_16x16x32_bf16 v[0:3], v[172:175], v[208:211], v[0:3]
	v_mfma_f32_16x16x32_bf16 v[56:59], v[168:171], v[184:187], v[56:59]
	v_mfma_f32_16x16x32_bf16 v[48:51], v[176:179], v[184:187], v[48:51]
	v_mfma_f32_16x16x32_bf16 v[40:43], v[168:171], v[192:195], v[40:43]
	v_mfma_f32_16x16x32_bf16 v[32:35], v[176:179], v[192:195], v[32:35]
	v_mfma_f32_16x16x32_bf16 v[24:27], v[168:171], v[200:203], v[24:27]
	v_mfma_f32_16x16x32_bf16 v[16:19], v[176:179], v[200:203], v[16:19]
	v_mfma_f32_16x16x32_bf16 v[8:11], v[168:171], v[212:215], v[8:11]
	v_mfma_f32_16x16x32_bf16 v[0:3], v[176:179], v[212:215], v[0:3]
	s_setprio 0
	s_barrier
	s_add_i32 s59, 0, 0x18000
	s_add_i32 s60, 0, 0x1c000
	v_add_u32_e32 v160, s59, v143
	v_add_u32_e32 v176, s60, v143
	ds_read_b128 v[148:151], v160
	ds_read_b128 v[152:155], v160 offset:1024
	ds_read_b128 v[156:159], v160 offset:2048
	ds_read_b128 v[160:163], v160 offset:3072
	ds_read_b128 v[164:167], v176
	ds_read_b128 v[168:171], v176 offset:1024
	ds_read_b128 v[172:175], v176 offset:2048
	ds_read_b128 v[176:179], v176 offset:3072
	s_add_u32 s40, s40, 0x40000
	s_addc_u32 s41, s41, 0
	s_mov_b32 m0, s45
	v_lshl_add_u64 v[220:221], s[40:41], 0, v[130:131]
	ds_read_b128 v[180:183], v147 offset:32768
	ds_read_b128 v[184:187], v147 offset:33792
	ds_read_b128 v[188:191], v147 offset:34816
	ds_read_b128 v[192:195], v147 offset:35840
	ds_read_b128 v[196:199], v147 offset:36864
	ds_read_b128 v[200:203], v147 offset:37888
	ds_read_b128 v[208:211], v147 offset:38912
	ds_read_b128 v[212:215], v147 offset:39936
	global_load_lds_dwordx4 v[220:221], off
	v_lshl_add_u64 v[220:221], s[40:41], 0, v[128:129]
	s_mov_b32 m0, s46
	s_nop 0
	global_load_lds_dwordx4 v[220:221], off
	s_waitcnt vmcnt(8)
	s_waitcnt lgkmcnt(0)
	s_barrier
	s_setprio 1
	v_mfma_f32_16x16x32_bf16 v[124:127], v[148:151], v[180:183], v[124:127]
	v_mfma_f32_16x16x32_bf16 v[116:119], v[156:159], v[180:183], v[116:119]
	v_mfma_f32_16x16x32_bf16 v[108:111], v[148:151], v[188:191], v[108:111]
	v_mfma_f32_16x16x32_bf16 v[100:103], v[156:159], v[188:191], v[100:103]
	v_mfma_f32_16x16x32_bf16 v[92:95], v[148:151], v[196:199], v[92:95]
	v_mfma_f32_16x16x32_bf16 v[84:87], v[156:159], v[196:199], v[84:87]
	v_mfma_f32_16x16x32_bf16 v[76:79], v[148:151], v[208:211], v[76:79]
	v_mfma_f32_16x16x32_bf16 v[68:71], v[156:159], v[208:211], v[68:71]
	v_mfma_f32_16x16x32_bf16 v[124:127], v[152:155], v[184:187], v[124:127]
	v_mfma_f32_16x16x32_bf16 v[116:119], v[160:163], v[184:187], v[116:119]
	v_mfma_f32_16x16x32_bf16 v[108:111], v[152:155], v[192:195], v[108:111]
	v_mfma_f32_16x16x32_bf16 v[100:103], v[160:163], v[192:195], v[100:103]
	v_mfma_f32_16x16x32_bf16 v[92:95], v[152:155], v[200:203], v[92:95]
	v_mfma_f32_16x16x32_bf16 v[84:87], v[160:163], v[200:203], v[84:87]
	v_mfma_f32_16x16x32_bf16 v[76:79], v[152:155], v[212:215], v[76:79]
	v_mfma_f32_16x16x32_bf16 v[68:71], v[160:163], v[212:215], v[68:71]
	s_setprio 0
	s_setprio 1
	v_mfma_f32_16x16x32_bf16 v[120:123], v[164:167], v[180:183], v[120:123]
	v_mfma_f32_16x16x32_bf16 v[112:115], v[172:175], v[180:183], v[112:115]
	v_mfma_f32_16x16x32_bf16 v[104:107], v[164:167], v[188:191], v[104:107]
	v_mfma_f32_16x16x32_bf16 v[96:99], v[172:175], v[188:191], v[96:99]
	v_mfma_f32_16x16x32_bf16 v[88:91], v[164:167], v[196:199], v[88:91]
	v_mfma_f32_16x16x32_bf16 v[80:83], v[172:175], v[196:199], v[80:83]
	v_mfma_f32_16x16x32_bf16 v[72:75], v[164:167], v[208:211], v[72:75]
	v_mfma_f32_16x16x32_bf16 v[64:67], v[172:175], v[208:211], v[64:67]
	v_mfma_f32_16x16x32_bf16 v[120:123], v[168:171], v[184:187], v[120:123]
	v_mfma_f32_16x16x32_bf16 v[112:115], v[176:179], v[184:187], v[112:115]
	v_mfma_f32_16x16x32_bf16 v[104:107], v[168:171], v[192:195], v[104:107]
	v_mfma_f32_16x16x32_bf16 v[96:99], v[176:179], v[192:195], v[96:99]
	v_mfma_f32_16x16x32_bf16 v[88:91], v[168:171], v[200:203], v[88:91]
	v_mfma_f32_16x16x32_bf16 v[80:83], v[176:179], v[200:203], v[80:83]
	v_mfma_f32_16x16x32_bf16 v[72:75], v[168:171], v[212:215], v[72:75]
	v_mfma_f32_16x16x32_bf16 v[64:67], v[176:179], v[212:215], v[64:67]
	s_setprio 0
	s_barrier
; #define PG8_STAGE(bufoff, gbase, voff) do { _Pragma("unroll") for (int _i = 0; _i < 2; ++_i) \
;         __builtin_amdgcn_global_load_lds((const unsigned*)((const char*)(gbase) + (voff)[_i]), (LAS unsigned*)(lds + (bufoff) + ldsw + _i * 8192), 16, 0, 0); } while (0)
; #define PG8_LDA(dst, b, h) do { _Pragma("unroll") for (int m = 0; m < 4; ++m) _Pragma("unroll") for (int k = 0; k < 2; ++k) dst[m][k] = *(const LAS bf16x8*)(lds + PG8_SA(b, h) + aoff + m * 2048 + k * 1024); } while (0)
; #define PG8_WAIT_V(n) asm volatile("s_waitcnt vmcnt(" #n ")" ::: "memory")
; #define PG8_WAIT_L(n) asm volatile("s_waitcnt lgkmcnt(" #n ")" ::: "memory")
; #define PG8_BAR __builtin_amdgcn_s_barrier()
; #define PG8_SCHED __builtin_amdgcn_sched_barrier(0)
; template <class Epi, class Sched, bool SWAPD = false>
; __device__ __forceinline__ void gemm_phase(LAS unsigned char* lds, const Gemm g, const Sched& S, const Epi& E) {
;     ...
;             PG8_LDA(At, 1, 1); PG8_STAGE(PG8_SB(1, 0), b3, voffB); PG8_STAGE(PG8_SB(1, 1), b3 + hstepB, voffB); PG8_STAGE(PG8_SA(1, 0), a3, voffA);
;             PG8_WAIT_V(8); PG8_WAIT_L(0); PG8_BAR; PG8_MMA(1, 0, At, B0); PG8_MMA(1, 1, At, B1); PG8_BAR; PG8_SCHED;
;         }
	s_add_i32 s40, s59, s42
	v_lshl_add_u64 v[140:141], v[140:141], 0, s[8:9]
	s_mov_b32 m0, s40
	ds_read_b128 v[180:183], v147 offset:49152
	ds_read_b128 v[184:187], v147 offset:50176
	ds_read_b128 v[188:191], v147 offset:51200
	ds_read_b128 v[192:195], v147 offset:52224
	ds_read_b128 v[196:199], v147 offset:53248
	ds_read_b128 v[200:203], v147 offset:54272
	ds_read_b128 v[208:211], v147 offset:55296
	ds_read_b128 v[212:215], v147 offset:56320
	global_load_lds_dwordx4 v[140:141], off
	s_add_i32 m0, s40, 0x2000
	s_add_u32 s38, s38, 0x40080
	v_lshl_add_u64 v[140:141], v[204:205], 0, s[8:9]
	s_addc_u32 s39, s39, 0
	s_add_i32 s40, s60, s42
	global_load_lds_dwordx4 v[140:141], off
	v_lshl_add_u64 v[140:141], s[38:39], 0, v[130:131]
	s_mov_b32 m0, s40
	s_nop 0
	global_load_lds_dwordx4 v[140:141], off
	v_lshl_add_u64 v[140:141], s[38:39], 0, v[128:129]
	s_add_i32 m0, s40, 0x2000
	s_nop 0
	global_load_lds_dwordx4 v[140:141], off
	v_lshl_add_u64 v[140:141], v[216:217], 0, s[8:9]
	s_mov_b32 m0, s48
	s_nop 0
	global_load_lds_dwordx4 v[140:141], off
	v_lshl_add_u64 v[140:141], v[218:219], 0, s[8:9]
	s_mov_b32 m0, s49
	s_nop 0
	global_load_lds_dwordx4 v[140:141], off
	s_waitcnt vmcnt(8)
	s_waitcnt lgkmcnt(0)
	s_barrier
	s_setprio 1
	v_mfma_f32_16x16x32_bf16 v[60:63], v[148:151], v[180:183], v[60:63]
	v_mfma_f32_16x16x32_bf16 v[52:55], v[156:159], v[180:183], v[52:55]
	v_mfma_f32_16x16x32_bf16 v[44:47], v[148:151], v[188:191], v[44:47]
	v_mfma_f32_16x16x32_bf16 v[36:39], v[156:159], v[188:191], v[36:39]
	v_mfma_f32_16x16x32_bf16 v[28:31], v[148:151], v[196:199], v[28:31]
	v_mfma_f32_16x16x32_bf16 v[20:23], v[156:159], v[196:199], v[20:23]
	v_mfma_f32_16x16x32_bf16 v[12:15], v[148:151], v[208:211], v[12:15]
	v_mfma_f32_16x16x32_bf16 v[4:7], v[156:159], v[208:211], v[4:7]
	v_mfma_f32_16x16x32_bf16 v[60:63], v[152:155], v[184:187], v[60:63]
	v_mfma_f32_16x16x32_bf16 v[52:55], v[160:163], v[184:187], v[52:55]
	v_mfma_f32_16x16x32_bf16 v[44:47], v[152:155], v[192:195], v[44:47]
	v_mfma_f32_16x16x32_bf16 v[36:39], v[160:163], v[192:195], v[36:39]
	v_mfma_f32_16x16x32_bf16 v[28:31], v[152:155], v[200:203], v[28:31]
	v_mfma_f32_16x16x32_bf16 v[20:23], v[160:163], v[200:203], v[20:23]
	v_mfma_f32_16x16x32_bf16 v[12:15], v[152:155], v[212:215], v[12:15]
	v_mfma_f32_16x16x32_bf16 v[4:7], v[160:163], v[212:215], v[4:7]
	s_setprio 0
	s_setprio 1
	v_mfma_f32_16x16x32_bf16 v[56:59], v[164:167], v[180:183], v[56:59]
	v_mfma_f32_16x16x32_bf16 v[48:51], v[172:175], v[180:183], v[48:51]
	v_mfma_f32_16x16x32_bf16 v[40:43], v[164:167], v[188:191], v[40:43]
	v_mfma_f32_16x16x32_bf16 v[32:35], v[172:175], v[188:191], v[32:35]
	v_mfma_f32_16x16x32_bf16 v[24:27], v[164:167], v[196:199], v[24:27]
	v_mfma_f32_16x16x32_bf16 v[16:19], v[172:175], v[196:199], v[16:19]
	v_mfma_f32_16x16x32_bf16 v[8:11], v[164:167], v[208:211], v[8:11]
	v_mfma_f32_16x16x32_bf16 v[0:3], v[172:175], v[208:211], v[0:3]
	v_mfma_f32_16x16x32_bf16 v[56:59], v[168:171], v[184:187], v[56:59]
	v_mfma_f32_16x16x32_bf16 v[48:51], v[176:179], v[184:187], v[48:51]
	v_mfma_f32_16x16x32_bf16 v[40:43], v[168:171], v[192:195], v[40:43]
	v_mfma_f32_16x16x32_bf16 v[32:35], v[176:179], v[192:195], v[32:35]
	v_mfma_f32_16x16x32_bf16 v[24:27], v[168:171], v[200:203], v[24:27]
	v_mfma_f32_16x16x32_bf16 v[16:19], v[176:179], v[200:203], v[16:19]
	v_mfma_f32_16x16x32_bf16 v[8:11], v[168:171], v[212:215], v[8:11]
	v_mfma_f32_16x16x32_bf16 v[0:3], v[176:179], v[212:215], v[0:3]
	s_setprio 0
	s_add_i32 s58, s58, 2
	s_add_u32 s36, s36, 0x100
	s_addc_u32 s37, s37, 0
	s_add_u32 s56, s56, 0x100
	s_addc_u32 s57, s57, 0
	s_cmp_gt_u32 s58, 13
	s_barrier
	s_cbranch_scc0 .LBB0_1863
	s_and_b64 vcc, exec, s[10:11]
	s_cbranch_vccz .LBB0_1866
	s_barrier

; #define PG8_STAGE(bufoff, gbase, voff) do { _Pragma("unroll") for (int _i = 0; _i < 2; ++_i) \
;         __builtin_amdgcn_global_load_lds((const unsigned*)((const char*)(gbase) + (voff)[_i]), (LAS unsigned*)(lds + (bufoff) + ldsw + _i * 8192), 16, 0, 0); } while (0)
; #define PG8_LDA(dst, b, h) do { _Pragma("unroll") for (int m = 0; m < 4; ++m) _Pragma("unroll") for (int k = 0; k < 2; ++k) dst[m][k] = *(const LAS bf16x8*)(lds + PG8_SA(b, h) + aoff + m * 2048 + k * 1024); } while (0)
; #define PG8_LDB(dst, b, h) do { _Pragma("unroll") for (int n = 0; n < 2; ++n) _Pragma("unroll") for (int k = 0; k < 2; ++k) dst[n][k] = *(const LAS bf16x8*)(lds + PG8_SB(b, h) + boff + n * 2048 + k * 1024); } while (0)
; #define PG8_WAIT_V(n) asm volatile("s_waitcnt vmcnt(" #n ")" ::: "memory")
; #define PG8_WAIT_L(n) asm volatile("s_waitcnt lgkmcnt(" #n ")" ::: "memory")
; #define PG8_BAR __builtin_amdgcn_s_barrier()
; #define PG8_SCHED __builtin_amdgcn_sched_barrier(0)
; template <class Epi, class Sched, bool SWAPD = false>
; __device__ __forceinline__ void gemm_phase(LAS unsigned char* lds, const Gemm g, const Sched& S, const Epi& E) {
;     ...
;             const bool last = (t == nt - 2);
;             const char* a1 = cA + (size_t)(t + 1) * kstepA;
;             const char* a2 = last ? nA : cA + (size_t)(t + 2) * kstepA; const char* b2 = last ? nB : cB + (size_t)(t + 2) * kstep;
;             const char* a3 = a2 + kstepA; const char* b3 = b2 + kstep;
;             PG8_LDB(B0, 0, 0); PG8_LDB(B1, 0, 1); PG8_SCHED; PG8_LDA(At, 0, 0); PG8_STAGE(PG8_SA(1, 1), a1 + hstepA, voffA);
;             PG8_WAIT_V(8); PG8_WAIT_L(0); PG8_BAR; PG8_MMA(0, 0, At, B0); PG8_MMA(0, 1, At, B1); PG8_BAR; PG8_SCHED;
;             PG8_LDA(At, 0, 1); PG8_STAGE(PG8_SB(0, 0), b2, voffB); PG8_STAGE(PG8_SB(0, 1), b2 + hstepB, voffB); PG8_STAGE(PG8_SA(0, 0), a2, voffA);
.LBB0_1940:
	ds_read_b128 v[156:159], v168
	ds_read_b128 v[160:163], v168 offset:1024
	ds_read_b128 v[172:175], v168 offset:2048
	ds_read_b128 v[176:179], v168 offset:3072
	ds_read_b128 v[180:183], v169
	ds_read_b128 v[184:187], v169 offset:1024
	ds_read_b128 v[188:191], v169 offset:2048
	ds_read_b128 v[192:195], v169 offset:3072
	s_add_u32 s22, s20, 0x100
	s_addc_u32 s23, s21, 0
	s_cmp_eq_u32 s53, 40
	s_cselect_b32 s27, s47, s23
	s_cselect_b32 s26, s48, s22
	s_cselect_b32 s25, s49, s52
	s_cselect_b32 s24, s50, s51
	v_lshl_add_u64 v[164:165], s[20:21], 0, v[148:149]
	s_add_i32 m0, s31, 0xc000
	ds_read_b128 v[196:199], v170
	ds_read_b128 v[200:203], v170 offset:1024
	ds_read_b128 v[204:207], v170 offset:2048
	ds_read_b128 v[208:211], v170 offset:3072
	ds_read_b128 v[212:215], v170 offset:4096
	ds_read_b128 v[216:219], v170 offset:5120
	ds_read_b128 v[220:223], v170 offset:6144
	ds_read_b128 v[224:227], v170 offset:7168
	global_load_lds_dwordx4 v[164:165], off
	v_lshl_add_u64 v[164:165], s[20:21], 0, v[150:151]
	s_add_i32 m0, s31, 0xe000
	s_nop 0
	global_load_lds_dwordx4 v[164:165], off
	s_waitcnt vmcnt(8)
	s_waitcnt lgkmcnt(0)
	s_barrier
	s_setprio 1
	v_mfma_f32_16x16x32_bf16 v[124:127], v[156:159], v[196:199], v[124:127]
	v_mfma_f32_16x16x32_bf16 v[120:123], v[172:175], v[196:199], v[120:123]
	v_mfma_f32_16x16x32_bf16 v[108:111], v[156:159], v[204:207], v[108:111]
	v_mfma_f32_16x16x32_bf16 v[104:107], v[172:175], v[204:207], v[104:107]
	v_mfma_f32_16x16x32_bf16 v[92:95], v[156:159], v[212:215], v[92:95]
	v_mfma_f32_16x16x32_bf16 v[88:91], v[172:175], v[212:215], v[88:91]
	v_mfma_f32_16x16x32_bf16 v[76:79], v[156:159], v[220:223], v[76:79]
	v_mfma_f32_16x16x32_bf16 v[72:75], v[172:175], v[220:223], v[72:75]
	v_mfma_f32_16x16x32_bf16 v[124:127], v[160:163], v[200:203], v[124:127]
	v_mfma_f32_16x16x32_bf16 v[120:123], v[176:179], v[200:203], v[120:123]
	v_mfma_f32_16x16x32_bf16 v[108:111], v[160:163], v[208:211], v[108:111]
	v_mfma_f32_16x16x32_bf16 v[104:107], v[176:179], v[208:211], v[104:107]
	v_mfma_f32_16x16x32_bf16 v[92:95], v[160:163], v[216:219], v[92:95]
	v_mfma_f32_16x16x32_bf16 v[88:91], v[176:179], v[216:219], v[88:91]
	v_mfma_f32_16x16x32_bf16 v[76:79], v[160:163], v[224:227], v[76:79]
	v_mfma_f32_16x16x32_bf16 v[72:75], v[176:179], v[224:227], v[72:75]
	s_setprio 0
	s_setprio 1
	v_mfma_f32_16x16x32_bf16 v[116:119], v[180:183], v[196:199], v[116:119]
	v_mfma_f32_16x16x32_bf16 v[112:115], v[188:191], v[196:199], v[112:115]
	v_mfma_f32_16x16x32_bf16 v[100:103], v[180:183], v[204:207], v[100:103]
	v_mfma_f32_16x16x32_bf16 v[96:99], v[188:191], v[204:207], v[96:99]
	v_mfma_f32_16x16x32_bf16 v[84:87], v[180:183], v[212:215], v[84:87]
	v_mfma_f32_16x16x32_bf16 v[80:83], v[188:191], v[212:215], v[80:83]
	v_mfma_f32_16x16x32_bf16 v[68:71], v[180:183], v[220:223], v[68:71]
	v_mfma_f32_16x16x32_bf16 v[64:67], v[188:191], v[220:223], v[64:67]
	v_mfma_f32_16x16x32_bf16 v[116:119], v[184:187], v[200:203], v[116:119]
	v_mfma_f32_16x16x32_bf16 v[112:115], v[192:195], v[200:203], v[112:115]
	v_mfma_f32_16x16x32_bf16 v[100:103], v[184:187], v[208:211], v[100:103]
	v_mfma_f32_16x16x32_bf16 v[96:99], v[192:195], v[208:211], v[96:99]
	v_mfma_f32_16x16x32_bf16 v[84:87], v[184:187], v[216:219], v[84:87]
	v_mfma_f32_16x16x32_bf16 v[80:83], v[192:195], v[216:219], v[80:83]
	v_mfma_f32_16x16x32_bf16 v[68:71], v[184:187], v[224:227], v[68:71]
	v_mfma_f32_16x16x32_bf16 v[64:67], v[192:195], v[224:227], v[64:67]
	s_setprio 0
	s_barrier
	s_add_i32 s20, s41, s30
	v_lshl_add_u64 v[164:165], s[24:25], 0, v[128:129]
	s_mov_b32 m0, s20
	ds_read_b128 v[196:199], v170 offset:16384
	ds_read_b128 v[200:203], v170 offset:17408
	ds_read_b128 v[204:207], v170 offset:18432
	ds_read_b128 v[208:211], v170 offset:19456
	ds_read_b128 v[212:215], v170 offset:20480
	ds_read_b128 v[216:219], v170 offset:21504
	ds_read_b128 v[220:223], v170 offset:22528
	ds_read_b128 v[224:227], v170 offset:23552
	global_load_lds_dwordx4 v[164:165], off
	s_add_i32 m0, s20, 0x2000
	s_add_u32 s20, s24, 0xb0000
	v_lshl_add_u64 v[228:229], s[24:25], 0, v[130:131]
	s_addc_u32 s21, s25, 0
	s_add_i32 s54, s42, s30
	global_load_lds_dwordx4 v[228:229], off
	v_lshl_add_u64 v[230:231], s[20:21], 0, v[128:129]
	s_mov_b32 m0, s54
	v_lshl_add_u64 v[232:233], s[26:27], 0, v[130:131]
	global_load_lds_dwordx4 v[230:231], off
	v_lshl_add_u64 v[230:231], s[20:21], 0, v[130:131]
	s_add_i32 m0, s54, 0x2000
	s_nop 0
	global_load_lds_dwordx4 v[230:231], off
	v_lshl_add_u64 v[230:231], s[26:27], 0, v[128:129]
	s_mov_b32 m0, s31
	s_nop 0
	global_load_lds_dwordx4 v[230:231], off
	s_mov_b32 m0, s33
	s_nop 0
	global_load_lds_dwordx4 v[232:233], off
	s_waitcnt vmcnt(8)
	s_waitcnt lgkmcnt(0)
	s_barrier
; #define PG8_STAGE(bufoff, gbase, voff) do { _Pragma("unroll") for (int _i = 0; _i < 2; ++_i) \
;         __builtin_amdgcn_global_load_lds((const unsigned*)((const char*)(gbase) + (voff)[_i]), (LAS unsigned*)(lds + (bufoff) + ldsw + _i * 8192), 16, 0, 0); } while (0)
; #define PG8_LDA(dst, b, h) do { _Pragma("unroll") for (int m = 0; m < 4; ++m) _Pragma("unroll") for (int k = 0; k < 2; ++k) dst[m][k] = *(const LAS bf16x8*)(lds + PG8_SA(b, h) + aoff + m * 2048 + k * 1024); } while (0)
; #define PG8_LDB(dst, b, h) do { _Pragma("unroll") for (int n = 0; n < 2; ++n) _Pragma("unroll") for (int k = 0; k < 2; ++k) dst[n][k] = *(const LAS bf16x8*)(lds + PG8_SB(b, h) + boff + n * 2048 + k * 1024); } while (0)
; #define PG8_WAIT_V(n) asm volatile("s_waitcnt vmcnt(" #n ")" ::: "memory")
; #define PG8_WAIT_L(n) asm volatile("s_waitcnt lgkmcnt(" #n ")" ::: "memory")
; #define PG8_BAR __builtin_amdgcn_s_barrier()
; #define PG8_SCHED __builtin_amdgcn_sched_barrier(0)
; template <class Epi, class Sched, bool SWAPD = false>
; __device__ __forceinline__ void gemm_phase(LAS unsigned char* lds, const Gemm g, const Sched& S, const Epi& E) {
;     ...
;             PG8_WAIT_V(8); PG8_WAIT_L(0); PG8_BAR; PG8_MMA(1, 0, At, B0); PG8_MMA(1, 1, At, B1); PG8_BAR; PG8_SCHED;
;             PG8_LDB(B0, 1, 0); PG8_LDB(B1, 1, 1); PG8_SCHED; PG8_LDA(At, 1, 0); PG8_STAGE(PG8_SA(0, 1), a2 + hstepA, voffA);
;             PG8_WAIT_V(8); PG8_WAIT_L(0); PG8_BAR; PG8_MMA(0, 0, At, B0); PG8_MMA(0, 1, At, B1); PG8_BAR; PG8_SCHED;
	s_setprio 1
	v_mfma_f32_16x16x32_bf16 v[60:63], v[156:159], v[196:199], v[60:63]
	v_mfma_f32_16x16x32_bf16 v[56:59], v[172:175], v[196:199], v[56:59]
	v_mfma_f32_16x16x32_bf16 v[44:47], v[156:159], v[204:207], v[44:47]
	v_mfma_f32_16x16x32_bf16 v[40:43], v[172:175], v[204:207], v[40:43]
	v_mfma_f32_16x16x32_bf16 v[28:31], v[156:159], v[212:215], v[28:31]
	v_mfma_f32_16x16x32_bf16 v[24:27], v[172:175], v[212:215], v[24:27]
	v_mfma_f32_16x16x32_bf16 v[12:15], v[156:159], v[220:223], v[12:15]
	v_mfma_f32_16x16x32_bf16 v[8:11], v[172:175], v[220:223], v[8:11]
	v_mfma_f32_16x16x32_bf16 v[60:63], v[160:163], v[200:203], v[60:63]
	v_mfma_f32_16x16x32_bf16 v[56:59], v[176:179], v[200:203], v[56:59]
	v_mfma_f32_16x16x32_bf16 v[44:47], v[160:163], v[208:211], v[44:47]
	v_mfma_f32_16x16x32_bf16 v[40:43], v[176:179], v[208:211], v[40:43]
	v_mfma_f32_16x16x32_bf16 v[28:31], v[160:163], v[216:219], v[28:31]
	v_mfma_f32_16x16x32_bf16 v[24:27], v[176:179], v[216:219], v[24:27]
	v_mfma_f32_16x16x32_bf16 v[12:15], v[160:163], v[224:227], v[12:15]
	v_mfma_f32_16x16x32_bf16 v[8:11], v[176:179], v[224:227], v[8:11]
	s_setprio 0
	s_setprio 1
	v_mfma_f32_16x16x32_bf16 v[52:55], v[180:183], v[196:199], v[52:55]
	v_mfma_f32_16x16x32_bf16 v[48:51], v[188:191], v[196:199], v[48:51]
	v_mfma_f32_16x16x32_bf16 v[36:39], v[180:183], v[204:207], v[36:39]
	v_mfma_f32_16x16x32_bf16 v[32:35], v[188:191], v[204:207], v[32:35]
	v_mfma_f32_16x16x32_bf16 v[20:23], v[180:183], v[212:215], v[20:23]
	v_mfma_f32_16x16x32_bf16 v[16:19], v[188:191], v[212:215], v[16:19]
	v_mfma_f32_16x16x32_bf16 v[4:7], v[180:183], v[220:223], v[4:7]
	v_mfma_f32_16x16x32_bf16 v[0:3], v[188:191], v[220:223], v[0:3]
	v_mfma_f32_16x16x32_bf16 v[52:55], v[184:187], v[200:203], v[52:55]
	v_mfma_f32_16x16x32_bf16 v[48:51], v[192:195], v[200:203], v[48:51]
	v_mfma_f32_16x16x32_bf16 v[36:39], v[184:187], v[208:211], v[36:39]
	v_mfma_f32_16x16x32_bf16 v[32:35], v[192:195], v[208:211], v[32:35]
	v_mfma_f32_16x16x32_bf16 v[20:23], v[184:187], v[216:219], v[20:23]
	v_mfma_f32_16x16x32_bf16 v[16:19], v[192:195], v[216:219], v[16:19]
	v_mfma_f32_16x16x32_bf16 v[4:7], v[184:187], v[224:227], v[4:7]
	v_mfma_f32_16x16x32_bf16 v[0:3], v[192:195], v[224:227], v[0:3]
	s_setprio 0
	s_barrier
	s_add_i32 s54, 0, 0x18000
	v_add_u32_e32 v171, s54, v166
	s_add_i32 s55, 0, 0x1c000
	ds_read_b128 v[156:159], v171
	ds_read_b128 v[160:163], v171 offset:1024
	ds_read_b128 v[172:175], v171 offset:2048
	ds_read_b128 v[176:179], v171 offset:3072
	v_add_u32_e32 v171, s55, v166
	ds_read_b128 v[180:183], v171
	ds_read_b128 v[184:187], v171 offset:1024
	ds_read_b128 v[188:191], v171 offset:2048
	ds_read_b128 v[192:195], v171 offset:3072
	s_add_u32 s20, s26, 0xb0000
	s_addc_u32 s21, s27, 0
	s_mov_b32 m0, s34
	v_lshl_add_u64 v[234:235], s[20:21], 0, v[128:129]
	ds_read_b128 v[196:199], v170 offset:32768
	ds_read_b128 v[200:203], v170 offset:33792
	ds_read_b128 v[204:207], v170 offset:34816
	ds_read_b128 v[208:211], v170 offset:35840
	ds_read_b128 v[212:215], v170 offset:36864
	ds_read_b128 v[216:219], v170 offset:37888
	ds_read_b128 v[220:223], v170 offset:38912
	ds_read_b128 v[224:227], v170 offset:39936
	global_load_lds_dwordx4 v[234:235], off
	v_lshl_add_u64 v[234:235], s[20:21], 0, v[130:131]
	s_mov_b32 m0, s35
	s_nop 0
	global_load_lds_dwordx4 v[234:235], off
	s_waitcnt vmcnt(8)
	s_waitcnt lgkmcnt(0)
	s_barrier
	s_setprio 1
	v_mfma_f32_16x16x32_bf16 v[124:127], v[156:159], v[196:199], v[124:127]
	v_mfma_f32_16x16x32_bf16 v[120:123], v[172:175], v[196:199], v[120:123]
	v_mfma_f32_16x16x32_bf16 v[108:111], v[156:159], v[204:207], v[108:111]
	v_mfma_f32_16x16x32_bf16 v[104:107], v[172:175], v[204:207], v[104:107]
	v_mfma_f32_16x16x32_bf16 v[92:95], v[156:159], v[212:215], v[92:95]
	v_mfma_f32_16x16x32_bf16 v[88:91], v[172:175], v[212:215], v[88:91]
	v_mfma_f32_16x16x32_bf16 v[76:79], v[156:159], v[220:223], v[76:79]
	v_mfma_f32_16x16x32_bf16 v[72:75], v[172:175], v[220:223], v[72:75]
	v_mfma_f32_16x16x32_bf16 v[124:127], v[160:163], v[200:203], v[124:127]
	v_mfma_f32_16x16x32_bf16 v[120:123], v[176:179], v[200:203], v[120:123]
	v_mfma_f32_16x16x32_bf16 v[108:111], v[160:163], v[208:211], v[108:111]
	v_mfma_f32_16x16x32_bf16 v[104:107], v[176:179], v[208:211], v[104:107]
	v_mfma_f32_16x16x32_bf16 v[92:95], v[160:163], v[216:219], v[92:95]
	v_mfma_f32_16x16x32_bf16 v[88:91], v[176:179], v[216:219], v[88:91]
	v_mfma_f32_16x16x32_bf16 v[76:79], v[160:163], v[224:227], v[76:79]
	v_mfma_f32_16x16x32_bf16 v[72:75], v[176:179], v[224:227], v[72:75]
	s_setprio 0
	s_setprio 1
	v_mfma_f32_16x16x32_bf16 v[116:119], v[180:183], v[196:199], v[116:119]
	v_mfma_f32_16x16x32_bf16 v[112:115], v[188:191], v[196:199], v[112:115]
	v_mfma_f32_16x16x32_bf16 v[100:103], v[180:183], v[204:207], v[100:103]
	v_mfma_f32_16x16x32_bf16 v[96:99], v[188:191], v[204:207], v[96:99]
	v_mfma_f32_16x16x32_bf16 v[84:87], v[180:183], v[212:215], v[84:87]
	v_mfma_f32_16x16x32_bf16 v[80:83], v[188:191], v[212:215], v[80:83]
	v_mfma_f32_16x16x32_bf16 v[68:71], v[180:183], v[220:223], v[68:71]
	v_mfma_f32_16x16x32_bf16 v[64:67], v[188:191], v[220:223], v[64:67]
	v_mfma_f32_16x16x32_bf16 v[116:119], v[184:187], v[200:203], v[116:119]
	v_mfma_f32_16x16x32_bf16 v[112:115], v[192:195], v[200:203], v[112:115]
	v_mfma_f32_16x16x32_bf16 v[100:103], v[184:187], v[208:211], v[100:103]
	v_mfma_f32_16x16x32_bf16 v[96:99], v[192:195], v[208:211], v[96:99]
	v_mfma_f32_16x16x32_bf16 v[84:87], v[184:187], v[216:219], v[84:87]
	v_mfma_f32_16x16x32_bf16 v[80:83], v[192:195], v[216:219], v[80:83]
	v_mfma_f32_16x16x32_bf16 v[68:71], v[184:187], v[224:227], v[68:71]
	v_mfma_f32_16x16x32_bf16 v[64:67], v[192:195], v[224:227], v[64:67]
	s_setprio 0
	s_barrier
; #define PG8_STAGE(bufoff, gbase, voff) do { _Pragma("unroll") for (int _i = 0; _i < 2; ++_i) \
;         __builtin_amdgcn_global_load_lds((const unsigned*)((const char*)(gbase) + (voff)[_i]), (LAS unsigned*)(lds + (bufoff) + ldsw + _i * 8192), 16, 0, 0); } while (0)
; #define PG8_LDA(dst, b, h) do { _Pragma("unroll") for (int m = 0; m < 4; ++m) _Pragma("unroll") for (int k = 0; k < 2; ++k) dst[m][k] = *(const LAS bf16x8*)(lds + PG8_SA(b, h) + aoff + m * 2048 + k * 1024); } while (0)
; #define PG8_WAIT_V(n) asm volatile("s_waitcnt vmcnt(" #n ")" ::: "memory")
; #define PG8_WAIT_L(n) asm volatile("s_waitcnt lgkmcnt(" #n ")" ::: "memory")
; #define PG8_BAR __builtin_amdgcn_s_barrier()
; #define PG8_SCHED __builtin_amdgcn_sched_barrier(0)
; template <class Epi, class Sched, bool SWAPD = false>
; __device__ __forceinline__ void gemm_phase(LAS unsigned char* lds, const Gemm g, const Sched& S, const Epi& E) {
;     ...
;             PG8_LDA(At, 1, 1); PG8_STAGE(PG8_SB(1, 0), b3, voffB); PG8_STAGE(PG8_SB(1, 1), b3 + hstepB, voffB); PG8_STAGE(PG8_SA(1, 0), a3, voffA);
;             PG8_WAIT_V(8); PG8_WAIT_L(0); PG8_BAR; PG8_MMA(1, 0, At, B0); PG8_MMA(1, 1, At, B1); PG8_BAR; PG8_SCHED;
;         }
	s_add_i32 s20, s54, s30
	v_lshl_add_u64 v[164:165], v[164:165], 0, s[6:7]
	s_mov_b32 m0, s20
	ds_read_b128 v[196:199], v170 offset:49152
	ds_read_b128 v[200:203], v170 offset:50176
	ds_read_b128 v[204:207], v170 offset:51200
	ds_read_b128 v[208:211], v170 offset:52224
	ds_read_b128 v[212:215], v170 offset:53248
	ds_read_b128 v[216:219], v170 offset:54272
	ds_read_b128 v[220:223], v170 offset:55296
	ds_read_b128 v[224:227], v170 offset:56320
	global_load_lds_dwordx4 v[164:165], off
	s_add_i32 m0, s20, 0x2000
	s_add_u32 s20, s24, 0xb0080
	v_lshl_add_u64 v[164:165], v[228:229], 0, s[6:7]
	s_addc_u32 s21, s25, 0
	s_add_i32 s24, s55, s30
	global_load_lds_dwordx4 v[164:165], off
	v_lshl_add_u64 v[164:165], s[20:21], 0, v[128:129]
	s_mov_b32 m0, s24
	s_nop 0
	global_load_lds_dwordx4 v[164:165], off
	v_lshl_add_u64 v[164:165], s[20:21], 0, v[130:131]
	s_add_i32 m0, s24, 0x2000
	s_nop 0
	global_load_lds_dwordx4 v[164:165], off
	v_lshl_add_u64 v[164:165], v[230:231], 0, s[6:7]
	s_mov_b32 m0, s39
	s_nop 0
	global_load_lds_dwordx4 v[164:165], off
	v_lshl_add_u64 v[164:165], v[232:233], 0, s[6:7]
	s_mov_b32 m0, s40
	s_nop 0
	global_load_lds_dwordx4 v[164:165], off
	s_waitcnt vmcnt(8)
	s_waitcnt lgkmcnt(0)
	s_barrier
	s_setprio 1
	v_mfma_f32_16x16x32_bf16 v[60:63], v[156:159], v[196:199], v[60:63]
	v_mfma_f32_16x16x32_bf16 v[56:59], v[172:175], v[196:199], v[56:59]
	v_mfma_f32_16x16x32_bf16 v[44:47], v[156:159], v[204:207], v[44:47]
	v_mfma_f32_16x16x32_bf16 v[40:43], v[172:175], v[204:207], v[40:43]
	v_mfma_f32_16x16x32_bf16 v[28:31], v[156:159], v[212:215], v[28:31]
	v_mfma_f32_16x16x32_bf16 v[24:27], v[172:175], v[212:215], v[24:27]
	v_mfma_f32_16x16x32_bf16 v[12:15], v[156:159], v[220:223], v[12:15]
	v_mfma_f32_16x16x32_bf16 v[8:11], v[172:175], v[220:223], v[8:11]
	v_mfma_f32_16x16x32_bf16 v[60:63], v[160:163], v[200:203], v[60:63]
	v_mfma_f32_16x16x32_bf16 v[56:59], v[176:179], v[200:203], v[56:59]
	v_mfma_f32_16x16x32_bf16 v[44:47], v[160:163], v[208:211], v[44:47]
	v_mfma_f32_16x16x32_bf16 v[40:43], v[176:179], v[208:211], v[40:43]
	v_mfma_f32_16x16x32_bf16 v[28:31], v[160:163], v[216:219], v[28:31]
	v_mfma_f32_16x16x32_bf16 v[24:27], v[176:179], v[216:219], v[24:27]
	v_mfma_f32_16x16x32_bf16 v[12:15], v[160:163], v[224:227], v[12:15]
	v_mfma_f32_16x16x32_bf16 v[8:11], v[176:179], v[224:227], v[8:11]
	s_setprio 0
	s_setprio 1
	v_mfma_f32_16x16x32_bf16 v[52:55], v[180:183], v[196:199], v[52:55]
	v_mfma_f32_16x16x32_bf16 v[48:51], v[188:191], v[196:199], v[48:51]
	v_mfma_f32_16x16x32_bf16 v[36:39], v[180:183], v[204:207], v[36:39]
	v_mfma_f32_16x16x32_bf16 v[32:35], v[188:191], v[204:207], v[32:35]
	v_mfma_f32_16x16x32_bf16 v[20:23], v[180:183], v[212:215], v[20:23]
	v_mfma_f32_16x16x32_bf16 v[16:19], v[188:191], v[212:215], v[16:19]
	v_mfma_f32_16x16x32_bf16 v[4:7], v[180:183], v[220:223], v[4:7]
	v_mfma_f32_16x16x32_bf16 v[0:3], v[188:191], v[220:223], v[0:3]
	v_mfma_f32_16x16x32_bf16 v[52:55], v[184:187], v[200:203], v[52:55]
	v_mfma_f32_16x16x32_bf16 v[48:51], v[192:195], v[200:203], v[48:51]
	v_mfma_f32_16x16x32_bf16 v[36:39], v[184:187], v[208:211], v[36:39]
	v_mfma_f32_16x16x32_bf16 v[32:35], v[192:195], v[208:211], v[32:35]
	v_mfma_f32_16x16x32_bf16 v[20:23], v[184:187], v[216:219], v[20:23]
	v_mfma_f32_16x16x32_bf16 v[16:19], v[192:195], v[216:219], v[16:19]
	v_mfma_f32_16x16x32_bf16 v[4:7], v[184:187], v[224:227], v[4:7]
	v_mfma_f32_16x16x32_bf16 v[0:3], v[192:195], v[224:227], v[0:3]
	s_setprio 0
	s_add_i32 s53, s53, 2
	s_add_u32 s51, s51, 0x100
	s_addc_u32 s52, s52, 0
	s_cmp_gt_u32 s53, 41
	s_mov_b64 s[20:21], s[22:23]
	s_barrier
	s_cbranch_scc0 .LBB0_1940
	s_and_b64 vcc, exec, s[8:9]
	s_cbranch_vccz .LBB0_1943
	s_barrier
